# segment-head and back-edge SALU (address/counter updates, m0 set-up, loop compare) hoisted into the preceding MFMA run's shadow, on top of k-outer stack
# speedup vs baseline: 1.0025x; 1.0001x over previous
;     __host__ __device__ bool next(int i, Unit& u) const { const int t = i / 3, b = i - 3 * t; Unit v; if (!StaticOrder::next(t, v)) return false; u.pm = v.pm; u.pn = 8 * b + v.pn; return true; }
; #define PG8_STAGE(bufoff, gbase, voff) do { const int so_ = (int)(unsigned)((const char*)(gbase) - base_##voff); _Pragma("unroll") for (int _i = 0; _i < 2; ++_i) \
;         __builtin_amdgcn_raw_ptr_buffer_load_lds(rs_##voff, (PG8_LAS unsigned*)(lds + (bufoff) + ldsw + _i * 8192), 16, (int)(voff)[_i], so_, 0, 0); } while (0)
; #define PG8_LDA(dst, b, h) do { _Pragma("unroll") for (int m = 0; m < 4; ++m) _Pragma("unroll") for (int k = 0; k < 2; ++k) dst[m][k] = *(const PG8_LAS bf16x8*)(lds + PG8_SA(b, h) + aoff + m * 2048 + k * 1024); } while (0)
; #define PG8_WAIT_V(n) asm volatile("s_waitcnt vmcnt(" #n ")" ::: "memory")
; #define PG8_WAIT_L(n) asm volatile("s_waitcnt lgkmcnt(" #n ")" ::: "memory")
; #define PG8_BAR __builtin_amdgcn_s_barrier()
; template <class Epi, class Sched, bool ALIGN_EPI = false, bool SP2 = false>
; __device__ __forceinline__ void gemm_phase(PG8_LAS unsigned char* lds, const Gemm g, const Sched& S, const Epi& E, int tid_in) {
;     ...
;         const bool has_next = S.next(ui + 1, nxt);
;         const char* nA = has_next ? (const char*)g.A + (size_t)nxt.pm * tstepA + (g.grp ? (size_t)(nxt.pn / g.grp) * g.agrp : (size_t)0) : cA; const char* nB = has_next ? (const char*)g.Bt + (size_t)nxt.pn * tstepB : cB;
;         for (int t = 0; t < nt; t += 2) {
;             const bool last = (t == nt - 2);
;             const char* a1 = cA + (size_t)(t + 1) * kstep;
;             const char* a2 = last ? nA : cA + (size_t)(t + 2) * kstep; const char* b2 = last ? nB : cB + (size_t)(t + 2) * kstep;
;             const char* a3 = a2 + kstep; const char* b3 = b2 + kstep;
;             if (last && has_next) S.a_ready(nxt);
;             if constexpr (SP2) {
;             PG8_LDB(B0, 0, 0); PG8_LDB(B1, 0, 1); PG8_SCHED; PG8_LDA(At, 0, 0); PG8_STAGE(PG8_SA(1, 1), a1 + hstepA, voffA);
;             PG8_WAIT_V(8); PG8_WAIT_L(0); PG8_BAR; PG8_MMA(0, 0, At, B0); PG8_MMA(0, 1, At, B1); PG8_BAR; PG8_SCHED;
;             PG8_LDA(At, 0, 1); PG8_STAGE(PG8_SB(0, 0), b2, voffB); PG8_STAGE(PG8_SB(0, 1), b2 + hstepB, voffB); PG8_STAGE(PG8_SA(0, 0), a2, voffA);
;             PG8_WAIT_V(8); PG8_WAIT_L(0); PG8_BAR; PG8_MMA(1, 0, At, B0); PG8_MMA(1, 1, At, B1); PG8_BAR; PG8_SCHED;
.LBB0_311:
	s_ashr_i32 s23, s22, 31
	s_lshl_b64 s[10:11], s[22:23], 20
	s_add_u32 s24, s4, s10
	s_addc_u32 s25, s26, s11
	s_and_b64 s[10:11], s[34:35], exec
	s_cselect_b32 s19, s24, s12
	s_ashr_i32 s15, s14, 31
	s_lshl_b64 s[10:11], s[14:15], 20
	s_add_u32 s10, s40, s10
	s_addc_u32 s11, s60, s11
	s_and_b64 s[20:21], s[34:35], exec
	s_cselect_b32 s15, s10, s16
	s_add_u32 s20, s16, 0x100
	v_mov_b32_e32 v2, 0
	s_addc_u32 s21, s17, 0
	s_mov_b32 s23, -2
	v_add_u32_e32 v0, 0x10000, v237
	ds_read_b128 v[130:133], v0
	ds_read_b128 v[134:137], v0 offset:1024
	ds_read_b128 v[138:141], v0 offset:2048
	ds_read_b128 v[142:145], v0 offset:3072
	v_add_u32_e32 v0, 0x14000, v237
	ds_read_b128 v[146:149], v0
	ds_read_b128 v[150:153], v0 offset:1024
	ds_read_b128 v[154:157], v0 offset:2048
	ds_read_b128 v[158:161], v0 offset:3072
	s_add_u32 s16, s12, 0x100
	s_addc_u32 s17, s13, 0
	s_sub_i32 s12, s12, s4
	s_add_i32 s12, s12, 0x80080
	s_sub_i32 s36, s12, 0x80000
	s_cmp_eq_u32 s23, 28
	s_cselect_b32 s13, s19, s16
	s_mov_b32 m0, s69
	ds_read_b128 v[162:165], v238
	ds_read_b128 v[166:169], v238 offset:1024
	ds_read_b128 v[170:173], v238 offset:2048
	ds_read_b128 v[174:177], v238 offset:3072
	ds_read_b128 v[178:181], v238 offset:4096
	ds_read_b128 v[182:185], v238 offset:5120
	ds_read_b128 v[186:189], v238 offset:6144
	ds_read_b128 v[190:193], v238 offset:7168
	s_mov_b32 m0, s78
	s_nop 0
	buffer_load_dwordx4 v211, s[4:7], s36 offen lds
	s_mov_b32 m0, s69
	s_nop 0
	buffer_load_dwordx4 v195, s[4:7], s12 offen lds
	s_mov_b32 m0, s67
	s_nop 0
	buffer_load_dwordx4 v211, s[4:7], s12 offen lds
	s_waitcnt vmcnt(8)
	s_waitcnt lgkmcnt(0)
	s_setprio 1
	s_barrier
	v_mfma_f32_16x16x32_bf16 v[126:129], v[130:133], v[162:165], 0
	v_mfma_f32_16x16x32_bf16 v[122:125], v[138:141], v[162:165], 0
	v_mfma_f32_16x16x32_bf16 v[106:109], v[138:141], v[170:173], 0
	v_mfma_f32_16x16x32_bf16 v[110:113], v[130:133], v[170:173], 0
	v_mfma_f32_16x16x32_bf16 v[94:97], v[130:133], v[178:181], 0
	v_mfma_f32_16x16x32_bf16 v[90:93], v[138:141], v[178:181], 0
	v_mfma_f32_16x16x32_bf16 v[74:77], v[138:141], v[186:189], 0
	v_mfma_f32_16x16x32_bf16 v[78:81], v[130:133], v[186:189], 0
	s_cselect_b32 s12, s15, s20
	v_mfma_f32_16x16x32_bf16 v[126:129], v[134:137], v[166:169], v[126:129]
	s_mov_b32 m0, s61
	v_mfma_f32_16x16x32_bf16 v[122:125], v[142:145], v[166:169], v[122:125]
	s_mov_b32 s42, s6
	v_mfma_f32_16x16x32_bf16 v[106:109], v[142:145], v[174:177], v[106:109]
	s_mov_b32 s43, s7
	v_mfma_f32_16x16x32_bf16 v[110:113], v[134:137], v[174:177], v[110:113]
	s_sub_i32 s12, s12, s40
	v_mfma_f32_16x16x32_bf16 v[94:97], v[134:137], v[182:185], v[94:97]
	v_mfma_f32_16x16x32_bf16 v[90:93], v[142:145], v[182:185], v[90:93]
	v_mfma_f32_16x16x32_bf16 v[74:77], v[142:145], v[190:193], v[74:77]
	v_mfma_f32_16x16x32_bf16 v[78:81], v[134:137], v[190:193], v[78:81]
	v_mfma_f32_16x16x32_bf16 v[118:121], v[146:149], v[162:165], 0
	v_mfma_f32_16x16x32_bf16 v[114:117], v[154:157], v[162:165], 0
	v_mfma_f32_16x16x32_bf16 v[98:101], v[154:157], v[170:173], 0
	v_mfma_f32_16x16x32_bf16 v[102:105], v[146:149], v[170:173], 0
	v_mfma_f32_16x16x32_bf16 v[86:89], v[146:149], v[178:181], 0
	v_mfma_f32_16x16x32_bf16 v[82:85], v[154:157], v[178:181], 0
	v_mfma_f32_16x16x32_bf16 v[66:69], v[154:157], v[186:189], 0
	v_mfma_f32_16x16x32_bf16 v[70:73], v[146:149], v[186:189], 0
	v_mfma_f32_16x16x32_bf16 v[118:121], v[150:153], v[166:169], v[118:121]
	v_mfma_f32_16x16x32_bf16 v[114:117], v[158:161], v[166:169], v[114:117]
	v_mfma_f32_16x16x32_bf16 v[98:101], v[158:161], v[174:177], v[98:101]
	v_mfma_f32_16x16x32_bf16 v[102:105], v[150:153], v[174:177], v[102:105]
	v_mfma_f32_16x16x32_bf16 v[86:89], v[150:153], v[182:185], v[86:89]
	v_mfma_f32_16x16x32_bf16 v[82:85], v[158:161], v[182:185], v[82:85]
	v_mfma_f32_16x16x32_bf16 v[66:69], v[158:161], v[190:193], v[66:69]
	v_mfma_f32_16x16x32_bf16 v[70:73], v[150:153], v[190:193], v[70:73]
	s_barrier
	s_setprio 0
	ds_read_b128 v[162:165], v238 offset:16384
	ds_read_b128 v[166:169], v238 offset:17408
	ds_read_b128 v[170:173], v238 offset:18432
	ds_read_b128 v[174:177], v238 offset:19456
	ds_read_b128 v[178:181], v238 offset:20480
	ds_read_b128 v[182:185], v238 offset:21504
	ds_read_b128 v[186:189], v238 offset:22528
	ds_read_b128 v[190:193], v238 offset:23552
	buffer_load_dwordx4 v207, s[40:43], s12 offen lds
	s_mov_b32 m0, s62
	s_add_i32 s36, s12, 0x80000
	buffer_load_dwordx4 v224, s[40:43], s12 offen lds
	s_mov_b32 m0, s63
	s_sub_i32 s13, s13, s4
	buffer_load_dwordx4 v207, s[40:43], s36 offen lds
	s_mov_b32 m0, s71
	s_nop 0
	buffer_load_dwordx4 v224, s[40:43], s36 offen lds
	s_mov_b32 m0, s53
	s_nop 0
	buffer_load_dwordx4 v195, s[4:7], s13 offen lds
	s_waitcnt vmcnt(7)
	s_waitcnt lgkmcnt(0)
	s_setprio 1
	s_barrier
; #define PG8_STAGE(bufoff, gbase, voff) do { const int so_ = (int)(unsigned)((const char*)(gbase) - base_##voff); _Pragma("unroll") for (int _i = 0; _i < 2; ++_i) \
;         __builtin_amdgcn_raw_ptr_buffer_load_lds(rs_##voff, (PG8_LAS unsigned*)(lds + (bufoff) + ldsw + _i * 8192), 16, (int)(voff)[_i], so_, 0, 0); } while (0)
; #define PG8_LDA(dst, b, h) do { _Pragma("unroll") for (int m = 0; m < 4; ++m) _Pragma("unroll") for (int k = 0; k < 2; ++k) dst[m][k] = *(const PG8_LAS bf16x8*)(lds + PG8_SA(b, h) + aoff + m * 2048 + k * 1024); } while (0)
; #define PG8_LDB(dst, b, h) do { _Pragma("unroll") for (int n = 0; n < 2; ++n) _Pragma("unroll") for (int k = 0; k < 2; ++k) dst[n][k] = *(const PG8_LAS bf16x8*)(lds + PG8_SB(b, h) + boff + n * 2048 + k * 1024); } while (0)
; #define PG8_MMA(ai, bj, At, Bt) do { __builtin_amdgcn_s_setprio(1); _Pragma("unroll") for (int m = 0; m < 4; ++m) _Pragma("unroll") for (int n = 0; n < 2; ++n) _Pragma("unroll") for (int k = 0; k < 2; ++k) \
;         acc[ai][bj][m][n] = __builtin_amdgcn_mfma_f32_16x16x32_bf16(Bt[n][k], At[m][k], acc[ai][bj][m][n], 0, 0, 0); __builtin_amdgcn_s_setprio(0); } while (0)
; #define PG8_WAIT_V(n) asm volatile("s_waitcnt vmcnt(" #n ")" ::: "memory")
; #define PG8_WAIT_L(n) asm volatile("s_waitcnt lgkmcnt(" #n ")" ::: "memory")
; #define PG8_BAR __builtin_amdgcn_s_barrier()
; #define PG8_SCHED __builtin_amdgcn_sched_barrier(0)
; template <class Epi, class Sched, bool ALIGN_EPI = false, bool SP2 = false>
; __device__ __forceinline__ void gemm_phase(PG8_LAS unsigned char* lds, const Gemm g, const Sched& S, const Epi& E, int tid_in) {
;     ...
;             PG8_WAIT_V(8); PG8_WAIT_L(0); PG8_BAR; PG8_MMA(1, 0, At, B0); PG8_MMA(1, 1, At, B1); PG8_BAR; PG8_SCHED;
;             PG8_LDB(B0, 1, 0); PG8_LDB(B1, 1, 1); PG8_SCHED; PG8_LDA(At, 1, 0); PG8_STAGE(PG8_SA(0, 1), a2 + hstepA, voffA);
;             PG8_WAIT_V(8); PG8_WAIT_L(0); PG8_BAR; PG8_MMA(0, 0, At, B0); PG8_MMA(0, 1, At, B1); PG8_BAR; PG8_SCHED;
	v_mfma_f32_16x16x32_bf16 v[62:65], v[130:133], v[162:165], 0
	v_mfma_f32_16x16x32_bf16 v[58:61], v[138:141], v[162:165], 0
	v_mfma_f32_16x16x32_bf16 v[42:45], v[138:141], v[170:173], 0
	v_mfma_f32_16x16x32_bf16 v[46:49], v[130:133], v[170:173], 0
	v_mfma_f32_16x16x32_bf16 v[30:33], v[130:133], v[178:181], 0
	v_mfma_f32_16x16x32_bf16 v[26:29], v[138:141], v[178:181], 0
	v_mfma_f32_16x16x32_bf16 v[10:13], v[138:141], v[186:189], 0
	v_mfma_f32_16x16x32_bf16 v[14:17], v[130:133], v[186:189], 0
	v_mfma_f32_16x16x32_bf16 v[62:65], v[134:137], v[166:169], v[62:65]
	v_mfma_f32_16x16x32_bf16 v[58:61], v[142:145], v[166:169], v[58:61]
	v_mfma_f32_16x16x32_bf16 v[42:45], v[142:145], v[174:177], v[42:45]
	v_mfma_f32_16x16x32_bf16 v[46:49], v[134:137], v[174:177], v[46:49]
	v_mfma_f32_16x16x32_bf16 v[30:33], v[134:137], v[182:185], v[30:33]
	v_mfma_f32_16x16x32_bf16 v[26:29], v[142:145], v[182:185], v[26:29]
	v_mfma_f32_16x16x32_bf16 v[10:13], v[142:145], v[190:193], v[10:13]
	v_mfma_f32_16x16x32_bf16 v[14:17], v[134:137], v[190:193], v[14:17]
	v_mfma_f32_16x16x32_bf16 v[54:57], v[146:149], v[162:165], 0
	v_mfma_f32_16x16x32_bf16 v[50:53], v[154:157], v[162:165], 0
	v_mfma_f32_16x16x32_bf16 v[34:37], v[154:157], v[170:173], 0
	v_mfma_f32_16x16x32_bf16 v[38:41], v[146:149], v[170:173], 0
	v_mfma_f32_16x16x32_bf16 v[22:25], v[146:149], v[178:181], 0
	v_mfma_f32_16x16x32_bf16 v[18:21], v[154:157], v[178:181], 0
	v_mfma_f32_16x16x32_bf16 v[2:5], v[154:157], v[186:189], 0
	v_mfma_f32_16x16x32_bf16 v[6:9], v[146:149], v[186:189], 0
	v_mfma_f32_16x16x32_bf16 v[54:57], v[150:153], v[166:169], v[54:57]
	v_mfma_f32_16x16x32_bf16 v[50:53], v[158:161], v[166:169], v[50:53]
	v_mfma_f32_16x16x32_bf16 v[34:37], v[158:161], v[174:177], v[34:37]
	v_mfma_f32_16x16x32_bf16 v[38:41], v[150:153], v[174:177], v[38:41]
	v_mfma_f32_16x16x32_bf16 v[22:25], v[150:153], v[182:185], v[22:25]
	v_mfma_f32_16x16x32_bf16 v[18:21], v[158:161], v[182:185], v[18:21]
	v_mfma_f32_16x16x32_bf16 v[2:5], v[158:161], v[190:193], v[2:5]
	v_mfma_f32_16x16x32_bf16 v[6:9], v[150:153], v[190:193], v[6:9]
	s_barrier
	s_setprio 0
	v_add_u32_e32 v0, 0x18000, v237
	ds_read_b128 v[130:133], v0
	ds_read_b128 v[134:137], v0 offset:1024
	ds_read_b128 v[138:141], v0 offset:2048
	ds_read_b128 v[142:145], v0 offset:3072
	v_add_u32_e32 v0, 0x1c000, v237
	ds_read_b128 v[146:149], v0
	ds_read_b128 v[150:153], v0 offset:1024
	ds_read_b128 v[154:157], v0 offset:2048
	ds_read_b128 v[158:161], v0 offset:3072
	s_add_i32 s36, s13, 0x80000
	s_mov_b32 m0, s73
	ds_read_b128 v[162:165], v238 offset:32768
	ds_read_b128 v[166:169], v238 offset:33792
	ds_read_b128 v[170:173], v238 offset:34816
	ds_read_b128 v[174:177], v238 offset:35840
	ds_read_b128 v[178:181], v238 offset:36864
	ds_read_b128 v[182:185], v238 offset:37888
	ds_read_b128 v[186:189], v238 offset:38912
	ds_read_b128 v[190:193], v238 offset:39936
	s_mov_b32 m0, s72
	s_nop 0
	buffer_load_dwordx4 v211, s[4:7], s13 offen lds
	s_mov_b32 m0, s73
	s_nop 0
	buffer_load_dwordx4 v195, s[4:7], s36 offen lds
	s_mov_b32 m0, s74
	s_nop 0
	buffer_load_dwordx4 v211, s[4:7], s36 offen lds
	s_waitcnt vmcnt(8)
	s_waitcnt lgkmcnt(0)
	s_setprio 1
	s_barrier
	v_mfma_f32_16x16x32_bf16 v[126:129], v[130:133], v[162:165], v[126:129]
	v_mfma_f32_16x16x32_bf16 v[122:125], v[138:141], v[162:165], v[122:125]
	v_mfma_f32_16x16x32_bf16 v[106:109], v[138:141], v[170:173], v[106:109]
	v_mfma_f32_16x16x32_bf16 v[110:113], v[130:133], v[170:173], v[110:113]
	v_mfma_f32_16x16x32_bf16 v[94:97], v[130:133], v[178:181], v[94:97]
	v_mfma_f32_16x16x32_bf16 v[90:93], v[138:141], v[178:181], v[90:93]
	v_mfma_f32_16x16x32_bf16 v[74:77], v[138:141], v[186:189], v[74:77]
	v_mfma_f32_16x16x32_bf16 v[78:81], v[130:133], v[186:189], v[78:81]
	s_mov_b32 m0, s75
	v_mfma_f32_16x16x32_bf16 v[70:73], v[146:149], v[186:189], v[70:73]
	s_add_i32 s36, s12, 0x80
	v_mfma_f32_16x16x32_bf16 v[66:69], v[154:157], v[186:189], v[66:69]
	v_mfma_f32_16x16x32_bf16 v[82:85], v[154:157], v[178:181], v[82:85]
	v_mfma_f32_16x16x32_bf16 v[86:89], v[146:149], v[178:181], v[86:89]
	v_mfma_f32_16x16x32_bf16 v[102:105], v[146:149], v[170:173], v[102:105]
	v_mfma_f32_16x16x32_bf16 v[98:101], v[154:157], v[170:173], v[98:101]
	v_mfma_f32_16x16x32_bf16 v[114:117], v[154:157], v[162:165], v[114:117]
	v_mfma_f32_16x16x32_bf16 v[118:121], v[146:149], v[162:165], v[118:121]
	v_mfma_f32_16x16x32_bf16 v[126:129], v[134:137], v[166:169], v[126:129]
	v_mfma_f32_16x16x32_bf16 v[122:125], v[142:145], v[166:169], v[122:125]
	v_mfma_f32_16x16x32_bf16 v[106:109], v[142:145], v[174:177], v[106:109]
	v_mfma_f32_16x16x32_bf16 v[110:113], v[134:137], v[174:177], v[110:113]
	v_mfma_f32_16x16x32_bf16 v[94:97], v[134:137], v[182:185], v[94:97]
	v_mfma_f32_16x16x32_bf16 v[90:93], v[142:145], v[182:185], v[90:93]
	v_mfma_f32_16x16x32_bf16 v[74:77], v[142:145], v[190:193], v[74:77]
	v_mfma_f32_16x16x32_bf16 v[78:81], v[134:137], v[190:193], v[78:81]
	v_mfma_f32_16x16x32_bf16 v[70:73], v[150:153], v[190:193], v[70:73]
	v_mfma_f32_16x16x32_bf16 v[66:69], v[158:161], v[190:193], v[66:69]
	v_mfma_f32_16x16x32_bf16 v[82:85], v[158:161], v[182:185], v[82:85]
	v_mfma_f32_16x16x32_bf16 v[86:89], v[150:153], v[182:185], v[86:89]
	v_mfma_f32_16x16x32_bf16 v[102:105], v[150:153], v[174:177], v[102:105]
	v_mfma_f32_16x16x32_bf16 v[98:101], v[158:161], v[174:177], v[98:101]
	v_mfma_f32_16x16x32_bf16 v[114:117], v[158:161], v[166:169], v[114:117]
	v_mfma_f32_16x16x32_bf16 v[118:121], v[150:153], v[166:169], v[118:121]
	s_barrier
; #define PG8_STAGE(bufoff, gbase, voff) do { const int so_ = (int)(unsigned)((const char*)(gbase) - base_##voff); _Pragma("unroll") for (int _i = 0; _i < 2; ++_i) \
;         __builtin_amdgcn_raw_ptr_buffer_load_lds(rs_##voff, (PG8_LAS unsigned*)(lds + (bufoff) + ldsw + _i * 8192), 16, (int)(voff)[_i], so_, 0, 0); } while (0)
; #define PG8_LDA(dst, b, h) do { _Pragma("unroll") for (int m = 0; m < 4; ++m) _Pragma("unroll") for (int k = 0; k < 2; ++k) dst[m][k] = *(const PG8_LAS bf16x8*)(lds + PG8_SA(b, h) + aoff + m * 2048 + k * 1024); } while (0)
; #define PG8_LDB(dst, b, h) do { _Pragma("unroll") for (int n = 0; n < 2; ++n) _Pragma("unroll") for (int k = 0; k < 2; ++k) dst[n][k] = *(const PG8_LAS bf16x8*)(lds + PG8_SB(b, h) + boff + n * 2048 + k * 1024); } while (0)
; #define PG8_MMA(ai, bj, At, Bt) do { __builtin_amdgcn_s_setprio(1); _Pragma("unroll") for (int m = 0; m < 4; ++m) _Pragma("unroll") for (int n = 0; n < 2; ++n) _Pragma("unroll") for (int k = 0; k < 2; ++k) \
;         acc[ai][bj][m][n] = __builtin_amdgcn_mfma_f32_16x16x32_bf16(Bt[n][k], At[m][k], acc[ai][bj][m][n], 0, 0, 0); __builtin_amdgcn_s_setprio(0); } while (0)
; template <class Epi, class Sched, bool ALIGN_EPI = false, bool SP2 = false>
; __device__ __forceinline__ void gemm_phase(PG8_LAS unsigned char* lds, const Gemm g, const Sched& S, const Epi& E, int tid_in) {
;     ...
;             PG8_LDB(B0, 0, 0); PG8_LDB(B1, 0, 1); PG8_SCHED; PG8_LDA(At, 0, 0); PG8_STAGE(PG8_SA(1, 1), a1 + hstepA, voffA);
;             PG8_WAIT_V(8); PG8_WAIT_L(0); PG8_BAR; PG8_MMA(0, 0, At, B0); PG8_MMA(0, 1, At, B1); PG8_BAR; PG8_SCHED;
;             PG8_LDA(At, 0, 1); PG8_STAGE(PG8_SB(0, 0), b2, voffB); PG8_STAGE(PG8_SB(0, 1), b2 + hstepB, voffB); PG8_STAGE(PG8_SA(0, 0), a2, voffA);
;             PG8_WAIT_V(8); PG8_WAIT_L(0); PG8_BAR; PG8_MMA(1, 0, At, B0); PG8_MMA(1, 1, At, B1); PG8_BAR; PG8_SCHED;
;             PG8_LDB(B0, 1, 0); PG8_LDB(B1, 1, 1); PG8_SCHED; PG8_LDA(At, 1, 0); PG8_STAGE(PG8_SA(0, 1), a2 + hstepA, voffA);
;             PG8_WAIT_V(8); PG8_WAIT_L(0); PG8_BAR; PG8_MMA(0, 0, At, B0); PG8_MMA(0, 1, At, B1); PG8_BAR; PG8_SCHED;
;             PG8_LDA(At, 1, 1); PG8_STAGE(PG8_SB(1, 0), b3, voffB); PG8_STAGE(PG8_SB(1, 1), b3 + hstepB, voffB); PG8_STAGE(PG8_SA(1, 0), a3, voffA);
;             PG8_WAIT_V(8); PG8_WAIT_L(0); PG8_BAR; PG8_MMA(1, 0, At, B0); PG8_MMA(1, 1, At, B1); PG8_BAR; PG8_SCHED;
	s_setprio 0
	ds_read_b128 v[162:165], v238 offset:49152
	ds_read_b128 v[166:169], v238 offset:50176
	ds_read_b128 v[170:173], v238 offset:51200
	ds_read_b128 v[174:177], v238 offset:52224
	ds_read_b128 v[178:181], v238 offset:53248
	ds_read_b128 v[182:185], v238 offset:54272
	ds_read_b128 v[186:189], v238 offset:55296
	ds_read_b128 v[190:193], v238 offset:56320
	buffer_load_dwordx4 v207, s[40:43], s36 offen lds
	s_mov_b32 m0, s76
	s_add_i32 s12, s12, 0x80080
	buffer_load_dwordx4 v224, s[40:43], s36 offen lds
	s_mov_b32 m0, s79
	s_addk_i32 s13, 0x80
	buffer_load_dwordx4 v207, s[40:43], s12 offen lds
	s_mov_b32 m0, s68
	s_nop 0
	buffer_load_dwordx4 v224, s[40:43], s12 offen lds
	s_mov_b32 m0, s77
	s_nop 0
	buffer_load_dwordx4 v195, s[4:7], s13 offen lds
	s_waitcnt vmcnt(7)
	s_waitcnt lgkmcnt(0)
	s_setprio 1
	s_barrier
	v_mfma_f32_16x16x32_bf16 v[62:65], v[130:133], v[162:165], v[62:65]
	v_mfma_f32_16x16x32_bf16 v[58:61], v[138:141], v[162:165], v[58:61]
	v_mfma_f32_16x16x32_bf16 v[42:45], v[138:141], v[170:173], v[42:45]
	v_mfma_f32_16x16x32_bf16 v[46:49], v[130:133], v[170:173], v[46:49]
	v_mfma_f32_16x16x32_bf16 v[30:33], v[130:133], v[178:181], v[30:33]
	v_mfma_f32_16x16x32_bf16 v[26:29], v[138:141], v[178:181], v[26:29]
	v_mfma_f32_16x16x32_bf16 v[10:13], v[138:141], v[186:189], v[10:13]
	v_mfma_f32_16x16x32_bf16 v[14:17], v[130:133], v[186:189], v[14:17]
	s_add_i32 s23, s23, 2
	v_mfma_f32_16x16x32_bf16 v[6:9], v[146:149], v[186:189], v[6:9]
	s_add_u32 s20, s20, 0x100
	v_mfma_f32_16x16x32_bf16 v[2:5], v[154:157], v[186:189], v[2:5]
	s_addc_u32 s21, s21, 0
	v_mfma_f32_16x16x32_bf16 v[18:21], v[154:157], v[178:181], v[18:21]
	s_cmp_gt_u32 s23, 29
	v_mfma_f32_16x16x32_bf16 v[22:25], v[146:149], v[178:181], v[22:25]
	s_mov_b64 s[12:13], s[16:17]
	v_mfma_f32_16x16x32_bf16 v[38:41], v[146:149], v[170:173], v[38:41]
	v_mfma_f32_16x16x32_bf16 v[34:37], v[154:157], v[170:173], v[34:37]
	v_mfma_f32_16x16x32_bf16 v[50:53], v[154:157], v[162:165], v[50:53]
	v_mfma_f32_16x16x32_bf16 v[54:57], v[146:149], v[162:165], v[54:57]
	v_mfma_f32_16x16x32_bf16 v[62:65], v[134:137], v[166:169], v[62:65]
	v_mfma_f32_16x16x32_bf16 v[58:61], v[142:145], v[166:169], v[58:61]
	v_mfma_f32_16x16x32_bf16 v[42:45], v[142:145], v[174:177], v[42:45]
	v_mfma_f32_16x16x32_bf16 v[46:49], v[134:137], v[174:177], v[46:49]
	v_mfma_f32_16x16x32_bf16 v[30:33], v[134:137], v[182:185], v[30:33]
	v_mfma_f32_16x16x32_bf16 v[26:29], v[142:145], v[182:185], v[26:29]
	v_mfma_f32_16x16x32_bf16 v[10:13], v[142:145], v[190:193], v[10:13]
	v_mfma_f32_16x16x32_bf16 v[14:17], v[134:137], v[190:193], v[14:17]
	v_mfma_f32_16x16x32_bf16 v[6:9], v[150:153], v[190:193], v[6:9]
	v_mfma_f32_16x16x32_bf16 v[2:5], v[158:161], v[190:193], v[2:5]
	v_mfma_f32_16x16x32_bf16 v[18:21], v[158:161], v[182:185], v[18:21]
	v_mfma_f32_16x16x32_bf16 v[22:25], v[150:153], v[182:185], v[22:25]
	v_mfma_f32_16x16x32_bf16 v[38:41], v[150:153], v[174:177], v[38:41]
	v_mfma_f32_16x16x32_bf16 v[34:37], v[158:161], v[174:177], v[34:37]
	v_mfma_f32_16x16x32_bf16 v[50:53], v[158:161], v[166:169], v[50:53]
	v_mfma_f32_16x16x32_bf16 v[54:57], v[150:153], v[166:169], v[54:57]
	s_barrier
	s_setprio 0
.LBB0_312:
	v_add_u32_e32 v0, 0x10000, v237
	ds_read_b128 v[130:133], v0
	ds_read_b128 v[134:137], v0 offset:1024
	ds_read_b128 v[138:141], v0 offset:2048
	ds_read_b128 v[142:145], v0 offset:3072
	v_add_u32_e32 v0, 0x14000, v237
	ds_read_b128 v[146:149], v0
	ds_read_b128 v[150:153], v0 offset:1024
	ds_read_b128 v[154:157], v0 offset:2048
	ds_read_b128 v[158:161], v0 offset:3072
	s_add_u32 s16, s12, 0x100
	s_addc_u32 s17, s13, 0
	s_sub_i32 s12, s12, s4
	s_add_i32 s12, s12, 0x80080
	s_sub_i32 s36, s12, 0x80000
	s_cmp_eq_u32 s23, 28
	s_cselect_b32 s13, s19, s16
	s_mov_b32 m0, s69
	ds_read_b128 v[162:165], v238
	ds_read_b128 v[166:169], v238 offset:1024
	ds_read_b128 v[170:173], v238 offset:2048
	ds_read_b128 v[174:177], v238 offset:3072
	ds_read_b128 v[178:181], v238 offset:4096
	ds_read_b128 v[182:185], v238 offset:5120
	ds_read_b128 v[186:189], v238 offset:6144
	ds_read_b128 v[190:193], v238 offset:7168
	s_mov_b32 m0, s78
	s_nop 0
	buffer_load_dwordx4 v211, s[4:7], s36 offen lds
	s_mov_b32 m0, s69
	s_nop 0
	buffer_load_dwordx4 v195, s[4:7], s12 offen lds
	s_mov_b32 m0, s67
	s_nop 0
	buffer_load_dwordx4 v211, s[4:7], s12 offen lds
	s_waitcnt vmcnt(8)
	s_waitcnt lgkmcnt(0)
	s_setprio 1
	s_barrier
	v_mfma_f32_16x16x32_bf16 v[126:129], v[130:133], v[162:165], v[126:129]
	v_mfma_f32_16x16x32_bf16 v[122:125], v[138:141], v[162:165], v[122:125]
	v_mfma_f32_16x16x32_bf16 v[106:109], v[138:141], v[170:173], v[106:109]
	v_mfma_f32_16x16x32_bf16 v[110:113], v[130:133], v[170:173], v[110:113]
	v_mfma_f32_16x16x32_bf16 v[94:97], v[130:133], v[178:181], v[94:97]
	v_mfma_f32_16x16x32_bf16 v[90:93], v[138:141], v[178:181], v[90:93]
	v_mfma_f32_16x16x32_bf16 v[74:77], v[138:141], v[186:189], v[74:77]
	v_mfma_f32_16x16x32_bf16 v[78:81], v[130:133], v[186:189], v[78:81]
	s_cselect_b32 s12, s15, s20
	v_mfma_f32_16x16x32_bf16 v[70:73], v[146:149], v[186:189], v[70:73]
	s_mov_b32 m0, s61
	v_mfma_f32_16x16x32_bf16 v[66:69], v[154:157], v[186:189], v[66:69]
	s_mov_b32 s42, s6
	v_mfma_f32_16x16x32_bf16 v[82:85], v[154:157], v[178:181], v[82:85]
	s_mov_b32 s43, s7
	v_mfma_f32_16x16x32_bf16 v[86:89], v[146:149], v[178:181], v[86:89]
	s_sub_i32 s12, s12, s40
	v_mfma_f32_16x16x32_bf16 v[102:105], v[146:149], v[170:173], v[102:105]
	v_mfma_f32_16x16x32_bf16 v[98:101], v[154:157], v[170:173], v[98:101]
	v_mfma_f32_16x16x32_bf16 v[114:117], v[154:157], v[162:165], v[114:117]
	v_mfma_f32_16x16x32_bf16 v[118:121], v[146:149], v[162:165], v[118:121]
	v_mfma_f32_16x16x32_bf16 v[126:129], v[134:137], v[166:169], v[126:129]
	v_mfma_f32_16x16x32_bf16 v[122:125], v[142:145], v[166:169], v[122:125]
	v_mfma_f32_16x16x32_bf16 v[106:109], v[142:145], v[174:177], v[106:109]
	v_mfma_f32_16x16x32_bf16 v[110:113], v[134:137], v[174:177], v[110:113]
	v_mfma_f32_16x16x32_bf16 v[94:97], v[134:137], v[182:185], v[94:97]
	v_mfma_f32_16x16x32_bf16 v[90:93], v[142:145], v[182:185], v[90:93]
	v_mfma_f32_16x16x32_bf16 v[74:77], v[142:145], v[190:193], v[74:77]
	v_mfma_f32_16x16x32_bf16 v[78:81], v[134:137], v[190:193], v[78:81]
	v_mfma_f32_16x16x32_bf16 v[70:73], v[150:153], v[190:193], v[70:73]
	v_mfma_f32_16x16x32_bf16 v[66:69], v[158:161], v[190:193], v[66:69]
	v_mfma_f32_16x16x32_bf16 v[82:85], v[158:161], v[182:185], v[82:85]
	v_mfma_f32_16x16x32_bf16 v[86:89], v[150:153], v[182:185], v[86:89]
	v_mfma_f32_16x16x32_bf16 v[102:105], v[150:153], v[174:177], v[102:105]
	v_mfma_f32_16x16x32_bf16 v[98:101], v[158:161], v[174:177], v[98:101]
	v_mfma_f32_16x16x32_bf16 v[114:117], v[158:161], v[166:169], v[114:117]
	v_mfma_f32_16x16x32_bf16 v[118:121], v[150:153], v[166:169], v[118:121]
	s_barrier
; #define PG8_STAGE(bufoff, gbase, voff) do { const int so_ = (int)(unsigned)((const char*)(gbase) - base_##voff); _Pragma("unroll") for (int _i = 0; _i < 2; ++_i) \
;         __builtin_amdgcn_raw_ptr_buffer_load_lds(rs_##voff, (PG8_LAS unsigned*)(lds + (bufoff) + ldsw + _i * 8192), 16, (int)(voff)[_i], so_, 0, 0); } while (0)
; #define PG8_LDA(dst, b, h) do { _Pragma("unroll") for (int m = 0; m < 4; ++m) _Pragma("unroll") for (int k = 0; k < 2; ++k) dst[m][k] = *(const PG8_LAS bf16x8*)(lds + PG8_SA(b, h) + aoff + m * 2048 + k * 1024); } while (0)
; #define PG8_LDB(dst, b, h) do { _Pragma("unroll") for (int n = 0; n < 2; ++n) _Pragma("unroll") for (int k = 0; k < 2; ++k) dst[n][k] = *(const PG8_LAS bf16x8*)(lds + PG8_SB(b, h) + boff + n * 2048 + k * 1024); } while (0)
; #define PG8_MMA(ai, bj, At, Bt) do { __builtin_amdgcn_s_setprio(1); _Pragma("unroll") for (int m = 0; m < 4; ++m) _Pragma("unroll") for (int n = 0; n < 2; ++n) _Pragma("unroll") for (int k = 0; k < 2; ++k) \
;         acc[ai][bj][m][n] = __builtin_amdgcn_mfma_f32_16x16x32_bf16(Bt[n][k], At[m][k], acc[ai][bj][m][n], 0, 0, 0); __builtin_amdgcn_s_setprio(0); } while (0)
; #define PG8_WAIT_V(n) asm volatile("s_waitcnt vmcnt(" #n ")" ::: "memory")
; #define PG8_WAIT_L(n) asm volatile("s_waitcnt lgkmcnt(" #n ")" ::: "memory")
; #define PG8_BAR __builtin_amdgcn_s_barrier()
; #define PG8_SCHED __builtin_amdgcn_sched_barrier(0)
; template <class Epi, class Sched, bool ALIGN_EPI = false, bool SP2 = false>
; __device__ __forceinline__ void gemm_phase(PG8_LAS unsigned char* lds, const Gemm g, const Sched& S, const Epi& E, int tid_in) {
;     ...
;             PG8_LDB(B0, 0, 0); PG8_LDB(B1, 0, 1); PG8_SCHED; PG8_LDA(At, 0, 0); PG8_STAGE(PG8_SA(1, 1), a1 + hstepA, voffA);
;             PG8_WAIT_V(8); PG8_WAIT_L(0); PG8_BAR; PG8_MMA(0, 0, At, B0); PG8_MMA(0, 1, At, B1); PG8_BAR; PG8_SCHED;
;             PG8_LDA(At, 0, 1); PG8_STAGE(PG8_SB(0, 0), b2, voffB); PG8_STAGE(PG8_SB(0, 1), b2 + hstepB, voffB); PG8_STAGE(PG8_SA(0, 0), a2, voffA);
;             PG8_WAIT_V(8); PG8_WAIT_L(0); PG8_BAR; PG8_MMA(1, 0, At, B0); PG8_MMA(1, 1, At, B1); PG8_BAR; PG8_SCHED;
;             PG8_LDB(B0, 1, 0); PG8_LDB(B1, 1, 1); PG8_SCHED; PG8_LDA(At, 1, 0); PG8_STAGE(PG8_SA(0, 1), a2 + hstepA, voffA);
;             PG8_WAIT_V(8); PG8_WAIT_L(0); PG8_BAR; PG8_MMA(0, 0, At, B0); PG8_MMA(0, 1, At, B1); PG8_BAR; PG8_SCHED;
	s_setprio 0
	ds_read_b128 v[162:165], v238 offset:16384
	ds_read_b128 v[166:169], v238 offset:17408
	ds_read_b128 v[170:173], v238 offset:18432
	ds_read_b128 v[174:177], v238 offset:19456
	ds_read_b128 v[178:181], v238 offset:20480
	ds_read_b128 v[182:185], v238 offset:21504
	ds_read_b128 v[186:189], v238 offset:22528
	ds_read_b128 v[190:193], v238 offset:23552
	buffer_load_dwordx4 v207, s[40:43], s12 offen lds
	s_mov_b32 m0, s62
	s_add_i32 s36, s12, 0x80000
	buffer_load_dwordx4 v224, s[40:43], s12 offen lds
	s_mov_b32 m0, s63
	s_sub_i32 s13, s13, s4
	buffer_load_dwordx4 v207, s[40:43], s36 offen lds
	s_mov_b32 m0, s71
	s_nop 0
	buffer_load_dwordx4 v224, s[40:43], s36 offen lds
	s_mov_b32 m0, s53
	s_nop 0
	buffer_load_dwordx4 v195, s[4:7], s13 offen lds
	s_waitcnt vmcnt(7)
	s_waitcnt lgkmcnt(0)
	s_setprio 1
	s_barrier
	v_mfma_f32_16x16x32_bf16 v[62:65], v[130:133], v[162:165], v[62:65]
	v_mfma_f32_16x16x32_bf16 v[58:61], v[138:141], v[162:165], v[58:61]
	v_mfma_f32_16x16x32_bf16 v[42:45], v[138:141], v[170:173], v[42:45]
	v_mfma_f32_16x16x32_bf16 v[46:49], v[130:133], v[170:173], v[46:49]
	v_mfma_f32_16x16x32_bf16 v[30:33], v[130:133], v[178:181], v[30:33]
	v_mfma_f32_16x16x32_bf16 v[26:29], v[138:141], v[178:181], v[26:29]
	v_mfma_f32_16x16x32_bf16 v[10:13], v[138:141], v[186:189], v[10:13]
	v_mfma_f32_16x16x32_bf16 v[14:17], v[130:133], v[186:189], v[14:17]
	v_mfma_f32_16x16x32_bf16 v[6:9], v[146:149], v[186:189], v[6:9]
	v_mfma_f32_16x16x32_bf16 v[2:5], v[154:157], v[186:189], v[2:5]
	v_mfma_f32_16x16x32_bf16 v[18:21], v[154:157], v[178:181], v[18:21]
	v_mfma_f32_16x16x32_bf16 v[22:25], v[146:149], v[178:181], v[22:25]
	v_mfma_f32_16x16x32_bf16 v[38:41], v[146:149], v[170:173], v[38:41]
	v_mfma_f32_16x16x32_bf16 v[34:37], v[154:157], v[170:173], v[34:37]
	v_mfma_f32_16x16x32_bf16 v[50:53], v[154:157], v[162:165], v[50:53]
	v_mfma_f32_16x16x32_bf16 v[54:57], v[146:149], v[162:165], v[54:57]
	v_mfma_f32_16x16x32_bf16 v[62:65], v[134:137], v[166:169], v[62:65]
	v_mfma_f32_16x16x32_bf16 v[58:61], v[142:145], v[166:169], v[58:61]
	v_mfma_f32_16x16x32_bf16 v[42:45], v[142:145], v[174:177], v[42:45]
	v_mfma_f32_16x16x32_bf16 v[46:49], v[134:137], v[174:177], v[46:49]
	v_mfma_f32_16x16x32_bf16 v[30:33], v[134:137], v[182:185], v[30:33]
	v_mfma_f32_16x16x32_bf16 v[26:29], v[142:145], v[182:185], v[26:29]
	v_mfma_f32_16x16x32_bf16 v[10:13], v[142:145], v[190:193], v[10:13]
	v_mfma_f32_16x16x32_bf16 v[14:17], v[134:137], v[190:193], v[14:17]
	v_mfma_f32_16x16x32_bf16 v[6:9], v[150:153], v[190:193], v[6:9]
	v_mfma_f32_16x16x32_bf16 v[2:5], v[158:161], v[190:193], v[2:5]
	v_mfma_f32_16x16x32_bf16 v[18:21], v[158:161], v[182:185], v[18:21]
	v_mfma_f32_16x16x32_bf16 v[22:25], v[150:153], v[182:185], v[22:25]
	v_mfma_f32_16x16x32_bf16 v[38:41], v[150:153], v[174:177], v[38:41]
	v_mfma_f32_16x16x32_bf16 v[34:37], v[158:161], v[174:177], v[34:37]
	v_mfma_f32_16x16x32_bf16 v[50:53], v[158:161], v[166:169], v[50:53]
	v_mfma_f32_16x16x32_bf16 v[54:57], v[150:153], v[166:169], v[54:57]
	s_barrier
	s_setprio 0
	v_add_u32_e32 v0, 0x18000, v237
	ds_read_b128 v[130:133], v0
	ds_read_b128 v[134:137], v0 offset:1024
	ds_read_b128 v[138:141], v0 offset:2048
	ds_read_b128 v[142:145], v0 offset:3072
	v_add_u32_e32 v0, 0x1c000, v237
	ds_read_b128 v[146:149], v0
	ds_read_b128 v[150:153], v0 offset:1024
	ds_read_b128 v[154:157], v0 offset:2048
	ds_read_b128 v[158:161], v0 offset:3072
	s_add_i32 s36, s13, 0x80000
	s_mov_b32 m0, s73
	ds_read_b128 v[162:165], v238 offset:32768
	ds_read_b128 v[166:169], v238 offset:33792
	ds_read_b128 v[170:173], v238 offset:34816
	ds_read_b128 v[174:177], v238 offset:35840
	ds_read_b128 v[178:181], v238 offset:36864
	ds_read_b128 v[182:185], v238 offset:37888
	ds_read_b128 v[186:189], v238 offset:38912
	ds_read_b128 v[190:193], v238 offset:39936
	s_mov_b32 m0, s72
	s_nop 0
	buffer_load_dwordx4 v211, s[4:7], s13 offen lds
	s_mov_b32 m0, s73
	s_nop 0
	buffer_load_dwordx4 v195, s[4:7], s36 offen lds
	s_mov_b32 m0, s74
	s_nop 0
	buffer_load_dwordx4 v211, s[4:7], s36 offen lds
	s_waitcnt vmcnt(8)
	s_waitcnt lgkmcnt(0)
	s_setprio 1
	s_barrier
; #define PG8_STAGE(bufoff, gbase, voff) do { const int so_ = (int)(unsigned)((const char*)(gbase) - base_##voff); _Pragma("unroll") for (int _i = 0; _i < 2; ++_i) \
;         __builtin_amdgcn_raw_ptr_buffer_load_lds(rs_##voff, (PG8_LAS unsigned*)(lds + (bufoff) + ldsw + _i * 8192), 16, (int)(voff)[_i], so_, 0, 0); } while (0)
; #define PG8_LDA(dst, b, h) do { _Pragma("unroll") for (int m = 0; m < 4; ++m) _Pragma("unroll") for (int k = 0; k < 2; ++k) dst[m][k] = *(const PG8_LAS bf16x8*)(lds + PG8_SA(b, h) + aoff + m * 2048 + k * 1024); } while (0)
; #define PG8_WAIT_V(n) asm volatile("s_waitcnt vmcnt(" #n ")" ::: "memory")
; #define PG8_WAIT_L(n) asm volatile("s_waitcnt lgkmcnt(" #n ")" ::: "memory")
; template <class Epi, class Sched, bool ALIGN_EPI = false, bool SP2 = false>
; __device__ __forceinline__ void gemm_phase(PG8_LAS unsigned char* lds, const Gemm g, const Sched& S, const Epi& E, int tid_in) {
;     ...
;         for (int t = 0; t < nt; t += 2) {
;             const bool last = (t == nt - 2);
;             const char* a1 = cA + (size_t)(t + 1) * kstep;
;             const char* a2 = last ? nA : cA + (size_t)(t + 2) * kstep; const char* b2 = last ? nB : cB + (size_t)(t + 2) * kstep;
;             const char* a3 = a2 + kstep; const char* b3 = b2 + kstep;
;             if (last && has_next) S.a_ready(nxt);
;             if constexpr (SP2) {
;             PG8_LDB(B0, 0, 0); PG8_LDB(B1, 0, 1); PG8_SCHED; PG8_LDA(At, 0, 0); PG8_STAGE(PG8_SA(1, 1), a1 + hstepA, voffA);
;             PG8_WAIT_V(8); PG8_WAIT_L(0); PG8_BAR; PG8_MMA(0, 0, At, B0); PG8_MMA(0, 1, At, B1); PG8_BAR; PG8_SCHED;
;             PG8_LDA(At, 0, 1); PG8_STAGE(PG8_SB(0, 0), b2, voffB); PG8_STAGE(PG8_SB(0, 1), b2 + hstepB, voffB); PG8_STAGE(PG8_SA(0, 0), a2, voffA);
;             PG8_WAIT_V(8); PG8_WAIT_L(0); PG8_BAR; PG8_MMA(1, 0, At, B0); PG8_MMA(1, 1, At, B1); PG8_BAR; PG8_SCHED;
;             PG8_LDB(B0, 1, 0); PG8_LDB(B1, 1, 1); PG8_SCHED; PG8_LDA(At, 1, 0); PG8_STAGE(PG8_SA(0, 1), a2 + hstepA, voffA);
;             PG8_WAIT_V(8); PG8_WAIT_L(0); PG8_BAR; PG8_MMA(0, 0, At, B0); PG8_MMA(0, 1, At, B1); PG8_BAR; PG8_SCHED;
;             PG8_LDA(At, 1, 1); PG8_STAGE(PG8_SB(1, 0), b3, voffB); PG8_STAGE(PG8_SB(1, 1), b3 + hstepB, voffB); PG8_STAGE(PG8_SA(1, 0), a3, voffA);
;             PG8_WAIT_V(8); PG8_WAIT_L(0); PG8_BAR; PG8_MMA(1, 0, At, B0); PG8_MMA(1, 1, At, B1); PG8_BAR; PG8_SCHED;
	v_mfma_f32_16x16x32_bf16 v[126:129], v[130:133], v[162:165], v[126:129]
	v_mfma_f32_16x16x32_bf16 v[122:125], v[138:141], v[162:165], v[122:125]
	v_mfma_f32_16x16x32_bf16 v[106:109], v[138:141], v[170:173], v[106:109]
	v_mfma_f32_16x16x32_bf16 v[110:113], v[130:133], v[170:173], v[110:113]
	v_mfma_f32_16x16x32_bf16 v[94:97], v[130:133], v[178:181], v[94:97]
	v_mfma_f32_16x16x32_bf16 v[90:93], v[138:141], v[178:181], v[90:93]
	v_mfma_f32_16x16x32_bf16 v[74:77], v[138:141], v[186:189], v[74:77]
	v_mfma_f32_16x16x32_bf16 v[78:81], v[130:133], v[186:189], v[78:81]
	s_mov_b32 m0, s75
	v_mfma_f32_16x16x32_bf16 v[70:73], v[146:149], v[186:189], v[70:73]
	s_add_i32 s36, s12, 0x80
	v_mfma_f32_16x16x32_bf16 v[66:69], v[154:157], v[186:189], v[66:69]
	v_mfma_f32_16x16x32_bf16 v[82:85], v[154:157], v[178:181], v[82:85]
	v_mfma_f32_16x16x32_bf16 v[86:89], v[146:149], v[178:181], v[86:89]
	v_mfma_f32_16x16x32_bf16 v[102:105], v[146:149], v[170:173], v[102:105]
	v_mfma_f32_16x16x32_bf16 v[98:101], v[154:157], v[170:173], v[98:101]
	v_mfma_f32_16x16x32_bf16 v[114:117], v[154:157], v[162:165], v[114:117]
	v_mfma_f32_16x16x32_bf16 v[118:121], v[146:149], v[162:165], v[118:121]
	v_mfma_f32_16x16x32_bf16 v[126:129], v[134:137], v[166:169], v[126:129]
	v_mfma_f32_16x16x32_bf16 v[122:125], v[142:145], v[166:169], v[122:125]
	v_mfma_f32_16x16x32_bf16 v[106:109], v[142:145], v[174:177], v[106:109]
	v_mfma_f32_16x16x32_bf16 v[110:113], v[134:137], v[174:177], v[110:113]
	v_mfma_f32_16x16x32_bf16 v[94:97], v[134:137], v[182:185], v[94:97]
	v_mfma_f32_16x16x32_bf16 v[90:93], v[142:145], v[182:185], v[90:93]
	v_mfma_f32_16x16x32_bf16 v[74:77], v[142:145], v[190:193], v[74:77]
	v_mfma_f32_16x16x32_bf16 v[78:81], v[134:137], v[190:193], v[78:81]
	v_mfma_f32_16x16x32_bf16 v[70:73], v[150:153], v[190:193], v[70:73]
	v_mfma_f32_16x16x32_bf16 v[66:69], v[158:161], v[190:193], v[66:69]
	v_mfma_f32_16x16x32_bf16 v[82:85], v[158:161], v[182:185], v[82:85]
	v_mfma_f32_16x16x32_bf16 v[86:89], v[150:153], v[182:185], v[86:89]
	v_mfma_f32_16x16x32_bf16 v[102:105], v[150:153], v[174:177], v[102:105]
	v_mfma_f32_16x16x32_bf16 v[98:101], v[158:161], v[174:177], v[98:101]
	v_mfma_f32_16x16x32_bf16 v[114:117], v[158:161], v[166:169], v[114:117]
	v_mfma_f32_16x16x32_bf16 v[118:121], v[150:153], v[166:169], v[118:121]
	s_barrier
	s_setprio 0
	ds_read_b128 v[162:165], v238 offset:49152
	ds_read_b128 v[166:169], v238 offset:50176
	ds_read_b128 v[170:173], v238 offset:51200
	ds_read_b128 v[174:177], v238 offset:52224
	ds_read_b128 v[178:181], v238 offset:53248
	ds_read_b128 v[182:185], v238 offset:54272
	ds_read_b128 v[186:189], v238 offset:55296
	ds_read_b128 v[190:193], v238 offset:56320
	buffer_load_dwordx4 v207, s[40:43], s36 offen lds
	s_mov_b32 m0, s76
	s_add_i32 s12, s12, 0x80080
	buffer_load_dwordx4 v224, s[40:43], s36 offen lds
	s_mov_b32 m0, s79
	s_addk_i32 s13, 0x80
	buffer_load_dwordx4 v207, s[40:43], s12 offen lds
	s_mov_b32 m0, s68
	s_nop 0
	buffer_load_dwordx4 v224, s[40:43], s12 offen lds
	s_mov_b32 m0, s77
	s_nop 0
	buffer_load_dwordx4 v195, s[4:7], s13 offen lds
	s_waitcnt vmcnt(7)
	s_waitcnt lgkmcnt(0)
	s_setprio 1
	s_barrier
	v_mfma_f32_16x16x32_bf16 v[62:65], v[130:133], v[162:165], v[62:65]
	v_mfma_f32_16x16x32_bf16 v[58:61], v[138:141], v[162:165], v[58:61]
	v_mfma_f32_16x16x32_bf16 v[42:45], v[138:141], v[170:173], v[42:45]
	v_mfma_f32_16x16x32_bf16 v[46:49], v[130:133], v[170:173], v[46:49]
	v_mfma_f32_16x16x32_bf16 v[30:33], v[130:133], v[178:181], v[30:33]
	v_mfma_f32_16x16x32_bf16 v[26:29], v[138:141], v[178:181], v[26:29]
	v_mfma_f32_16x16x32_bf16 v[10:13], v[138:141], v[186:189], v[10:13]
	v_mfma_f32_16x16x32_bf16 v[14:17], v[130:133], v[186:189], v[14:17]
	s_add_i32 s23, s23, 2
	v_mfma_f32_16x16x32_bf16 v[6:9], v[146:149], v[186:189], v[6:9]
	s_add_u32 s20, s20, 0x100
	v_mfma_f32_16x16x32_bf16 v[2:5], v[154:157], v[186:189], v[2:5]
	s_addc_u32 s21, s21, 0
	v_mfma_f32_16x16x32_bf16 v[18:21], v[154:157], v[178:181], v[18:21]
	s_cmp_gt_u32 s23, 29
	v_mfma_f32_16x16x32_bf16 v[22:25], v[146:149], v[178:181], v[22:25]
	s_mov_b64 s[12:13], s[16:17]
	v_mfma_f32_16x16x32_bf16 v[38:41], v[146:149], v[170:173], v[38:41]
	v_mfma_f32_16x16x32_bf16 v[34:37], v[154:157], v[170:173], v[34:37]
	v_mfma_f32_16x16x32_bf16 v[50:53], v[154:157], v[162:165], v[50:53]
	v_mfma_f32_16x16x32_bf16 v[54:57], v[146:149], v[162:165], v[54:57]
	v_mfma_f32_16x16x32_bf16 v[62:65], v[134:137], v[166:169], v[62:65]
	v_mfma_f32_16x16x32_bf16 v[58:61], v[142:145], v[166:169], v[58:61]
	v_mfma_f32_16x16x32_bf16 v[42:45], v[142:145], v[174:177], v[42:45]
	v_mfma_f32_16x16x32_bf16 v[46:49], v[134:137], v[174:177], v[46:49]
	v_mfma_f32_16x16x32_bf16 v[30:33], v[134:137], v[182:185], v[30:33]
	v_mfma_f32_16x16x32_bf16 v[26:29], v[142:145], v[182:185], v[26:29]
	v_mfma_f32_16x16x32_bf16 v[10:13], v[142:145], v[190:193], v[10:13]
	v_mfma_f32_16x16x32_bf16 v[14:17], v[134:137], v[190:193], v[14:17]
	v_mfma_f32_16x16x32_bf16 v[6:9], v[150:153], v[190:193], v[6:9]
	v_mfma_f32_16x16x32_bf16 v[2:5], v[158:161], v[190:193], v[2:5]
	v_mfma_f32_16x16x32_bf16 v[18:21], v[158:161], v[182:185], v[18:21]
	v_mfma_f32_16x16x32_bf16 v[22:25], v[150:153], v[182:185], v[22:25]
	v_mfma_f32_16x16x32_bf16 v[38:41], v[150:153], v[174:177], v[38:41]
	v_mfma_f32_16x16x32_bf16 v[34:37], v[158:161], v[174:177], v[34:37]
	v_mfma_f32_16x16x32_bf16 v[50:53], v[158:161], v[166:169], v[50:53]
	v_mfma_f32_16x16x32_bf16 v[54:57], v[150:153], v[166:169], v[54:57]
	s_barrier
	s_setprio 0
	s_cbranch_scc0 .LBB0_312
	s_and_b64 vcc, exec, s[48:49]
	s_cbranch_vccz .LBB0_315
	s_barrier

; #define PG8_STAGE(bufoff, gbase, voff) do { const int so_ = (int)(unsigned)((const char*)(gbase) - base_##voff); _Pragma("unroll") for (int _i = 0; _i < 2; ++_i) \
;         __builtin_amdgcn_raw_ptr_buffer_load_lds(rs_##voff, (PG8_LAS unsigned*)(lds + (bufoff) + ldsw + _i * 8192), 16, (int)(voff)[_i], so_, 0, 0); } while (0)
; #define PG8_LDA(dst, b, h) do { _Pragma("unroll") for (int m = 0; m < 4; ++m) _Pragma("unroll") for (int k = 0; k < 2; ++k) dst[m][k] = *(const PG8_LAS bf16x8*)(lds + PG8_SA(b, h) + aoff + m * 2048 + k * 1024); } while (0)
; #define PG8_LDB(dst, b, h) do { _Pragma("unroll") for (int n = 0; n < 2; ++n) _Pragma("unroll") for (int k = 0; k < 2; ++k) dst[n][k] = *(const PG8_LAS bf16x8*)(lds + PG8_SB(b, h) + boff + n * 2048 + k * 1024); } while (0)
; #define PG8_MMA(ai, bj, At, Bt) do { __builtin_amdgcn_s_setprio(1); _Pragma("unroll") for (int m = 0; m < 4; ++m) _Pragma("unroll") for (int n = 0; n < 2; ++n) _Pragma("unroll") for (int k = 0; k < 2; ++k) \
;         acc[ai][bj][m][n] = __builtin_amdgcn_mfma_f32_16x16x32_bf16(Bt[n][k], At[m][k], acc[ai][bj][m][n], 0, 0, 0); __builtin_amdgcn_s_setprio(0); } while (0)
; #define PG8_WAIT_V(n) asm volatile("s_waitcnt vmcnt(" #n ")" ::: "memory")
; #define PG8_WAIT_L(n) asm volatile("s_waitcnt lgkmcnt(" #n ")" ::: "memory")
; #define PG8_BAR __builtin_amdgcn_s_barrier()
; #define PG8_SCHED __builtin_amdgcn_sched_barrier(0)
; template <class Epi, class Sched, bool ALIGN_EPI = false, bool SP2 = false>
; __device__ __forceinline__ void gemm_phase(PG8_LAS unsigned char* lds, const Gemm g, const Sched& S, const Epi& E, int tid_in) {
;     ...
;             PG8_LDB(B0, 0, 0); PG8_LDB(B1, 0, 1); PG8_SCHED; PG8_LDA(At, 0, 0); PG8_STAGE(PG8_SA(1, 1), a1 + hstepA, voffA);
;             PG8_WAIT_V(8); PG8_WAIT_L(0); PG8_BAR; PG8_MMA(0, 0, At, B0); PG8_MMA(0, 1, At, B1); PG8_BAR; PG8_SCHED;
;             PG8_LDA(At, 0, 1); PG8_STAGE(PG8_SB(0, 0), b2, voffB); PG8_STAGE(PG8_SB(0, 1), b2 + hstepB, voffB); PG8_STAGE(PG8_SA(0, 0), a2, voffA);
;             PG8_WAIT_V(8); PG8_WAIT_L(0); PG8_BAR; PG8_MMA(1, 0, At, B0); PG8_MMA(1, 1, At, B1); PG8_BAR; PG8_SCHED;
;             PG8_LDB(B0, 1, 0); PG8_LDB(B1, 1, 1); PG8_SCHED; PG8_LDA(At, 1, 0); PG8_STAGE(PG8_SA(0, 1), a2 + hstepA, voffA);
;             PG8_WAIT_V(8); PG8_WAIT_L(0); PG8_BAR; PG8_MMA(0, 0, At, B0); PG8_MMA(0, 1, At, B1); PG8_BAR; PG8_SCHED;
.LBB0_1037:
	v_add_u32_e32 v0, 0x10000, v236
	ds_read_b128 v[132:135], v0
	ds_read_b128 v[136:139], v0 offset:1024
	ds_read_b128 v[140:143], v0 offset:2048
	ds_read_b128 v[144:147], v0 offset:3072
	v_add_u32_e32 v0, 0x14000, v236
	ds_read_b128 v[148:151], v0
	ds_read_b128 v[152:155], v0 offset:1024
	ds_read_b128 v[156:159], v0 offset:2048
	ds_read_b128 v[160:163], v0 offset:3072
	s_add_u32 s16, s12, 0x100
	s_addc_u32 s17, s13, 0
	s_sub_i32 s12, s12, s4
	s_add_i32 s12, s12, 0xc0080
	s_sub_i32 s39, s12, 0xc0000
	s_cmp_eq_u32 s38, 12
	s_cselect_b32 s13, s24, s16
	s_mov_b32 m0, s76
	ds_read_b128 v[164:167], v237
	ds_read_b128 v[168:171], v237 offset:1024
	ds_read_b128 v[172:175], v237 offset:2048
	ds_read_b128 v[176:179], v237 offset:3072
	ds_read_b128 v[180:183], v237 offset:4096
	ds_read_b128 v[184:187], v237 offset:5120
	ds_read_b128 v[188:191], v237 offset:6144
	ds_read_b128 v[192:195], v237 offset:7168
	s_mov_b32 m0, s73
	s_nop 0
	buffer_load_dwordx4 v222, s[4:7], s39 offen lds
	s_mov_b32 m0, s76
	s_nop 0
	buffer_load_dwordx4 v220, s[4:7], s12 offen lds
	s_mov_b32 m0, s77
	s_nop 0
	buffer_load_dwordx4 v222, s[4:7], s12 offen lds
	s_waitcnt vmcnt(8)
	s_waitcnt lgkmcnt(0)
	s_setprio 1
	s_barrier
	v_mfma_f32_16x16x32_bf16 v[128:131], v[132:135], v[164:167], v[128:131]
	v_mfma_f32_16x16x32_bf16 v[124:127], v[140:143], v[164:167], v[124:127]
	v_mfma_f32_16x16x32_bf16 v[116:119], v[140:143], v[172:175], v[116:119]
	v_mfma_f32_16x16x32_bf16 v[120:123], v[132:135], v[172:175], v[120:123]
	v_mfma_f32_16x16x32_bf16 v[112:115], v[132:135], v[180:183], v[112:115]
	v_mfma_f32_16x16x32_bf16 v[108:111], v[140:143], v[180:183], v[108:111]
	v_mfma_f32_16x16x32_bf16 v[100:103], v[140:143], v[188:191], v[100:103]
	v_mfma_f32_16x16x32_bf16 v[104:107], v[132:135], v[188:191], v[104:107]
	s_cselect_b32 s12, s18, s19
	v_mfma_f32_16x16x32_bf16 v[72:75], v[148:151], v[188:191], v[72:75]
	s_mov_b32 m0, s26
	v_mfma_f32_16x16x32_bf16 v[68:71], v[156:159], v[188:191], v[68:71]
	s_mov_b32 s46, s6
	v_mfma_f32_16x16x32_bf16 v[76:79], v[156:159], v[180:183], v[76:79]
	s_mov_b32 s47, s7
	v_mfma_f32_16x16x32_bf16 v[80:83], v[148:151], v[180:183], v[80:83]
	s_sub_i32 s12, s12, s44
	v_mfma_f32_16x16x32_bf16 v[88:91], v[148:151], v[172:175], v[88:91]
	v_mfma_f32_16x16x32_bf16 v[84:87], v[156:159], v[172:175], v[84:87]
	v_mfma_f32_16x16x32_bf16 v[92:95], v[156:159], v[164:167], v[92:95]
	v_mfma_f32_16x16x32_bf16 v[96:99], v[148:151], v[164:167], v[96:99]
	v_mfma_f32_16x16x32_bf16 v[128:131], v[136:139], v[168:171], v[128:131]
	v_mfma_f32_16x16x32_bf16 v[124:127], v[144:147], v[168:171], v[124:127]
	v_mfma_f32_16x16x32_bf16 v[116:119], v[144:147], v[176:179], v[116:119]
	v_mfma_f32_16x16x32_bf16 v[120:123], v[136:139], v[176:179], v[120:123]
	v_mfma_f32_16x16x32_bf16 v[112:115], v[136:139], v[184:187], v[112:115]
	v_mfma_f32_16x16x32_bf16 v[108:111], v[144:147], v[184:187], v[108:111]
	v_mfma_f32_16x16x32_bf16 v[100:103], v[144:147], v[192:195], v[100:103]
	v_mfma_f32_16x16x32_bf16 v[104:107], v[136:139], v[192:195], v[104:107]
	v_mfma_f32_16x16x32_bf16 v[72:75], v[152:155], v[192:195], v[72:75]
	v_mfma_f32_16x16x32_bf16 v[68:71], v[160:163], v[192:195], v[68:71]
	v_mfma_f32_16x16x32_bf16 v[76:79], v[160:163], v[184:187], v[76:79]
	v_mfma_f32_16x16x32_bf16 v[80:83], v[152:155], v[184:187], v[80:83]
	v_mfma_f32_16x16x32_bf16 v[88:91], v[152:155], v[176:179], v[88:91]
	v_mfma_f32_16x16x32_bf16 v[84:87], v[160:163], v[176:179], v[84:87]
	v_mfma_f32_16x16x32_bf16 v[92:95], v[160:163], v[168:171], v[92:95]
	v_mfma_f32_16x16x32_bf16 v[96:99], v[152:155], v[168:171], v[96:99]
	s_barrier
	s_setprio 0
	ds_read_b128 v[164:167], v237 offset:16384
	ds_read_b128 v[168:171], v237 offset:17408
	ds_read_b128 v[172:175], v237 offset:18432
	ds_read_b128 v[176:179], v237 offset:19456
	ds_read_b128 v[180:183], v237 offset:20480
	ds_read_b128 v[184:187], v237 offset:21504
	ds_read_b128 v[188:191], v237 offset:22528
	ds_read_b128 v[192:195], v237 offset:23552
	buffer_load_dwordx4 v221, s[44:47], s12 offen lds
	s_mov_b32 m0, s53
	s_add_i32 s39, s12, 0x40000
	buffer_load_dwordx4 v223, s[44:47], s12 offen lds
	s_mov_b32 m0, s60
	s_sub_i32 s13, s13, s4
	buffer_load_dwordx4 v221, s[44:47], s39 offen lds
	s_mov_b32 m0, s61
	s_nop 0
	buffer_load_dwordx4 v223, s[44:47], s39 offen lds
	s_mov_b32 m0, s21
	s_nop 0
	buffer_load_dwordx4 v220, s[4:7], s13 offen lds
	s_waitcnt vmcnt(7)
	s_waitcnt lgkmcnt(0)
	s_setprio 1
	s_barrier
	v_mfma_f32_16x16x32_bf16 v[64:67], v[132:135], v[164:167], v[64:67]
	v_mfma_f32_16x16x32_bf16 v[60:63], v[140:143], v[164:167], v[60:63]
	v_mfma_f32_16x16x32_bf16 v[52:55], v[140:143], v[172:175], v[52:55]
	v_mfma_f32_16x16x32_bf16 v[56:59], v[132:135], v[172:175], v[56:59]
	v_mfma_f32_16x16x32_bf16 v[48:51], v[132:135], v[180:183], v[48:51]
	v_mfma_f32_16x16x32_bf16 v[44:47], v[140:143], v[180:183], v[44:47]
	v_mfma_f32_16x16x32_bf16 v[36:39], v[140:143], v[188:191], v[36:39]
	v_mfma_f32_16x16x32_bf16 v[40:43], v[132:135], v[188:191], v[40:43]
	v_mfma_f32_16x16x32_bf16 v[64:67], v[136:139], v[168:171], v[64:67]
	v_mfma_f32_16x16x32_bf16 v[60:63], v[144:147], v[168:171], v[60:63]
	v_mfma_f32_16x16x32_bf16 v[52:55], v[144:147], v[176:179], v[52:55]
	v_mfma_f32_16x16x32_bf16 v[56:59], v[136:139], v[176:179], v[56:59]
	v_mfma_f32_16x16x32_bf16 v[48:51], v[136:139], v[184:187], v[48:51]
	v_mfma_f32_16x16x32_bf16 v[44:47], v[144:147], v[184:187], v[44:47]
	v_mfma_f32_16x16x32_bf16 v[36:39], v[144:147], v[192:195], v[36:39]
	v_mfma_f32_16x16x32_bf16 v[40:43], v[136:139], v[192:195], v[40:43]
	v_mfma_f32_16x16x32_bf16 v[32:35], v[148:151], v[164:167], v[32:35]
	v_mfma_f32_16x16x32_bf16 v[28:31], v[156:159], v[164:167], v[28:31]
	v_mfma_f32_16x16x32_bf16 v[20:23], v[156:159], v[172:175], v[20:23]
	v_mfma_f32_16x16x32_bf16 v[24:27], v[148:151], v[172:175], v[24:27]
	v_mfma_f32_16x16x32_bf16 v[16:19], v[148:151], v[180:183], v[16:19]
	v_mfma_f32_16x16x32_bf16 v[12:15], v[156:159], v[180:183], v[12:15]
	v_mfma_f32_16x16x32_bf16 v[2:5], v[156:159], v[188:191], v[4:7]
	v_mfma_f32_16x16x32_bf16 v[8:11], v[148:151], v[188:191], v[8:11]
	v_mfma_f32_16x16x32_bf16 v[32:35], v[152:155], v[168:171], v[32:35]
	v_mfma_f32_16x16x32_bf16 v[28:31], v[160:163], v[168:171], v[28:31]
	v_mfma_f32_16x16x32_bf16 v[20:23], v[160:163], v[176:179], v[20:23]
	v_mfma_f32_16x16x32_bf16 v[24:27], v[152:155], v[176:179], v[24:27]
	v_mfma_f32_16x16x32_bf16 v[16:19], v[152:155], v[184:187], v[16:19]
	v_mfma_f32_16x16x32_bf16 v[12:15], v[160:163], v[184:187], v[12:15]
	v_mfma_f32_16x16x32_bf16 v[2:5], v[160:163], v[192:195], v[2:5]
	v_mfma_f32_16x16x32_bf16 v[8:11], v[152:155], v[192:195], v[8:11]
	s_barrier
; #define PG8_STAGE(bufoff, gbase, voff) do { const int so_ = (int)(unsigned)((const char*)(gbase) - base_##voff); _Pragma("unroll") for (int _i = 0; _i < 2; ++_i) \
;         __builtin_amdgcn_raw_ptr_buffer_load_lds(rs_##voff, (PG8_LAS unsigned*)(lds + (bufoff) + ldsw + _i * 8192), 16, (int)(voff)[_i], so_, 0, 0); } while (0)
; #define PG8_LDA(dst, b, h) do { _Pragma("unroll") for (int m = 0; m < 4; ++m) _Pragma("unroll") for (int k = 0; k < 2; ++k) dst[m][k] = *(const PG8_LAS bf16x8*)(lds + PG8_SA(b, h) + aoff + m * 2048 + k * 1024); } while (0)
; #define PG8_LDB(dst, b, h) do { _Pragma("unroll") for (int n = 0; n < 2; ++n) _Pragma("unroll") for (int k = 0; k < 2; ++k) dst[n][k] = *(const PG8_LAS bf16x8*)(lds + PG8_SB(b, h) + boff + n * 2048 + k * 1024); } while (0)
; #define PG8_MMA(ai, bj, At, Bt) do { __builtin_amdgcn_s_setprio(1); _Pragma("unroll") for (int m = 0; m < 4; ++m) _Pragma("unroll") for (int n = 0; n < 2; ++n) _Pragma("unroll") for (int k = 0; k < 2; ++k) \
;         acc[ai][bj][m][n] = __builtin_amdgcn_mfma_f32_16x16x32_bf16(Bt[n][k], At[m][k], acc[ai][bj][m][n], 0, 0, 0); __builtin_amdgcn_s_setprio(0); } while (0)
; #define PG8_WAIT_V(n) asm volatile("s_waitcnt vmcnt(" #n ")" ::: "memory")
; #define PG8_WAIT_L(n) asm volatile("s_waitcnt lgkmcnt(" #n ")" ::: "memory")
; #define PG8_BAR __builtin_amdgcn_s_barrier()
; #define PG8_SCHED __builtin_amdgcn_sched_barrier(0)
; template <class Epi, class Sched, bool ALIGN_EPI = false, bool SP2 = false>
; __device__ __forceinline__ void gemm_phase(PG8_LAS unsigned char* lds, const Gemm g, const Sched& S, const Epi& E, int tid_in) {
;     ...
;             PG8_LDB(B0, 1, 0); PG8_LDB(B1, 1, 1); PG8_SCHED; PG8_LDA(At, 1, 0); PG8_STAGE(PG8_SA(0, 1), a2 + hstepA, voffA);
;             PG8_WAIT_V(8); PG8_WAIT_L(0); PG8_BAR; PG8_MMA(0, 0, At, B0); PG8_MMA(0, 1, At, B1); PG8_BAR; PG8_SCHED;
;             PG8_LDA(At, 1, 1); PG8_STAGE(PG8_SB(1, 0), b3, voffB); PG8_STAGE(PG8_SB(1, 1), b3 + hstepB, voffB); PG8_STAGE(PG8_SA(1, 0), a3, voffA);
;             PG8_WAIT_V(8); PG8_WAIT_L(0); PG8_BAR; PG8_MMA(1, 0, At, B0); PG8_MMA(1, 1, At, B1); PG8_BAR; PG8_SCHED;
	s_setprio 0
	v_add_u32_e32 v0, 0x18000, v236
	ds_read_b128 v[132:135], v0
	ds_read_b128 v[136:139], v0 offset:1024
	ds_read_b128 v[140:143], v0 offset:2048
	ds_read_b128 v[144:147], v0 offset:3072
	v_add_u32_e32 v0, 0x1c000, v236
	ds_read_b128 v[148:151], v0
	ds_read_b128 v[152:155], v0 offset:1024
	ds_read_b128 v[156:159], v0 offset:2048
	ds_read_b128 v[160:163], v0 offset:3072
	s_add_i32 s39, s13, 0xc0000
	s_mov_b32 m0, s63
	ds_read_b128 v[164:167], v237 offset:32768
	ds_read_b128 v[168:171], v237 offset:33792
	ds_read_b128 v[172:175], v237 offset:34816
	ds_read_b128 v[176:179], v237 offset:35840
	ds_read_b128 v[180:183], v237 offset:36864
	ds_read_b128 v[184:187], v237 offset:37888
	ds_read_b128 v[188:191], v237 offset:38912
	ds_read_b128 v[192:195], v237 offset:39936
	s_mov_b32 m0, s62
	s_nop 0
	buffer_load_dwordx4 v222, s[4:7], s13 offen lds
	s_mov_b32 m0, s63
	s_nop 0
	buffer_load_dwordx4 v220, s[4:7], s39 offen lds
	s_mov_b32 m0, s66
	s_nop 0
	buffer_load_dwordx4 v222, s[4:7], s39 offen lds
	s_waitcnt vmcnt(8)
	s_waitcnt lgkmcnt(0)
	s_setprio 1
	s_barrier
	v_mfma_f32_16x16x32_bf16 v[128:131], v[132:135], v[164:167], v[128:131]
	v_mfma_f32_16x16x32_bf16 v[124:127], v[140:143], v[164:167], v[124:127]
	v_mfma_f32_16x16x32_bf16 v[116:119], v[140:143], v[172:175], v[116:119]
	v_mfma_f32_16x16x32_bf16 v[120:123], v[132:135], v[172:175], v[120:123]
	v_mfma_f32_16x16x32_bf16 v[112:115], v[132:135], v[180:183], v[112:115]
	v_mfma_f32_16x16x32_bf16 v[108:111], v[140:143], v[180:183], v[108:111]
	v_mfma_f32_16x16x32_bf16 v[100:103], v[140:143], v[188:191], v[100:103]
	v_mfma_f32_16x16x32_bf16 v[104:107], v[132:135], v[188:191], v[104:107]
	s_mov_b32 m0, s69
	v_mfma_f32_16x16x32_bf16 v[72:75], v[148:151], v[188:191], v[72:75]
	s_add_i32 s39, s12, 0x80
	v_mfma_f32_16x16x32_bf16 v[68:71], v[156:159], v[188:191], v[68:71]
	v_mfma_f32_16x16x32_bf16 v[76:79], v[156:159], v[180:183], v[76:79]
	v_mfma_f32_16x16x32_bf16 v[80:83], v[148:151], v[180:183], v[80:83]
	v_mfma_f32_16x16x32_bf16 v[88:91], v[148:151], v[172:175], v[88:91]
	v_mfma_f32_16x16x32_bf16 v[84:87], v[156:159], v[172:175], v[84:87]
	v_mfma_f32_16x16x32_bf16 v[92:95], v[156:159], v[164:167], v[92:95]
	v_mfma_f32_16x16x32_bf16 v[96:99], v[148:151], v[164:167], v[96:99]
	v_mfma_f32_16x16x32_bf16 v[128:131], v[136:139], v[168:171], v[128:131]
	v_mfma_f32_16x16x32_bf16 v[124:127], v[144:147], v[168:171], v[124:127]
	v_mfma_f32_16x16x32_bf16 v[116:119], v[144:147], v[176:179], v[116:119]
	v_mfma_f32_16x16x32_bf16 v[120:123], v[136:139], v[176:179], v[120:123]
	v_mfma_f32_16x16x32_bf16 v[112:115], v[136:139], v[184:187], v[112:115]
	v_mfma_f32_16x16x32_bf16 v[108:111], v[144:147], v[184:187], v[108:111]
	v_mfma_f32_16x16x32_bf16 v[100:103], v[144:147], v[192:195], v[100:103]
	v_mfma_f32_16x16x32_bf16 v[104:107], v[136:139], v[192:195], v[104:107]
	v_mfma_f32_16x16x32_bf16 v[72:75], v[152:155], v[192:195], v[72:75]
	v_mfma_f32_16x16x32_bf16 v[68:71], v[160:163], v[192:195], v[68:71]
	v_mfma_f32_16x16x32_bf16 v[76:79], v[160:163], v[184:187], v[76:79]
	v_mfma_f32_16x16x32_bf16 v[80:83], v[152:155], v[184:187], v[80:83]
	v_mfma_f32_16x16x32_bf16 v[88:91], v[152:155], v[176:179], v[88:91]
	v_mfma_f32_16x16x32_bf16 v[84:87], v[160:163], v[176:179], v[84:87]
	v_mfma_f32_16x16x32_bf16 v[92:95], v[160:163], v[168:171], v[92:95]
	v_mfma_f32_16x16x32_bf16 v[96:99], v[152:155], v[168:171], v[96:99]
	s_barrier
	s_setprio 0
	ds_read_b128 v[164:167], v237 offset:49152
	ds_read_b128 v[168:171], v237 offset:50176
	ds_read_b128 v[172:175], v237 offset:51200
	ds_read_b128 v[176:179], v237 offset:52224
	ds_read_b128 v[180:183], v237 offset:53248
	ds_read_b128 v[184:187], v237 offset:54272
	ds_read_b128 v[188:191], v237 offset:55296
	ds_read_b128 v[192:195], v237 offset:56320
	buffer_load_dwordx4 v221, s[44:47], s39 offen lds
	s_mov_b32 m0, s71
	s_add_i32 s12, s12, 0x40080
	buffer_load_dwordx4 v223, s[44:47], s39 offen lds
	s_mov_b32 m0, s74
	s_addk_i32 s13, 0x80
	buffer_load_dwordx4 v221, s[44:47], s12 offen lds
	s_mov_b32 m0, s75
	s_nop 0
	buffer_load_dwordx4 v223, s[44:47], s12 offen lds
	s_mov_b32 m0, s72
	s_nop 0
	buffer_load_dwordx4 v220, s[4:7], s13 offen lds
	s_waitcnt vmcnt(7)
	s_waitcnt lgkmcnt(0)
	s_setprio 1
	s_barrier
	v_mfma_f32_16x16x32_bf16 v[64:67], v[132:135], v[164:167], v[64:67]
	v_mfma_f32_16x16x32_bf16 v[60:63], v[140:143], v[164:167], v[60:63]
	v_mfma_f32_16x16x32_bf16 v[52:55], v[140:143], v[172:175], v[52:55]
	v_mfma_f32_16x16x32_bf16 v[56:59], v[132:135], v[172:175], v[56:59]
	v_mfma_f32_16x16x32_bf16 v[48:51], v[132:135], v[180:183], v[48:51]
	v_mfma_f32_16x16x32_bf16 v[44:47], v[140:143], v[180:183], v[44:47]
	v_mfma_f32_16x16x32_bf16 v[36:39], v[140:143], v[188:191], v[36:39]
	v_mfma_f32_16x16x32_bf16 v[40:43], v[132:135], v[188:191], v[40:43]
	s_add_i32 s38, s38, 2
	v_mfma_f32_16x16x32_bf16 v[64:67], v[136:139], v[168:171], v[64:67]
	s_add_u32 s19, s19, 0x100
	v_mfma_f32_16x16x32_bf16 v[60:63], v[144:147], v[168:171], v[60:63]
	s_addc_u32 s23, s23, 0
	v_mfma_f32_16x16x32_bf16 v[52:55], v[144:147], v[176:179], v[52:55]
	s_cmp_gt_u32 s38, 13
	v_mfma_f32_16x16x32_bf16 v[56:59], v[136:139], v[176:179], v[56:59]
	s_mov_b64 s[12:13], s[16:17]
	v_mfma_f32_16x16x32_bf16 v[48:51], v[136:139], v[184:187], v[48:51]
	v_mfma_f32_16x16x32_bf16 v[44:47], v[144:147], v[184:187], v[44:47]
	v_mfma_f32_16x16x32_bf16 v[36:39], v[144:147], v[192:195], v[36:39]
	v_mfma_f32_16x16x32_bf16 v[40:43], v[136:139], v[192:195], v[40:43]
	v_mfma_f32_16x16x32_bf16 v[32:35], v[148:151], v[164:167], v[32:35]
	v_mfma_f32_16x16x32_bf16 v[28:31], v[156:159], v[164:167], v[28:31]
	v_mfma_f32_16x16x32_bf16 v[20:23], v[156:159], v[172:175], v[20:23]
	v_mfma_f32_16x16x32_bf16 v[24:27], v[148:151], v[172:175], v[24:27]
	v_mfma_f32_16x16x32_bf16 v[16:19], v[148:151], v[180:183], v[16:19]
	v_mfma_f32_16x16x32_bf16 v[12:15], v[156:159], v[180:183], v[12:15]
	v_mfma_f32_16x16x32_bf16 v[2:5], v[156:159], v[188:191], v[2:5]
	v_mfma_f32_16x16x32_bf16 v[6:9], v[148:151], v[188:191], v[8:11]
	v_mfma_f32_16x16x32_bf16 v[32:35], v[152:155], v[168:171], v[32:35]
	v_mfma_f32_16x16x32_bf16 v[28:31], v[160:163], v[168:171], v[28:31]
	v_mfma_f32_16x16x32_bf16 v[20:23], v[160:163], v[176:179], v[20:23]
	v_mfma_f32_16x16x32_bf16 v[24:27], v[152:155], v[176:179], v[24:27]
	v_mfma_f32_16x16x32_bf16 v[16:19], v[152:155], v[184:187], v[16:19]
	v_mfma_f32_16x16x32_bf16 v[12:15], v[160:163], v[184:187], v[12:15]
	v_mfma_f32_16x16x32_bf16 v[8:11], v[152:155], v[192:195], v[6:9]
	v_mfma_f32_16x16x32_bf16 v[4:7], v[160:163], v[192:195], v[2:5]
	s_barrier
	s_setprio 0
	s_cbranch_scc0 .LBB0_1037
	s_and_b64 vcc, exec, s[14:15]
	s_cbranch_vccz .LBB0_1040
	s_barrier

; #define PG8_STAGE(bufoff, gbase, voff) do { const int so_ = (int)(unsigned)((const char*)(gbase) - base_##voff); _Pragma("unroll") for (int _i = 0; _i < 2; ++_i) \
;         __builtin_amdgcn_raw_ptr_buffer_load_lds(rs_##voff, (PG8_LAS unsigned*)(lds + (bufoff) + ldsw + _i * 8192), 16, (int)(voff)[_i], so_, 0, 0); } while (0)
; #define PG8_LDA(dst, b, h) do { _Pragma("unroll") for (int m = 0; m < 4; ++m) _Pragma("unroll") for (int k = 0; k < 2; ++k) dst[m][k] = *(const PG8_LAS bf16x8*)(lds + PG8_SA(b, h) + aoff + m * 2048 + k * 1024); } while (0)
; #define PG8_LDB(dst, b, h) do { _Pragma("unroll") for (int n = 0; n < 2; ++n) _Pragma("unroll") for (int k = 0; k < 2; ++k) dst[n][k] = *(const PG8_LAS bf16x8*)(lds + PG8_SB(b, h) + boff + n * 2048 + k * 1024); } while (0)
; #define PG8_MMA(ai, bj, At, Bt) do { __builtin_amdgcn_s_setprio(1); _Pragma("unroll") for (int m = 0; m < 4; ++m) _Pragma("unroll") for (int n = 0; n < 2; ++n) _Pragma("unroll") for (int k = 0; k < 2; ++k) \
;         acc[ai][bj][m][n] = __builtin_amdgcn_mfma_f32_16x16x32_bf16(Bt[n][k], At[m][k], acc[ai][bj][m][n], 0, 0, 0); __builtin_amdgcn_s_setprio(0); } while (0)
; #define PG8_WAIT_V(n) asm volatile("s_waitcnt vmcnt(" #n ")" ::: "memory")
; #define PG8_WAIT_L(n) asm volatile("s_waitcnt lgkmcnt(" #n ")" ::: "memory")
; #define PG8_BAR __builtin_amdgcn_s_barrier()
; #define PG8_SCHED __builtin_amdgcn_sched_barrier(0)
; template <class Epi, class Sched, bool ALIGN_EPI = false, bool SP2 = false>
; __device__ __forceinline__ void gemm_phase(PG8_LAS unsigned char* lds, const Gemm g, const Sched& S, const Epi& E, int tid_in) {
;     ...
;             PG8_LDB(B0, 0, 0); PG8_LDB(B1, 0, 1); PG8_SCHED; PG8_LDA(At, 0, 0); PG8_STAGE(PG8_SA(1, 1), a1 + hstepA, voffA);
;             PG8_WAIT_V(8); PG8_WAIT_L(0); PG8_BAR; PG8_MMA(0, 0, At, B0); PG8_MMA(0, 1, At, B1); PG8_BAR; PG8_SCHED;
;             PG8_LDA(At, 0, 1); PG8_STAGE(PG8_SB(0, 0), b2, voffB); PG8_STAGE(PG8_SB(0, 1), b2 + hstepB, voffB); PG8_STAGE(PG8_SA(0, 0), a2, voffA);
;             PG8_WAIT_V(8); PG8_WAIT_L(0); PG8_BAR; PG8_MMA(1, 0, At, B0); PG8_MMA(1, 1, At, B1); PG8_BAR; PG8_SCHED;
.LBB0_1265:
	v_add_u32_e32 v133, 0x10000, v131
	ds_read_b128 v[134:137], v133
	ds_read_b128 v[138:141], v133 offset:1024
	ds_read_b128 v[142:145], v133 offset:2048
	ds_read_b128 v[146:149], v133 offset:3072
	v_add_u32_e32 v133, 0x14000, v131
	ds_read_b128 v[150:153], v133
	ds_read_b128 v[154:157], v133 offset:1024
	ds_read_b128 v[158:161], v133 offset:2048
	ds_read_b128 v[166:169], v133 offset:3072
	s_add_i32 s42, s18, s44
	s_add_i32 s21, s14, s44
	s_add_i32 s79, s12, s44
	s_addk_i32 s42, 0xff80
	s_sub_i32 vcc_lo, s42, 0x80000
	s_cmp_eq_u32 s19, 28
	s_cselect_b32 s21, s15, s21
	s_mov_b32 m0, s75
	ds_read_b128 v[170:173], v132
	ds_read_b128 v[174:177], v132 offset:1024
	ds_read_b128 v[178:181], v132 offset:2048
	ds_read_b128 v[182:185], v132 offset:3072
	ds_read_b128 v[186:189], v132 offset:4096
	ds_read_b128 v[190:193], v132 offset:5120
	ds_read_b128 v[200:203], v132 offset:6144
	ds_read_b128 v[206:209], v132 offset:7168
	s_mov_b32 m0, s72
	s_nop 0
	buffer_load_dwordx4 v130, s[4:7], vcc_lo offen lds
	s_mov_b32 m0, s75
	s_nop 0
	buffer_load_dwordx4 v0, s[4:7], s42 offen lds
	s_mov_b32 m0, s76
	s_nop 0
	buffer_load_dwordx4 v130, s[4:7], s42 offen lds
	s_waitcnt vmcnt(8)
	s_waitcnt lgkmcnt(0)
	s_setprio 1
	s_barrier
	v_mfma_f32_16x16x32_bf16 v[34:37], v[134:137], v[170:173], v[34:37]
	v_mfma_f32_16x16x32_bf16 v[18:21], v[142:145], v[170:173], v[18:21]
	v_mfma_f32_16x16x32_bf16 v[78:81], v[142:145], v[178:181], v[78:81]
	v_mfma_f32_16x16x32_bf16 v[86:89], v[134:137], v[178:181], v[86:89]
	v_mfma_f32_16x16x32_bf16 v[106:109], v[134:137], v[186:189], v[106:109]
	v_mfma_f32_16x16x32_bf16 v[102:105], v[142:145], v[186:189], v[102:105]
	v_mfma_f32_16x16x32_bf16 v[122:125], v[142:145], v[200:203], v[122:125]
	v_mfma_f32_16x16x32_bf16 v[126:129], v[134:137], v[200:203], v[126:129]
	s_cselect_b32 s79, s17, s79
	v_mfma_f32_16x16x32_bf16 v[118:121], v[150:153], v[200:203], v[118:121]
	s_mov_b32 m0, s49
	v_mfma_f32_16x16x32_bf16 v[114:117], v[158:161], v[200:203], v[114:117]
	s_mov_b32 s42, s6
	v_mfma_f32_16x16x32_bf16 v[110:113], v[158:161], v[186:189], v[110:113]
	s_mov_b32 s43, s7
	v_mfma_f32_16x16x32_bf16 v[98:101], v[150:153], v[186:189], v[98:101]
	s_sub_i32 s79, s79, s40
	v_mfma_f32_16x16x32_bf16 v[74:77], v[150:153], v[178:181], v[74:77]
	v_mfma_f32_16x16x32_bf16 v[90:93], v[158:161], v[178:181], v[90:93]
	v_mfma_f32_16x16x32_bf16 v[38:41], v[158:161], v[170:173], v[38:41]
	v_mfma_f32_16x16x32_bf16 v[14:17], v[150:153], v[170:173], v[14:17]
	v_mfma_f32_16x16x32_bf16 v[34:37], v[138:141], v[174:177], v[34:37]
	v_mfma_f32_16x16x32_bf16 v[18:21], v[146:149], v[174:177], v[18:21]
	v_mfma_f32_16x16x32_bf16 v[78:81], v[146:149], v[182:185], v[78:81]
	v_mfma_f32_16x16x32_bf16 v[86:89], v[138:141], v[182:185], v[86:89]
	v_mfma_f32_16x16x32_bf16 v[106:109], v[138:141], v[190:193], v[106:109]
	v_mfma_f32_16x16x32_bf16 v[102:105], v[146:149], v[190:193], v[102:105]
	v_mfma_f32_16x16x32_bf16 v[122:125], v[146:149], v[206:209], v[122:125]
	v_mfma_f32_16x16x32_bf16 v[126:129], v[138:141], v[206:209], v[126:129]
	v_mfma_f32_16x16x32_bf16 v[118:121], v[154:157], v[206:209], v[118:121]
	v_mfma_f32_16x16x32_bf16 v[114:117], v[166:169], v[206:209], v[114:117]
	v_mfma_f32_16x16x32_bf16 v[110:113], v[166:169], v[190:193], v[110:113]
	v_mfma_f32_16x16x32_bf16 v[98:101], v[154:157], v[190:193], v[98:101]
	v_mfma_f32_16x16x32_bf16 v[74:77], v[154:157], v[182:185], v[74:77]
	v_mfma_f32_16x16x32_bf16 v[90:93], v[166:169], v[182:185], v[90:93]
	v_mfma_f32_16x16x32_bf16 v[38:41], v[166:169], v[174:177], v[38:41]
	v_mfma_f32_16x16x32_bf16 v[14:17], v[154:157], v[174:177], v[14:17]
	s_barrier
	s_setprio 0
	ds_read_b128 v[170:173], v132 offset:16384
	ds_read_b128 v[174:177], v132 offset:17408
	ds_read_b128 v[178:181], v132 offset:18432
	ds_read_b128 v[182:185], v132 offset:19456
	ds_read_b128 v[186:189], v132 offset:20480
	ds_read_b128 v[190:193], v132 offset:21504
	ds_read_b128 v[200:203], v132 offset:22528
	ds_read_b128 v[206:209], v132 offset:23552
	buffer_load_dwordx4 v0, s[40:43], s79 offen lds
	s_mov_b32 m0, s60
	s_add_i32 vcc_lo, s79, 0x80000
	buffer_load_dwordx4 v130, s[40:43], s79 offen lds
	s_mov_b32 m0, s61
	s_sub_i32 s21, s21, s4
	buffer_load_dwordx4 v0, s[40:43], vcc_lo offen lds
	s_mov_b32 m0, s62
	s_nop 0
	buffer_load_dwordx4 v130, s[40:43], vcc_lo offen lds
	s_mov_b32 m0, s35
	s_nop 0
	buffer_load_dwordx4 v0, s[4:7], s21 offen lds
	s_waitcnt vmcnt(7)
	s_waitcnt lgkmcnt(0)
	s_setprio 1
	s_barrier
	v_mfma_f32_16x16x32_bf16 v[50:53], v[134:137], v[170:173], v[50:53]
	v_mfma_f32_16x16x32_bf16 v[30:33], v[142:145], v[170:173], v[30:33]
	v_mfma_f32_16x16x32_bf16 v[58:61], v[142:145], v[178:181], v[58:61]
	v_mfma_f32_16x16x32_bf16 v[62:65], v[134:137], v[178:181], v[62:65]
	v_mfma_f32_16x16x32_bf16 v[94:97], v[134:137], v[186:189], v[94:97]
	v_mfma_f32_16x16x32_bf16 v[82:85], v[142:145], v[186:189], v[82:85]
	v_mfma_f32_16x16x32_bf16 v[26:29], v[142:145], v[200:203], v[26:29]
	v_mfma_f32_16x16x32_bf16 v[46:49], v[134:137], v[200:203], v[46:49]
	v_mfma_f32_16x16x32_bf16 v[6:9], v[150:153], v[200:203], v[6:9]
	v_mfma_f32_16x16x32_bf16 v[2:5], v[158:161], v[200:203], v[2:5]
	v_mfma_f32_16x16x32_bf16 v[42:45], v[158:161], v[186:189], v[42:45]
	v_mfma_f32_16x16x32_bf16 v[70:73], v[150:153], v[186:189], v[70:73]
	v_mfma_f32_16x16x32_bf16 v[54:57], v[150:153], v[178:181], v[54:57]
	v_mfma_f32_16x16x32_bf16 v[66:69], v[158:161], v[178:181], v[66:69]
	v_mfma_f32_16x16x32_bf16 v[10:13], v[158:161], v[170:173], v[10:13]
	v_mfma_f32_16x16x32_bf16 v[22:25], v[150:153], v[170:173], v[22:25]
	v_mfma_f32_16x16x32_bf16 v[50:53], v[138:141], v[174:177], v[50:53]
	v_mfma_f32_16x16x32_bf16 v[30:33], v[146:149], v[174:177], v[30:33]
	v_mfma_f32_16x16x32_bf16 v[58:61], v[146:149], v[182:185], v[58:61]
	v_mfma_f32_16x16x32_bf16 v[62:65], v[138:141], v[182:185], v[62:65]
	v_mfma_f32_16x16x32_bf16 v[94:97], v[138:141], v[190:193], v[94:97]
	v_mfma_f32_16x16x32_bf16 v[82:85], v[146:149], v[190:193], v[82:85]
	v_mfma_f32_16x16x32_bf16 v[26:29], v[146:149], v[206:209], v[26:29]
	v_mfma_f32_16x16x32_bf16 v[46:49], v[138:141], v[206:209], v[46:49]
	v_mfma_f32_16x16x32_bf16 v[6:9], v[154:157], v[206:209], v[6:9]
	v_mfma_f32_16x16x32_bf16 v[2:5], v[166:169], v[206:209], v[2:5]
	v_mfma_f32_16x16x32_bf16 v[42:45], v[166:169], v[190:193], v[42:45]
	v_mfma_f32_16x16x32_bf16 v[70:73], v[154:157], v[190:193], v[70:73]
	v_mfma_f32_16x16x32_bf16 v[54:57], v[154:157], v[182:185], v[54:57]
	v_mfma_f32_16x16x32_bf16 v[66:69], v[166:169], v[182:185], v[66:69]
	v_mfma_f32_16x16x32_bf16 v[10:13], v[166:169], v[174:177], v[10:13]
	v_mfma_f32_16x16x32_bf16 v[22:25], v[154:157], v[174:177], v[22:25]
	s_barrier
; #define PG8_STAGE(bufoff, gbase, voff) do { const int so_ = (int)(unsigned)((const char*)(gbase) - base_##voff); _Pragma("unroll") for (int _i = 0; _i < 2; ++_i) \
;         __builtin_amdgcn_raw_ptr_buffer_load_lds(rs_##voff, (PG8_LAS unsigned*)(lds + (bufoff) + ldsw + _i * 8192), 16, (int)(voff)[_i], so_, 0, 0); } while (0)
; #define PG8_LDA(dst, b, h) do { _Pragma("unroll") for (int m = 0; m < 4; ++m) _Pragma("unroll") for (int k = 0; k < 2; ++k) dst[m][k] = *(const PG8_LAS bf16x8*)(lds + PG8_SA(b, h) + aoff + m * 2048 + k * 1024); } while (0)
; #define PG8_LDB(dst, b, h) do { _Pragma("unroll") for (int n = 0; n < 2; ++n) _Pragma("unroll") for (int k = 0; k < 2; ++k) dst[n][k] = *(const PG8_LAS bf16x8*)(lds + PG8_SB(b, h) + boff + n * 2048 + k * 1024); } while (0)
; #define PG8_MMA(ai, bj, At, Bt) do { __builtin_amdgcn_s_setprio(1); _Pragma("unroll") for (int m = 0; m < 4; ++m) _Pragma("unroll") for (int n = 0; n < 2; ++n) _Pragma("unroll") for (int k = 0; k < 2; ++k) \
;         acc[ai][bj][m][n] = __builtin_amdgcn_mfma_f32_16x16x32_bf16(Bt[n][k], At[m][k], acc[ai][bj][m][n], 0, 0, 0); __builtin_amdgcn_s_setprio(0); } while (0)
; #define PG8_WAIT_V(n) asm volatile("s_waitcnt vmcnt(" #n ")" ::: "memory")
; #define PG8_WAIT_L(n) asm volatile("s_waitcnt lgkmcnt(" #n ")" ::: "memory")
; #define PG8_BAR __builtin_amdgcn_s_barrier()
; #define PG8_SCHED __builtin_amdgcn_sched_barrier(0)
; template <class Epi, class Sched, bool ALIGN_EPI = false, bool SP2 = false>
; __device__ __forceinline__ void gemm_phase(PG8_LAS unsigned char* lds, const Gemm g, const Sched& S, const Epi& E, int tid_in) {
;     ...
;             PG8_LDA(At, 0, 1); PG8_STAGE(PG8_SB(0, 0), b2, voffB); PG8_STAGE(PG8_SB(0, 1), b2 + hstepB, voffB); PG8_STAGE(PG8_SA(0, 0), a2, voffA);
;             PG8_WAIT_V(8); PG8_WAIT_L(0); PG8_BAR; PG8_MMA(1, 0, At, B0); PG8_MMA(1, 1, At, B1); PG8_BAR; PG8_SCHED;
;             PG8_LDB(B0, 1, 0); PG8_LDB(B1, 1, 1); PG8_SCHED; PG8_LDA(At, 1, 0); PG8_STAGE(PG8_SA(0, 1), a2 + hstepA, voffA);
;             PG8_WAIT_V(8); PG8_WAIT_L(0); PG8_BAR; PG8_MMA(0, 0, At, B0); PG8_MMA(0, 1, At, B1); PG8_BAR; PG8_SCHED;
	s_setprio 0
	v_add_u32_e32 v133, 0x18000, v131
	ds_read_b128 v[134:137], v133
	ds_read_b128 v[138:141], v133 offset:1024
	ds_read_b128 v[142:145], v133 offset:2048
	ds_read_b128 v[146:149], v133 offset:3072
	v_add_u32_e32 v133, 0x1c000, v131
	ds_read_b128 v[150:153], v133
	ds_read_b128 v[154:157], v133 offset:1024
	ds_read_b128 v[158:161], v133 offset:2048
	ds_read_b128 v[166:169], v133 offset:3072
	s_add_i32 vcc_lo, s21, 0x80000
	s_mov_b32 m0, s66
	ds_read_b128 v[170:173], v132 offset:32768
	ds_read_b128 v[174:177], v132 offset:33792
	ds_read_b128 v[178:181], v132 offset:34816
	ds_read_b128 v[182:185], v132 offset:35840
	ds_read_b128 v[186:189], v132 offset:36864
	ds_read_b128 v[190:193], v132 offset:37888
	ds_read_b128 v[200:203], v132 offset:38912
	ds_read_b128 v[206:209], v132 offset:39936
	s_mov_b32 m0, s63
	s_nop 0
	buffer_load_dwordx4 v130, s[4:7], s21 offen lds
	s_mov_b32 m0, s66
	s_nop 0
	buffer_load_dwordx4 v0, s[4:7], vcc_lo offen lds
	s_mov_b32 m0, s67
	s_nop 0
	buffer_load_dwordx4 v130, s[4:7], vcc_lo offen lds
	s_waitcnt vmcnt(8)
	s_waitcnt lgkmcnt(0)
	s_setprio 1
	s_barrier
	v_mfma_f32_16x16x32_bf16 v[34:37], v[134:137], v[170:173], v[34:37]
	v_mfma_f32_16x16x32_bf16 v[18:21], v[142:145], v[170:173], v[18:21]
	v_mfma_f32_16x16x32_bf16 v[78:81], v[142:145], v[178:181], v[78:81]
	v_mfma_f32_16x16x32_bf16 v[86:89], v[134:137], v[178:181], v[86:89]
	v_mfma_f32_16x16x32_bf16 v[106:109], v[134:137], v[186:189], v[106:109]
	v_mfma_f32_16x16x32_bf16 v[102:105], v[142:145], v[186:189], v[102:105]
	v_mfma_f32_16x16x32_bf16 v[122:125], v[142:145], v[200:203], v[122:125]
	v_mfma_f32_16x16x32_bf16 v[126:129], v[134:137], v[200:203], v[126:129]
	s_mov_b32 m0, s68
	v_mfma_f32_16x16x32_bf16 v[118:121], v[150:153], v[200:203], v[118:121]
	v_mfma_f32_16x16x32_bf16 v[114:117], v[158:161], v[200:203], v[114:117]
	v_mfma_f32_16x16x32_bf16 v[110:113], v[158:161], v[186:189], v[110:113]
	v_mfma_f32_16x16x32_bf16 v[98:101], v[150:153], v[186:189], v[98:101]
	v_mfma_f32_16x16x32_bf16 v[74:77], v[150:153], v[178:181], v[74:77]
	v_mfma_f32_16x16x32_bf16 v[90:93], v[158:161], v[178:181], v[90:93]
	v_mfma_f32_16x16x32_bf16 v[38:41], v[158:161], v[170:173], v[38:41]
	v_mfma_f32_16x16x32_bf16 v[14:17], v[150:153], v[170:173], v[14:17]
	v_mfma_f32_16x16x32_bf16 v[34:37], v[138:141], v[174:177], v[34:37]
	v_mfma_f32_16x16x32_bf16 v[18:21], v[146:149], v[174:177], v[18:21]
	v_mfma_f32_16x16x32_bf16 v[78:81], v[146:149], v[182:185], v[78:81]
	v_mfma_f32_16x16x32_bf16 v[86:89], v[138:141], v[182:185], v[86:89]
	v_mfma_f32_16x16x32_bf16 v[106:109], v[138:141], v[190:193], v[106:109]
	v_mfma_f32_16x16x32_bf16 v[102:105], v[146:149], v[190:193], v[102:105]
	v_mfma_f32_16x16x32_bf16 v[122:125], v[146:149], v[206:209], v[122:125]
	v_mfma_f32_16x16x32_bf16 v[126:129], v[138:141], v[206:209], v[126:129]
	v_mfma_f32_16x16x32_bf16 v[118:121], v[154:157], v[206:209], v[118:121]
	v_mfma_f32_16x16x32_bf16 v[114:117], v[166:169], v[206:209], v[114:117]
	v_mfma_f32_16x16x32_bf16 v[110:113], v[166:169], v[190:193], v[110:113]
	v_mfma_f32_16x16x32_bf16 v[98:101], v[154:157], v[190:193], v[98:101]
	v_mfma_f32_16x16x32_bf16 v[74:77], v[154:157], v[182:185], v[74:77]
	v_mfma_f32_16x16x32_bf16 v[90:93], v[166:169], v[182:185], v[90:93]
	v_mfma_f32_16x16x32_bf16 v[38:41], v[166:169], v[174:177], v[38:41]
	v_mfma_f32_16x16x32_bf16 v[14:17], v[154:157], v[174:177], v[14:17]
	s_barrier
	s_setprio 0
	s_add_i32 vcc_lo, s79, 0x80
	ds_read_b128 v[170:173], v132 offset:49152
	ds_read_b128 v[174:177], v132 offset:50176
	ds_read_b128 v[178:181], v132 offset:51200
	ds_read_b128 v[182:185], v132 offset:52224
	ds_read_b128 v[186:189], v132 offset:53248
	ds_read_b128 v[190:193], v132 offset:54272
	ds_read_b128 v[200:203], v132 offset:55296
	ds_read_b128 v[206:209], v132 offset:56320
	buffer_load_dwordx4 v0, s[40:43], vcc_lo offen lds
	s_mov_b32 m0, s69
	s_add_i32 s79, s79, 0x80080
	buffer_load_dwordx4 v130, s[40:43], vcc_lo offen lds
	s_mov_b32 m0, s73
	s_addk_i32 s21, 0x80
	buffer_load_dwordx4 v0, s[40:43], s79 offen lds
	s_mov_b32 m0, s74
	s_nop 0
	buffer_load_dwordx4 v130, s[40:43], s79 offen lds
	s_mov_b32 m0, s71
	s_nop 0
	buffer_load_dwordx4 v0, s[4:7], s21 offen lds
	s_waitcnt vmcnt(7)
	s_waitcnt lgkmcnt(0)
	s_setprio 1
	s_barrier
;     static __device__ __forceinline__ bool last_of_chain(const Unit& u) { return (u.pn >> 3) == 2; }
; #define PG8_STAGE(bufoff, gbase, voff) do { const int so_ = (int)(unsigned)((const char*)(gbase) - base_##voff); _Pragma("unroll") for (int _i = 0; _i < 2; ++_i) \
;         __builtin_amdgcn_raw_ptr_buffer_load_lds(rs_##voff, (PG8_LAS unsigned*)(lds + (bufoff) + ldsw + _i * 8192), 16, (int)(voff)[_i], so_, 0, 0); } while (0)
; #define PG8_LDA(dst, b, h) do { _Pragma("unroll") for (int m = 0; m < 4; ++m) _Pragma("unroll") for (int k = 0; k < 2; ++k) dst[m][k] = *(const PG8_LAS bf16x8*)(lds + PG8_SA(b, h) + aoff + m * 2048 + k * 1024); } while (0)
; #define PG8_MMA(ai, bj, At, Bt) do { __builtin_amdgcn_s_setprio(1); _Pragma("unroll") for (int m = 0; m < 4; ++m) _Pragma("unroll") for (int n = 0; n < 2; ++n) _Pragma("unroll") for (int k = 0; k < 2; ++k) \
;         acc[ai][bj][m][n] = __builtin_amdgcn_mfma_f32_16x16x32_bf16(Bt[n][k], At[m][k], acc[ai][bj][m][n], 0, 0, 0); __builtin_amdgcn_s_setprio(0); } while (0)
; #define PG8_WAIT_V(n) asm volatile("s_waitcnt vmcnt(" #n ")" ::: "memory")
; #define PG8_WAIT_L(n) asm volatile("s_waitcnt lgkmcnt(" #n ")" ::: "memory")
; #define PG8_BAR __builtin_amdgcn_s_barrier()
; #define PG8_SCHED __builtin_amdgcn_sched_barrier(0)
; template <class Epi, class Sched, bool ALIGN_EPI = false, bool SP2 = false>
; __device__ __forceinline__ void gemm_phase(PG8_LAS unsigned char* lds, const Gemm g, const Sched& S, const Epi& E, int tid_in) {
;     ...
;             PG8_WAIT_V(8); PG8_WAIT_L(0); PG8_BAR; PG8_MMA(0, 0, At, B0); PG8_MMA(0, 1, At, B1); PG8_BAR; PG8_SCHED;
;             PG8_LDA(At, 1, 1); PG8_STAGE(PG8_SB(1, 0), b3, voffB); PG8_STAGE(PG8_SB(1, 1), b3 + hstepB, voffB); PG8_STAGE(PG8_SA(1, 0), a3, voffA);
;             PG8_WAIT_V(8); PG8_WAIT_L(0); PG8_BAR; PG8_MMA(1, 0, At, B0); PG8_MMA(1, 1, At, B1); PG8_BAR; PG8_SCHED;
;     ...
;         bool zero_acc = true; if constexpr (Epi::CHAIN) zero_acc = Epi::last_of_chain(cur);
;         if (zero_acc) {
; #pragma unroll
;         for (int a = 0; a < 2; ++a)
; #pragma unroll
;             for (int b = 0; b < 2; ++b)
; #pragma unroll
;                 for (int m = 0; m < 4; ++m)
; #pragma unroll
;                     for (int n = 0; n < 2; ++n) acc[a][b][m][n] = (f32x4){0.f, 0.f, 0.f, 0.f};
;         }
	v_mfma_f32_16x16x32_bf16 v[50:53], v[134:137], v[170:173], v[50:53]
	v_mfma_f32_16x16x32_bf16 v[30:33], v[142:145], v[170:173], v[30:33]
	v_mfma_f32_16x16x32_bf16 v[58:61], v[142:145], v[178:181], v[58:61]
	v_mfma_f32_16x16x32_bf16 v[62:65], v[134:137], v[178:181], v[62:65]
	v_mfma_f32_16x16x32_bf16 v[94:97], v[134:137], v[186:189], v[94:97]
	v_mfma_f32_16x16x32_bf16 v[82:85], v[142:145], v[186:189], v[82:85]
	v_mfma_f32_16x16x32_bf16 v[26:29], v[142:145], v[200:203], v[26:29]
	v_mfma_f32_16x16x32_bf16 v[46:49], v[134:137], v[200:203], v[46:49]
	s_add_i32 s19, s19, 2
	v_mfma_f32_16x16x32_bf16 v[6:9], v[150:153], v[200:203], v[6:9]
	s_add_u32 s44, s44, 0x100
	v_mfma_f32_16x16x32_bf16 v[2:5], v[158:161], v[200:203], v[2:5]
	s_addc_u32 s45, s45, 0
	v_mfma_f32_16x16x32_bf16 v[42:45], v[158:161], v[186:189], v[42:45]
	s_cmp_gt_u32 s19, 29
	v_mfma_f32_16x16x32_bf16 v[70:73], v[150:153], v[186:189], v[70:73]
	v_mfma_f32_16x16x32_bf16 v[54:57], v[150:153], v[178:181], v[54:57]
	v_mfma_f32_16x16x32_bf16 v[66:69], v[158:161], v[178:181], v[66:69]
	v_mfma_f32_16x16x32_bf16 v[10:13], v[158:161], v[170:173], v[10:13]
	v_mfma_f32_16x16x32_bf16 v[22:25], v[150:153], v[170:173], v[22:25]
	v_mfma_f32_16x16x32_bf16 v[50:53], v[138:141], v[174:177], v[50:53]
	v_mfma_f32_16x16x32_bf16 v[30:33], v[146:149], v[174:177], v[30:33]
	v_mfma_f32_16x16x32_bf16 v[58:61], v[146:149], v[182:185], v[58:61]
	v_mfma_f32_16x16x32_bf16 v[62:65], v[138:141], v[182:185], v[62:65]
	v_mfma_f32_16x16x32_bf16 v[94:97], v[138:141], v[190:193], v[94:97]
	v_mfma_f32_16x16x32_bf16 v[82:85], v[146:149], v[190:193], v[82:85]
	v_mfma_f32_16x16x32_bf16 v[26:29], v[146:149], v[206:209], v[26:29]
	v_mfma_f32_16x16x32_bf16 v[46:49], v[138:141], v[206:209], v[46:49]
	v_mfma_f32_16x16x32_bf16 v[6:9], v[154:157], v[206:209], v[6:9]
	v_mfma_f32_16x16x32_bf16 v[2:5], v[166:169], v[206:209], v[2:5]
	v_mfma_f32_16x16x32_bf16 v[42:45], v[166:169], v[190:193], v[42:45]
	v_mfma_f32_16x16x32_bf16 v[70:73], v[154:157], v[190:193], v[70:73]
	v_mfma_f32_16x16x32_bf16 v[54:57], v[154:157], v[182:185], v[54:57]
	v_mfma_f32_16x16x32_bf16 v[66:69], v[166:169], v[182:185], v[66:69]
	v_mfma_f32_16x16x32_bf16 v[10:13], v[166:169], v[174:177], v[10:13]
	v_mfma_f32_16x16x32_bf16 v[22:25], v[154:157], v[174:177], v[22:25]
	s_barrier
	s_setprio 0
	s_cbranch_scc0 .LBB0_1265
	s_andn2_b64 vcc, exec, s[38:39]
	s_cbranch_vccnz .LBB0_1257
	v_mov_b32_e32 v2, 0
	s_mov_b64 s[12:13], s[24:25]
	s_mov_b32 s10, s16
	s_mov_b32 s48, s20
	s_mov_b64 s[14:15], s[22:23]
	s_mov_b32 s13, s78
	v_mov_b32_e32 v3, v2
	v_mov_b32_e32 v4, v2
	v_mov_b32_e32 v5, v2
	v_mov_b32_e32 v6, v2
	v_mov_b32_e32 v7, v2
	v_mov_b32_e32 v8, v2
	v_mov_b32_e32 v9, v2
	v_mov_b32_e32 v42, v2
	v_mov_b32_e32 v43, v2
	v_mov_b32_e32 v44, v2
	v_mov_b32_e32 v45, v2
	v_mov_b32_e32 v70, v2
	v_mov_b32_e32 v71, v2
	v_mov_b32_e32 v72, v2
	v_mov_b32_e32 v73, v2
	v_mov_b32_e32 v66, v2
	v_mov_b32_e32 v67, v2
	v_mov_b32_e32 v68, v2
	v_mov_b32_e32 v69, v2
	v_mov_b32_e32 v54, v2
	v_mov_b32_e32 v55, v2
	v_mov_b32_e32 v56, v2
	v_mov_b32_e32 v57, v2
	v_mov_b32_e32 v10, v2
	v_mov_b32_e32 v11, v2
	v_mov_b32_e32 v12, v2
	v_mov_b32_e32 v13, v2
	v_mov_b32_e32 v22, v2
	v_mov_b32_e32 v23, v2
	v_mov_b32_e32 v24, v2
	v_mov_b32_e32 v25, v2
	v_mov_b32_e32 v26, v2
	v_mov_b32_e32 v27, v2
	v_mov_b32_e32 v28, v2
	v_mov_b32_e32 v29, v2
	v_mov_b32_e32 v46, v2
	v_mov_b32_e32 v47, v2
	v_mov_b32_e32 v48, v2
	v_mov_b32_e32 v49, v2
	v_mov_b32_e32 v82, v2
	v_mov_b32_e32 v83, v2
	v_mov_b32_e32 v84, v2
	v_mov_b32_e32 v85, v2
	v_mov_b32_e32 v94, v2
	v_mov_b32_e32 v95, v2
	v_mov_b32_e32 v96, v2
	v_mov_b32_e32 v97, v2
	v_mov_b32_e32 v58, v2
	v_mov_b32_e32 v59, v2
	v_mov_b32_e32 v60, v2
	v_mov_b32_e32 v61, v2
	v_mov_b32_e32 v62, v2
	v_mov_b32_e32 v63, v2
	v_mov_b32_e32 v64, v2
	v_mov_b32_e32 v65, v2
	v_mov_b32_e32 v30, v2
	v_mov_b32_e32 v31, v2
	v_mov_b32_e32 v32, v2
	v_mov_b32_e32 v33, v2
	v_mov_b32_e32 v50, v2
	v_mov_b32_e32 v51, v2
	v_mov_b32_e32 v52, v2
	v_mov_b32_e32 v53, v2
	v_mov_b32_e32 v114, v2
	v_mov_b32_e32 v115, v2
	v_mov_b32_e32 v116, v2
	v_mov_b32_e32 v117, v2
	v_mov_b32_e32 v118, v2
	v_mov_b32_e32 v119, v2
	v_mov_b32_e32 v120, v2
	v_mov_b32_e32 v121, v2
	v_mov_b32_e32 v110, v2
	v_mov_b32_e32 v111, v2
	v_mov_b32_e32 v112, v2
	v_mov_b32_e32 v113, v2
	v_mov_b32_e32 v98, v2
	v_mov_b32_e32 v99, v2
	v_mov_b32_e32 v100, v2
	v_mov_b32_e32 v101, v2
	v_mov_b32_e32 v90, v2
	v_mov_b32_e32 v91, v2
	v_mov_b32_e32 v92, v2
	v_mov_b32_e32 v93, v2
	v_mov_b32_e32 v74, v2
	v_mov_b32_e32 v75, v2
	v_mov_b32_e32 v76, v2
	v_mov_b32_e32 v77, v2
	v_mov_b32_e32 v38, v2
	v_mov_b32_e32 v39, v2
	v_mov_b32_e32 v40, v2
	v_mov_b32_e32 v41, v2
	v_mov_b32_e32 v14, v2
	v_mov_b32_e32 v15, v2
	v_mov_b32_e32 v16, v2
	v_mov_b32_e32 v17, v2
	v_mov_b32_e32 v122, v2
	v_mov_b32_e32 v123, v2
	v_mov_b32_e32 v124, v2
	v_mov_b32_e32 v125, v2
	v_mov_b32_e32 v126, v2
	v_mov_b32_e32 v127, v2
	v_mov_b32_e32 v128, v2
	v_mov_b32_e32 v129, v2
	v_mov_b32_e32 v102, v2
	v_mov_b32_e32 v103, v2
	v_mov_b32_e32 v104, v2
	v_mov_b32_e32 v105, v2
	v_mov_b32_e32 v106, v2
	v_mov_b32_e32 v107, v2
	v_mov_b32_e32 v108, v2
	v_mov_b32_e32 v109, v2
	v_mov_b32_e32 v78, v2
	v_mov_b32_e32 v79, v2
	v_mov_b32_e32 v80, v2
	v_mov_b32_e32 v81, v2
	v_mov_b32_e32 v86, v2
	v_mov_b32_e32 v87, v2
	v_mov_b32_e32 v88, v2
	v_mov_b32_e32 v89, v2
	v_mov_b32_e32 v18, v2
	v_mov_b32_e32 v19, v2
	v_mov_b32_e32 v20, v2
	v_mov_b32_e32 v21, v2
	v_mov_b32_e32 v34, v2
	v_mov_b32_e32 v35, v2
	v_mov_b32_e32 v36, v2
	v_mov_b32_e32 v37, v2
	s_branch .LBB0_1257

;     __host__ __device__ bool next(int i, Unit& u) const { const int t = i / 3, b = i - 3 * t; Unit v; if (!StaticOrder::next(t, v)) return false; u.pm = v.pm; u.pn = 8 * b + v.pn; return true; }
; #define PG8_STAGE(bufoff, gbase, voff) do { const int so_ = (int)(unsigned)((const char*)(gbase) - base_##voff); _Pragma("unroll") for (int _i = 0; _i < 2; ++_i) \
;         __builtin_amdgcn_raw_ptr_buffer_load_lds(rs_##voff, (PG8_LAS unsigned*)(lds + (bufoff) + ldsw + _i * 8192), 16, (int)(voff)[_i], so_, 0, 0); } while (0)
; #define PG8_LDA(dst, b, h) do { _Pragma("unroll") for (int m = 0; m < 4; ++m) _Pragma("unroll") for (int k = 0; k < 2; ++k) dst[m][k] = *(const PG8_LAS bf16x8*)(lds + PG8_SA(b, h) + aoff + m * 2048 + k * 1024); } while (0)
; #define PG8_WAIT_V(n) asm volatile("s_waitcnt vmcnt(" #n ")" ::: "memory")
; #define PG8_WAIT_L(n) asm volatile("s_waitcnt lgkmcnt(" #n ")" ::: "memory")
; #define PG8_BAR __builtin_amdgcn_s_barrier()
; template <class Epi, class Sched, bool ALIGN_EPI = false, bool SP2 = false>
; __device__ __forceinline__ void gemm_phase(PG8_LAS unsigned char* lds, const Gemm g, const Sched& S, const Epi& E, int tid_in) {
;     ...
;         const bool has_next = S.next(ui + 1, nxt);
;         const char* nA = has_next ? (const char*)g.A + (size_t)nxt.pm * tstepA + (g.grp ? (size_t)(nxt.pn / g.grp) * g.agrp : (size_t)0) : cA; const char* nB = has_next ? (const char*)g.Bt + (size_t)nxt.pn * tstepB : cB;
;         for (int t = 0; t < nt; t += 2) {
;             const bool last = (t == nt - 2);
;             const char* a1 = cA + (size_t)(t + 1) * kstep;
;             const char* a2 = last ? nA : cA + (size_t)(t + 2) * kstep; const char* b2 = last ? nB : cB + (size_t)(t + 2) * kstep;
;             const char* a3 = a2 + kstep; const char* b3 = b2 + kstep;
;             if (last && has_next) S.a_ready(nxt);
;             if constexpr (SP2) {
;             PG8_LDB(B0, 0, 0); PG8_LDB(B1, 0, 1); PG8_SCHED; PG8_LDA(At, 0, 0); PG8_STAGE(PG8_SA(1, 1), a1 + hstepA, voffA);
;             PG8_WAIT_V(8); PG8_WAIT_L(0); PG8_BAR; PG8_MMA(0, 0, At, B0); PG8_MMA(0, 1, At, B1); PG8_BAR; PG8_SCHED;
;             PG8_LDA(At, 0, 1); PG8_STAGE(PG8_SB(0, 0), b2, voffB); PG8_STAGE(PG8_SB(0, 1), b2 + hstepB, voffB); PG8_STAGE(PG8_SA(0, 0), a2, voffA);
;             PG8_WAIT_V(8); PG8_WAIT_L(0); PG8_BAR; PG8_MMA(1, 0, At, B0); PG8_MMA(1, 1, At, B1); PG8_BAR; PG8_SCHED;
.LBB0_1513:
	s_ashr_i32 s21, s20, 31
	s_lshl_b64 s[18:19], s[20:21], 20
	s_add_u32 s22, s4, s18
	s_addc_u32 s23, s9, s19
	s_and_b64 s[18:19], s[36:37], exec
	s_cselect_b32 s18, s22, s16
	s_ashr_i32 s15, s14, 31
	s_lshl_b64 s[24:25], s[14:15], 20
	s_add_u32 s24, s40, s24
	s_addc_u32 s25, s26, s25
	s_and_b64 s[42:43], s[36:37], exec
	s_cselect_b32 s15, s24, s38
	s_add_u32 s19, s38, 0x100
	v_mov_b32_e32 v2, 0
	s_addc_u32 s21, s39, 0
	s_mov_b32 s73, -2
	v_add_u32_e32 v141, 0x10000, v139
	ds_read_b128 v[130:133], v141
	ds_read_b128 v[142:145], v141 offset:1024
	ds_read_b128 v[146:149], v141 offset:2048
	ds_read_b128 v[150:153], v141 offset:3072
	v_add_u32_e32 v141, 0x14000, v139
	ds_read_b128 v[154:157], v141
	ds_read_b128 v[158:161], v141 offset:1024
	ds_read_b128 v[162:165], v141 offset:2048
	ds_read_b128 v[166:169], v141 offset:3072
	s_add_u32 s38, s16, 0x100
	s_addc_u32 s39, s17, 0
	s_sub_i32 s16, s16, s4
	s_add_i32 s16, s16, 0x80080
	s_sub_i32 s74, s16, 0x80000
	s_cmp_eq_u32 s73, 28
	s_cselect_b32 s17, s18, s38
	s_mov_b32 m0, s67
	ds_read_b128 v[170:173], v140
	ds_read_b128 v[174:177], v140 offset:1024
	ds_read_b128 v[178:181], v140 offset:2048
	ds_read_b128 v[182:185], v140 offset:3072
	ds_read_b128 v[186:189], v140 offset:4096
	ds_read_b128 v[190:193], v140 offset:5120
	ds_read_b128 v[200:203], v140 offset:6144
	ds_read_b128 v[206:209], v140 offset:7168
	s_mov_b32 m0, s62
	s_nop 0
	buffer_load_dwordx4 v135, s[4:7], s74 offen lds
	s_mov_b32 m0, s67
	s_nop 0
	buffer_load_dwordx4 v0, s[4:7], s16 offen lds
	s_mov_b32 m0, s68
	s_nop 0
	buffer_load_dwordx4 v135, s[4:7], s16 offen lds
	s_waitcnt vmcnt(8)
	s_waitcnt lgkmcnt(0)
	s_setprio 1
	s_barrier
	v_mfma_f32_16x16x32_bf16 v[126:129], v[130:133], v[170:173], 0
	v_mfma_f32_16x16x32_bf16 v[122:125], v[146:149], v[170:173], 0
	v_mfma_f32_16x16x32_bf16 v[106:109], v[146:149], v[178:181], 0
	v_mfma_f32_16x16x32_bf16 v[110:113], v[130:133], v[178:181], 0
	v_mfma_f32_16x16x32_bf16 v[94:97], v[130:133], v[186:189], 0
	v_mfma_f32_16x16x32_bf16 v[90:93], v[146:149], v[186:189], 0
	v_mfma_f32_16x16x32_bf16 v[74:77], v[146:149], v[200:203], 0
	v_mfma_f32_16x16x32_bf16 v[78:81], v[130:133], v[200:203], 0
	s_cselect_b32 s16, s15, s19
	v_mfma_f32_16x16x32_bf16 v[126:129], v[142:145], v[174:177], v[126:129]
	s_mov_b32 m0, s35
	v_mfma_f32_16x16x32_bf16 v[122:125], v[150:153], v[174:177], v[122:125]
	s_mov_b32 s42, s6
	v_mfma_f32_16x16x32_bf16 v[106:109], v[150:153], v[182:185], v[106:109]
	s_mov_b32 s43, s7
	v_mfma_f32_16x16x32_bf16 v[110:113], v[142:145], v[182:185], v[110:113]
	s_sub_i32 s16, s16, s40
	v_mfma_f32_16x16x32_bf16 v[94:97], v[142:145], v[190:193], v[94:97]
	v_mfma_f32_16x16x32_bf16 v[90:93], v[150:153], v[190:193], v[90:93]
	v_mfma_f32_16x16x32_bf16 v[74:77], v[150:153], v[206:209], v[74:77]
	v_mfma_f32_16x16x32_bf16 v[78:81], v[142:145], v[206:209], v[78:81]
	v_mfma_f32_16x16x32_bf16 v[118:121], v[154:157], v[170:173], 0
	v_mfma_f32_16x16x32_bf16 v[114:117], v[162:165], v[170:173], 0
	v_mfma_f32_16x16x32_bf16 v[98:101], v[162:165], v[178:181], 0
	v_mfma_f32_16x16x32_bf16 v[102:105], v[154:157], v[178:181], 0
	v_mfma_f32_16x16x32_bf16 v[86:89], v[154:157], v[186:189], 0
	v_mfma_f32_16x16x32_bf16 v[82:85], v[162:165], v[186:189], 0
	v_mfma_f32_16x16x32_bf16 v[66:69], v[162:165], v[200:203], 0
	v_mfma_f32_16x16x32_bf16 v[70:73], v[154:157], v[200:203], 0
	v_mfma_f32_16x16x32_bf16 v[118:121], v[158:161], v[174:177], v[118:121]
	v_mfma_f32_16x16x32_bf16 v[114:117], v[166:169], v[174:177], v[114:117]
	v_mfma_f32_16x16x32_bf16 v[98:101], v[166:169], v[182:185], v[98:101]
	v_mfma_f32_16x16x32_bf16 v[102:105], v[158:161], v[182:185], v[102:105]
	v_mfma_f32_16x16x32_bf16 v[86:89], v[158:161], v[190:193], v[86:89]
	v_mfma_f32_16x16x32_bf16 v[82:85], v[166:169], v[190:193], v[82:85]
	v_mfma_f32_16x16x32_bf16 v[66:69], v[166:169], v[206:209], v[66:69]
	v_mfma_f32_16x16x32_bf16 v[70:73], v[158:161], v[206:209], v[70:73]
	s_barrier
	s_setprio 0
	ds_read_b128 v[170:173], v140 offset:16384
	ds_read_b128 v[174:177], v140 offset:17408
	ds_read_b128 v[178:181], v140 offset:18432
	ds_read_b128 v[182:185], v140 offset:19456
	ds_read_b128 v[186:189], v140 offset:20480
	ds_read_b128 v[190:193], v140 offset:21504
	ds_read_b128 v[200:203], v140 offset:22528
	ds_read_b128 v[206:209], v140 offset:23552
	buffer_load_dwordx4 v134, s[40:43], s16 offen lds
	s_mov_b32 m0, s44
	s_add_i32 s74, s16, 0x80000
	buffer_load_dwordx4 v136, s[40:43], s16 offen lds
	s_mov_b32 m0, s45
	s_sub_i32 s17, s17, s4
	buffer_load_dwordx4 v134, s[40:43], s74 offen lds
	s_mov_b32 m0, s46
	s_nop 0
	buffer_load_dwordx4 v136, s[40:43], s74 offen lds
	s_mov_b32 m0, s34
	s_nop 0
	buffer_load_dwordx4 v0, s[4:7], s17 offen lds
	s_waitcnt vmcnt(7)
	s_waitcnt lgkmcnt(0)
	s_setprio 1
	s_barrier
; #define PG8_STAGE(bufoff, gbase, voff) do { const int so_ = (int)(unsigned)((const char*)(gbase) - base_##voff); _Pragma("unroll") for (int _i = 0; _i < 2; ++_i) \
;         __builtin_amdgcn_raw_ptr_buffer_load_lds(rs_##voff, (PG8_LAS unsigned*)(lds + (bufoff) + ldsw + _i * 8192), 16, (int)(voff)[_i], so_, 0, 0); } while (0)
; #define PG8_LDA(dst, b, h) do { _Pragma("unroll") for (int m = 0; m < 4; ++m) _Pragma("unroll") for (int k = 0; k < 2; ++k) dst[m][k] = *(const PG8_LAS bf16x8*)(lds + PG8_SA(b, h) + aoff + m * 2048 + k * 1024); } while (0)
; #define PG8_LDB(dst, b, h) do { _Pragma("unroll") for (int n = 0; n < 2; ++n) _Pragma("unroll") for (int k = 0; k < 2; ++k) dst[n][k] = *(const PG8_LAS bf16x8*)(lds + PG8_SB(b, h) + boff + n * 2048 + k * 1024); } while (0)
; #define PG8_MMA(ai, bj, At, Bt) do { __builtin_amdgcn_s_setprio(1); _Pragma("unroll") for (int m = 0; m < 4; ++m) _Pragma("unroll") for (int n = 0; n < 2; ++n) _Pragma("unroll") for (int k = 0; k < 2; ++k) \
;         acc[ai][bj][m][n] = __builtin_amdgcn_mfma_f32_16x16x32_bf16(Bt[n][k], At[m][k], acc[ai][bj][m][n], 0, 0, 0); __builtin_amdgcn_s_setprio(0); } while (0)
; #define PG8_WAIT_V(n) asm volatile("s_waitcnt vmcnt(" #n ")" ::: "memory")
; #define PG8_WAIT_L(n) asm volatile("s_waitcnt lgkmcnt(" #n ")" ::: "memory")
; #define PG8_BAR __builtin_amdgcn_s_barrier()
; #define PG8_SCHED __builtin_amdgcn_sched_barrier(0)
; template <class Epi, class Sched, bool ALIGN_EPI = false, bool SP2 = false>
; __device__ __forceinline__ void gemm_phase(PG8_LAS unsigned char* lds, const Gemm g, const Sched& S, const Epi& E, int tid_in) {
;     ...
;             PG8_LDA(At, 0, 1); PG8_STAGE(PG8_SB(0, 0), b2, voffB); PG8_STAGE(PG8_SB(0, 1), b2 + hstepB, voffB); PG8_STAGE(PG8_SA(0, 0), a2, voffA);
;             PG8_WAIT_V(8); PG8_WAIT_L(0); PG8_BAR; PG8_MMA(1, 0, At, B0); PG8_MMA(1, 1, At, B1); PG8_BAR; PG8_SCHED;
;             PG8_LDB(B0, 1, 0); PG8_LDB(B1, 1, 1); PG8_SCHED; PG8_LDA(At, 1, 0); PG8_STAGE(PG8_SA(0, 1), a2 + hstepA, voffA);
;             PG8_WAIT_V(8); PG8_WAIT_L(0); PG8_BAR; PG8_MMA(0, 0, At, B0); PG8_MMA(0, 1, At, B1); PG8_BAR; PG8_SCHED;
	v_mfma_f32_16x16x32_bf16 v[62:65], v[130:133], v[170:173], 0
	v_mfma_f32_16x16x32_bf16 v[58:61], v[146:149], v[170:173], 0
	v_mfma_f32_16x16x32_bf16 v[42:45], v[146:149], v[178:181], 0
	v_mfma_f32_16x16x32_bf16 v[46:49], v[130:133], v[178:181], 0
	v_mfma_f32_16x16x32_bf16 v[30:33], v[130:133], v[186:189], 0
	v_mfma_f32_16x16x32_bf16 v[26:29], v[146:149], v[186:189], 0
	v_mfma_f32_16x16x32_bf16 v[10:13], v[146:149], v[200:203], 0
	v_mfma_f32_16x16x32_bf16 v[14:17], v[130:133], v[200:203], 0
	v_mfma_f32_16x16x32_bf16 v[62:65], v[142:145], v[174:177], v[62:65]
	v_mfma_f32_16x16x32_bf16 v[58:61], v[150:153], v[174:177], v[58:61]
	v_mfma_f32_16x16x32_bf16 v[42:45], v[150:153], v[182:185], v[42:45]
	v_mfma_f32_16x16x32_bf16 v[46:49], v[142:145], v[182:185], v[46:49]
	v_mfma_f32_16x16x32_bf16 v[30:33], v[142:145], v[190:193], v[30:33]
	v_mfma_f32_16x16x32_bf16 v[26:29], v[150:153], v[190:193], v[26:29]
	v_mfma_f32_16x16x32_bf16 v[10:13], v[150:153], v[206:209], v[10:13]
	v_mfma_f32_16x16x32_bf16 v[14:17], v[142:145], v[206:209], v[14:17]
	v_mfma_f32_16x16x32_bf16 v[54:57], v[154:157], v[170:173], 0
	v_mfma_f32_16x16x32_bf16 v[50:53], v[162:165], v[170:173], 0
	v_mfma_f32_16x16x32_bf16 v[34:37], v[162:165], v[178:181], 0
	v_mfma_f32_16x16x32_bf16 v[38:41], v[154:157], v[178:181], 0
	v_mfma_f32_16x16x32_bf16 v[22:25], v[154:157], v[186:189], 0
	v_mfma_f32_16x16x32_bf16 v[18:21], v[162:165], v[186:189], 0
	v_mfma_f32_16x16x32_bf16 v[2:5], v[162:165], v[200:203], 0
	v_mfma_f32_16x16x32_bf16 v[6:9], v[154:157], v[200:203], 0
	v_mfma_f32_16x16x32_bf16 v[54:57], v[158:161], v[174:177], v[54:57]
	v_mfma_f32_16x16x32_bf16 v[50:53], v[166:169], v[174:177], v[50:53]
	v_mfma_f32_16x16x32_bf16 v[34:37], v[166:169], v[182:185], v[34:37]
	v_mfma_f32_16x16x32_bf16 v[38:41], v[158:161], v[182:185], v[38:41]
	v_mfma_f32_16x16x32_bf16 v[22:25], v[158:161], v[190:193], v[22:25]
	v_mfma_f32_16x16x32_bf16 v[18:21], v[166:169], v[190:193], v[18:21]
	v_mfma_f32_16x16x32_bf16 v[2:5], v[166:169], v[206:209], v[2:5]
	v_mfma_f32_16x16x32_bf16 v[6:9], v[158:161], v[206:209], v[6:9]
	s_barrier
	s_setprio 0
	v_add_u32_e32 v141, 0x18000, v139
	ds_read_b128 v[130:133], v141
	ds_read_b128 v[142:145], v141 offset:1024
	ds_read_b128 v[146:149], v141 offset:2048
	ds_read_b128 v[150:153], v141 offset:3072
	v_add_u32_e32 v141, 0x1c000, v139
	ds_read_b128 v[154:157], v141
	ds_read_b128 v[158:161], v141 offset:1024
	ds_read_b128 v[162:165], v141 offset:2048
	ds_read_b128 v[166:169], v141 offset:3072
	s_add_i32 s74, s17, 0x80000
	s_mov_b32 m0, s48
	ds_read_b128 v[170:173], v140 offset:32768
	ds_read_b128 v[174:177], v140 offset:33792
	ds_read_b128 v[178:181], v140 offset:34816
	ds_read_b128 v[182:185], v140 offset:35840
	ds_read_b128 v[186:189], v140 offset:36864
	ds_read_b128 v[190:193], v140 offset:37888
	ds_read_b128 v[200:203], v140 offset:38912
	ds_read_b128 v[206:209], v140 offset:39936
	s_mov_b32 m0, s47
	s_nop 0
	buffer_load_dwordx4 v135, s[4:7], s17 offen lds
	s_mov_b32 m0, s48
	s_nop 0
	buffer_load_dwordx4 v0, s[4:7], s74 offen lds
	s_mov_b32 m0, s49
	s_nop 0
	buffer_load_dwordx4 v135, s[4:7], s74 offen lds
	s_waitcnt vmcnt(8)
	s_waitcnt lgkmcnt(0)
	s_setprio 1
	s_barrier
	v_mfma_f32_16x16x32_bf16 v[126:129], v[130:133], v[170:173], v[126:129]
	v_mfma_f32_16x16x32_bf16 v[122:125], v[146:149], v[170:173], v[122:125]
	v_mfma_f32_16x16x32_bf16 v[106:109], v[146:149], v[178:181], v[106:109]
	v_mfma_f32_16x16x32_bf16 v[110:113], v[130:133], v[178:181], v[110:113]
	v_mfma_f32_16x16x32_bf16 v[94:97], v[130:133], v[186:189], v[94:97]
	v_mfma_f32_16x16x32_bf16 v[90:93], v[146:149], v[186:189], v[90:93]
	v_mfma_f32_16x16x32_bf16 v[74:77], v[146:149], v[200:203], v[74:77]
	v_mfma_f32_16x16x32_bf16 v[78:81], v[130:133], v[200:203], v[78:81]
	s_mov_b32 m0, s53
	v_mfma_f32_16x16x32_bf16 v[70:73], v[154:157], v[200:203], v[70:73]
	s_add_i32 s74, s16, 0x80
	v_mfma_f32_16x16x32_bf16 v[66:69], v[162:165], v[200:203], v[66:69]
	v_mfma_f32_16x16x32_bf16 v[82:85], v[162:165], v[186:189], v[82:85]
	v_mfma_f32_16x16x32_bf16 v[86:89], v[154:157], v[186:189], v[86:89]
	v_mfma_f32_16x16x32_bf16 v[102:105], v[154:157], v[178:181], v[102:105]
	v_mfma_f32_16x16x32_bf16 v[98:101], v[162:165], v[178:181], v[98:101]
	v_mfma_f32_16x16x32_bf16 v[114:117], v[162:165], v[170:173], v[114:117]
	v_mfma_f32_16x16x32_bf16 v[118:121], v[154:157], v[170:173], v[118:121]
	v_mfma_f32_16x16x32_bf16 v[126:129], v[142:145], v[174:177], v[126:129]
	v_mfma_f32_16x16x32_bf16 v[122:125], v[150:153], v[174:177], v[122:125]
	v_mfma_f32_16x16x32_bf16 v[106:109], v[150:153], v[182:185], v[106:109]
	v_mfma_f32_16x16x32_bf16 v[110:113], v[142:145], v[182:185], v[110:113]
	v_mfma_f32_16x16x32_bf16 v[94:97], v[142:145], v[190:193], v[94:97]
	v_mfma_f32_16x16x32_bf16 v[90:93], v[150:153], v[190:193], v[90:93]
	v_mfma_f32_16x16x32_bf16 v[74:77], v[150:153], v[206:209], v[74:77]
	v_mfma_f32_16x16x32_bf16 v[78:81], v[142:145], v[206:209], v[78:81]
	v_mfma_f32_16x16x32_bf16 v[70:73], v[158:161], v[206:209], v[70:73]
	v_mfma_f32_16x16x32_bf16 v[66:69], v[166:169], v[206:209], v[66:69]
	v_mfma_f32_16x16x32_bf16 v[82:85], v[166:169], v[190:193], v[82:85]
	v_mfma_f32_16x16x32_bf16 v[86:89], v[158:161], v[190:193], v[86:89]
	v_mfma_f32_16x16x32_bf16 v[102:105], v[158:161], v[182:185], v[102:105]
	v_mfma_f32_16x16x32_bf16 v[98:101], v[166:169], v[182:185], v[98:101]
	v_mfma_f32_16x16x32_bf16 v[114:117], v[166:169], v[174:177], v[114:117]
	v_mfma_f32_16x16x32_bf16 v[118:121], v[158:161], v[174:177], v[118:121]
	s_barrier
; #define PG8_STAGE(bufoff, gbase, voff) do { const int so_ = (int)(unsigned)((const char*)(gbase) - base_##voff); _Pragma("unroll") for (int _i = 0; _i < 2; ++_i) \
;         __builtin_amdgcn_raw_ptr_buffer_load_lds(rs_##voff, (PG8_LAS unsigned*)(lds + (bufoff) + ldsw + _i * 8192), 16, (int)(voff)[_i], so_, 0, 0); } while (0)
; #define PG8_LDA(dst, b, h) do { _Pragma("unroll") for (int m = 0; m < 4; ++m) _Pragma("unroll") for (int k = 0; k < 2; ++k) dst[m][k] = *(const PG8_LAS bf16x8*)(lds + PG8_SA(b, h) + aoff + m * 2048 + k * 1024); } while (0)
; #define PG8_LDB(dst, b, h) do { _Pragma("unroll") for (int n = 0; n < 2; ++n) _Pragma("unroll") for (int k = 0; k < 2; ++k) dst[n][k] = *(const PG8_LAS bf16x8*)(lds + PG8_SB(b, h) + boff + n * 2048 + k * 1024); } while (0)
; #define PG8_MMA(ai, bj, At, Bt) do { __builtin_amdgcn_s_setprio(1); _Pragma("unroll") for (int m = 0; m < 4; ++m) _Pragma("unroll") for (int n = 0; n < 2; ++n) _Pragma("unroll") for (int k = 0; k < 2; ++k) \
;         acc[ai][bj][m][n] = __builtin_amdgcn_mfma_f32_16x16x32_bf16(Bt[n][k], At[m][k], acc[ai][bj][m][n], 0, 0, 0); __builtin_amdgcn_s_setprio(0); } while (0)
; template <class Epi, class Sched, bool ALIGN_EPI = false, bool SP2 = false>
; __device__ __forceinline__ void gemm_phase(PG8_LAS unsigned char* lds, const Gemm g, const Sched& S, const Epi& E, int tid_in) {
;     ...
;             PG8_LDB(B0, 0, 0); PG8_LDB(B1, 0, 1); PG8_SCHED; PG8_LDA(At, 0, 0); PG8_STAGE(PG8_SA(1, 1), a1 + hstepA, voffA);
;             PG8_WAIT_V(8); PG8_WAIT_L(0); PG8_BAR; PG8_MMA(0, 0, At, B0); PG8_MMA(0, 1, At, B1); PG8_BAR; PG8_SCHED;
;             PG8_LDA(At, 0, 1); PG8_STAGE(PG8_SB(0, 0), b2, voffB); PG8_STAGE(PG8_SB(0, 1), b2 + hstepB, voffB); PG8_STAGE(PG8_SA(0, 0), a2, voffA);
;             PG8_WAIT_V(8); PG8_WAIT_L(0); PG8_BAR; PG8_MMA(1, 0, At, B0); PG8_MMA(1, 1, At, B1); PG8_BAR; PG8_SCHED;
;             PG8_LDB(B0, 1, 0); PG8_LDB(B1, 1, 1); PG8_SCHED; PG8_LDA(At, 1, 0); PG8_STAGE(PG8_SA(0, 1), a2 + hstepA, voffA);
;             PG8_WAIT_V(8); PG8_WAIT_L(0); PG8_BAR; PG8_MMA(0, 0, At, B0); PG8_MMA(0, 1, At, B1); PG8_BAR; PG8_SCHED;
;             PG8_LDA(At, 1, 1); PG8_STAGE(PG8_SB(1, 0), b3, voffB); PG8_STAGE(PG8_SB(1, 1), b3 + hstepB, voffB); PG8_STAGE(PG8_SA(1, 0), a3, voffA);
;             PG8_WAIT_V(8); PG8_WAIT_L(0); PG8_BAR; PG8_MMA(1, 0, At, B0); PG8_MMA(1, 1, At, B1); PG8_BAR; PG8_SCHED;
	s_setprio 0
	ds_read_b128 v[170:173], v140 offset:49152
	ds_read_b128 v[174:177], v140 offset:50176
	ds_read_b128 v[178:181], v140 offset:51200
	ds_read_b128 v[182:185], v140 offset:52224
	ds_read_b128 v[186:189], v140 offset:53248
	ds_read_b128 v[190:193], v140 offset:54272
	ds_read_b128 v[200:203], v140 offset:55296
	ds_read_b128 v[206:209], v140 offset:56320
	buffer_load_dwordx4 v134, s[40:43], s74 offen lds
	s_mov_b32 m0, s60
	s_add_i32 s16, s16, 0x80080
	buffer_load_dwordx4 v136, s[40:43], s74 offen lds
	s_mov_b32 m0, s63
	s_addk_i32 s17, 0x80
	buffer_load_dwordx4 v134, s[40:43], s16 offen lds
	s_mov_b32 m0, s66
	s_nop 0
	buffer_load_dwordx4 v136, s[40:43], s16 offen lds
	s_mov_b32 m0, s61
	s_nop 0
	buffer_load_dwordx4 v0, s[4:7], s17 offen lds
	s_waitcnt vmcnt(7)
	s_waitcnt lgkmcnt(0)
	s_setprio 1
	s_barrier
	v_mfma_f32_16x16x32_bf16 v[62:65], v[130:133], v[170:173], v[62:65]
	v_mfma_f32_16x16x32_bf16 v[58:61], v[146:149], v[170:173], v[58:61]
	v_mfma_f32_16x16x32_bf16 v[42:45], v[146:149], v[178:181], v[42:45]
	v_mfma_f32_16x16x32_bf16 v[46:49], v[130:133], v[178:181], v[46:49]
	v_mfma_f32_16x16x32_bf16 v[30:33], v[130:133], v[186:189], v[30:33]
	v_mfma_f32_16x16x32_bf16 v[26:29], v[146:149], v[186:189], v[26:29]
	v_mfma_f32_16x16x32_bf16 v[10:13], v[146:149], v[200:203], v[10:13]
	v_mfma_f32_16x16x32_bf16 v[14:17], v[130:133], v[200:203], v[14:17]
	s_add_i32 s73, s73, 2
	v_mfma_f32_16x16x32_bf16 v[6:9], v[154:157], v[200:203], v[6:9]
	s_add_u32 s19, s19, 0x100
	v_mfma_f32_16x16x32_bf16 v[2:5], v[162:165], v[200:203], v[2:5]
	s_addc_u32 s21, s21, 0
	v_mfma_f32_16x16x32_bf16 v[18:21], v[162:165], v[186:189], v[18:21]
	s_cmp_gt_u32 s73, 29
	v_mfma_f32_16x16x32_bf16 v[22:25], v[154:157], v[186:189], v[22:25]
	s_mov_b64 s[16:17], s[38:39]
	v_mfma_f32_16x16x32_bf16 v[38:41], v[154:157], v[178:181], v[38:41]
	v_mfma_f32_16x16x32_bf16 v[34:37], v[162:165], v[178:181], v[34:37]
	v_mfma_f32_16x16x32_bf16 v[50:53], v[162:165], v[170:173], v[50:53]
	v_mfma_f32_16x16x32_bf16 v[54:57], v[154:157], v[170:173], v[54:57]
	v_mfma_f32_16x16x32_bf16 v[62:65], v[142:145], v[174:177], v[62:65]
	v_mfma_f32_16x16x32_bf16 v[58:61], v[150:153], v[174:177], v[58:61]
	v_mfma_f32_16x16x32_bf16 v[42:45], v[150:153], v[182:185], v[42:45]
	v_mfma_f32_16x16x32_bf16 v[46:49], v[142:145], v[182:185], v[46:49]
	v_mfma_f32_16x16x32_bf16 v[30:33], v[142:145], v[190:193], v[30:33]
	v_mfma_f32_16x16x32_bf16 v[26:29], v[150:153], v[190:193], v[26:29]
	v_mfma_f32_16x16x32_bf16 v[10:13], v[150:153], v[206:209], v[10:13]
	v_mfma_f32_16x16x32_bf16 v[14:17], v[142:145], v[206:209], v[14:17]
	v_mfma_f32_16x16x32_bf16 v[6:9], v[158:161], v[206:209], v[6:9]
	v_mfma_f32_16x16x32_bf16 v[2:5], v[166:169], v[206:209], v[2:5]
	v_mfma_f32_16x16x32_bf16 v[18:21], v[166:169], v[190:193], v[18:21]
	v_mfma_f32_16x16x32_bf16 v[22:25], v[158:161], v[190:193], v[22:25]
	v_mfma_f32_16x16x32_bf16 v[38:41], v[158:161], v[182:185], v[38:41]
	v_mfma_f32_16x16x32_bf16 v[34:37], v[166:169], v[182:185], v[34:37]
	v_mfma_f32_16x16x32_bf16 v[50:53], v[166:169], v[174:177], v[50:53]
	v_mfma_f32_16x16x32_bf16 v[54:57], v[158:161], v[174:177], v[54:57]
	s_barrier
	s_setprio 0
.LBB0_1514:
	v_add_u32_e32 v141, 0x10000, v139
	ds_read_b128 v[130:133], v141
	ds_read_b128 v[142:145], v141 offset:1024
	ds_read_b128 v[146:149], v141 offset:2048
	ds_read_b128 v[150:153], v141 offset:3072
	v_add_u32_e32 v141, 0x14000, v139
	ds_read_b128 v[154:157], v141
	ds_read_b128 v[158:161], v141 offset:1024
	ds_read_b128 v[162:165], v141 offset:2048
	ds_read_b128 v[166:169], v141 offset:3072
	s_add_u32 s38, s16, 0x100
	s_addc_u32 s39, s17, 0
	s_sub_i32 s16, s16, s4
	s_add_i32 s16, s16, 0x80080
	s_sub_i32 s74, s16, 0x80000
	s_cmp_eq_u32 s73, 28
	s_cselect_b32 s17, s18, s38
	s_mov_b32 m0, s67
	ds_read_b128 v[170:173], v140
	ds_read_b128 v[174:177], v140 offset:1024
	ds_read_b128 v[178:181], v140 offset:2048
	ds_read_b128 v[182:185], v140 offset:3072
	ds_read_b128 v[186:189], v140 offset:4096
	ds_read_b128 v[190:193], v140 offset:5120
	ds_read_b128 v[200:203], v140 offset:6144
	ds_read_b128 v[206:209], v140 offset:7168
	s_mov_b32 m0, s62
	s_nop 0
	buffer_load_dwordx4 v135, s[4:7], s74 offen lds
	s_mov_b32 m0, s67
	s_nop 0
	buffer_load_dwordx4 v0, s[4:7], s16 offen lds
	s_mov_b32 m0, s68
	s_nop 0
	buffer_load_dwordx4 v135, s[4:7], s16 offen lds
	s_waitcnt vmcnt(8)
	s_waitcnt lgkmcnt(0)
	s_setprio 1
	s_barrier
	v_mfma_f32_16x16x32_bf16 v[126:129], v[130:133], v[170:173], v[126:129]
	v_mfma_f32_16x16x32_bf16 v[122:125], v[146:149], v[170:173], v[122:125]
	v_mfma_f32_16x16x32_bf16 v[106:109], v[146:149], v[178:181], v[106:109]
	v_mfma_f32_16x16x32_bf16 v[110:113], v[130:133], v[178:181], v[110:113]
	v_mfma_f32_16x16x32_bf16 v[94:97], v[130:133], v[186:189], v[94:97]
	v_mfma_f32_16x16x32_bf16 v[90:93], v[146:149], v[186:189], v[90:93]
	v_mfma_f32_16x16x32_bf16 v[74:77], v[146:149], v[200:203], v[74:77]
	v_mfma_f32_16x16x32_bf16 v[78:81], v[130:133], v[200:203], v[78:81]
	s_cselect_b32 s16, s15, s19
	v_mfma_f32_16x16x32_bf16 v[70:73], v[154:157], v[200:203], v[70:73]
	s_mov_b32 m0, s35
	v_mfma_f32_16x16x32_bf16 v[66:69], v[162:165], v[200:203], v[66:69]
	s_mov_b32 s42, s6
	v_mfma_f32_16x16x32_bf16 v[82:85], v[162:165], v[186:189], v[82:85]
	s_mov_b32 s43, s7
	v_mfma_f32_16x16x32_bf16 v[86:89], v[154:157], v[186:189], v[86:89]
	s_sub_i32 s16, s16, s40
	v_mfma_f32_16x16x32_bf16 v[102:105], v[154:157], v[178:181], v[102:105]
	v_mfma_f32_16x16x32_bf16 v[98:101], v[162:165], v[178:181], v[98:101]
	v_mfma_f32_16x16x32_bf16 v[114:117], v[162:165], v[170:173], v[114:117]
	v_mfma_f32_16x16x32_bf16 v[118:121], v[154:157], v[170:173], v[118:121]
	v_mfma_f32_16x16x32_bf16 v[126:129], v[142:145], v[174:177], v[126:129]
	v_mfma_f32_16x16x32_bf16 v[122:125], v[150:153], v[174:177], v[122:125]
	v_mfma_f32_16x16x32_bf16 v[106:109], v[150:153], v[182:185], v[106:109]
	v_mfma_f32_16x16x32_bf16 v[110:113], v[142:145], v[182:185], v[110:113]
	v_mfma_f32_16x16x32_bf16 v[94:97], v[142:145], v[190:193], v[94:97]
	v_mfma_f32_16x16x32_bf16 v[90:93], v[150:153], v[190:193], v[90:93]
	v_mfma_f32_16x16x32_bf16 v[74:77], v[150:153], v[206:209], v[74:77]
	v_mfma_f32_16x16x32_bf16 v[78:81], v[142:145], v[206:209], v[78:81]
	v_mfma_f32_16x16x32_bf16 v[70:73], v[158:161], v[206:209], v[70:73]
	v_mfma_f32_16x16x32_bf16 v[66:69], v[166:169], v[206:209], v[66:69]
	v_mfma_f32_16x16x32_bf16 v[82:85], v[166:169], v[190:193], v[82:85]
	v_mfma_f32_16x16x32_bf16 v[86:89], v[158:161], v[190:193], v[86:89]
	v_mfma_f32_16x16x32_bf16 v[102:105], v[158:161], v[182:185], v[102:105]
	v_mfma_f32_16x16x32_bf16 v[98:101], v[166:169], v[182:185], v[98:101]
	v_mfma_f32_16x16x32_bf16 v[114:117], v[166:169], v[174:177], v[114:117]
	v_mfma_f32_16x16x32_bf16 v[118:121], v[158:161], v[174:177], v[118:121]
	s_barrier
; #define PG8_STAGE(bufoff, gbase, voff) do { const int so_ = (int)(unsigned)((const char*)(gbase) - base_##voff); _Pragma("unroll") for (int _i = 0; _i < 2; ++_i) \
;         __builtin_amdgcn_raw_ptr_buffer_load_lds(rs_##voff, (PG8_LAS unsigned*)(lds + (bufoff) + ldsw + _i * 8192), 16, (int)(voff)[_i], so_, 0, 0); } while (0)
; #define PG8_LDA(dst, b, h) do { _Pragma("unroll") for (int m = 0; m < 4; ++m) _Pragma("unroll") for (int k = 0; k < 2; ++k) dst[m][k] = *(const PG8_LAS bf16x8*)(lds + PG8_SA(b, h) + aoff + m * 2048 + k * 1024); } while (0)
; #define PG8_LDB(dst, b, h) do { _Pragma("unroll") for (int n = 0; n < 2; ++n) _Pragma("unroll") for (int k = 0; k < 2; ++k) dst[n][k] = *(const PG8_LAS bf16x8*)(lds + PG8_SB(b, h) + boff + n * 2048 + k * 1024); } while (0)
; #define PG8_MMA(ai, bj, At, Bt) do { __builtin_amdgcn_s_setprio(1); _Pragma("unroll") for (int m = 0; m < 4; ++m) _Pragma("unroll") for (int n = 0; n < 2; ++n) _Pragma("unroll") for (int k = 0; k < 2; ++k) \
;         acc[ai][bj][m][n] = __builtin_amdgcn_mfma_f32_16x16x32_bf16(Bt[n][k], At[m][k], acc[ai][bj][m][n], 0, 0, 0); __builtin_amdgcn_s_setprio(0); } while (0)
; #define PG8_WAIT_V(n) asm volatile("s_waitcnt vmcnt(" #n ")" ::: "memory")
; #define PG8_WAIT_L(n) asm volatile("s_waitcnt lgkmcnt(" #n ")" ::: "memory")
; #define PG8_BAR __builtin_amdgcn_s_barrier()
; #define PG8_SCHED __builtin_amdgcn_sched_barrier(0)
; template <class Epi, class Sched, bool ALIGN_EPI = false, bool SP2 = false>
; __device__ __forceinline__ void gemm_phase(PG8_LAS unsigned char* lds, const Gemm g, const Sched& S, const Epi& E, int tid_in) {
;     ...
;             PG8_LDA(At, 0, 1); PG8_STAGE(PG8_SB(0, 0), b2, voffB); PG8_STAGE(PG8_SB(0, 1), b2 + hstepB, voffB); PG8_STAGE(PG8_SA(0, 0), a2, voffA);
;             PG8_WAIT_V(8); PG8_WAIT_L(0); PG8_BAR; PG8_MMA(1, 0, At, B0); PG8_MMA(1, 1, At, B1); PG8_BAR; PG8_SCHED;
;             PG8_LDB(B0, 1, 0); PG8_LDB(B1, 1, 1); PG8_SCHED; PG8_LDA(At, 1, 0); PG8_STAGE(PG8_SA(0, 1), a2 + hstepA, voffA);
;             PG8_WAIT_V(8); PG8_WAIT_L(0); PG8_BAR; PG8_MMA(0, 0, At, B0); PG8_MMA(0, 1, At, B1); PG8_BAR; PG8_SCHED;
	s_setprio 0
	ds_read_b128 v[170:173], v140 offset:16384
	ds_read_b128 v[174:177], v140 offset:17408
	ds_read_b128 v[178:181], v140 offset:18432
	ds_read_b128 v[182:185], v140 offset:19456
	ds_read_b128 v[186:189], v140 offset:20480
	ds_read_b128 v[190:193], v140 offset:21504
	ds_read_b128 v[200:203], v140 offset:22528
	ds_read_b128 v[206:209], v140 offset:23552
	buffer_load_dwordx4 v134, s[40:43], s16 offen lds
	s_mov_b32 m0, s44
	s_add_i32 s74, s16, 0x80000
	buffer_load_dwordx4 v136, s[40:43], s16 offen lds
	s_mov_b32 m0, s45
	s_sub_i32 s17, s17, s4
	buffer_load_dwordx4 v134, s[40:43], s74 offen lds
	s_mov_b32 m0, s46
	s_nop 0
	buffer_load_dwordx4 v136, s[40:43], s74 offen lds
	s_mov_b32 m0, s34
	s_nop 0
	buffer_load_dwordx4 v0, s[4:7], s17 offen lds
	s_waitcnt vmcnt(7)
	s_waitcnt lgkmcnt(0)
	s_setprio 1
	s_barrier
	v_mfma_f32_16x16x32_bf16 v[62:65], v[130:133], v[170:173], v[62:65]
	v_mfma_f32_16x16x32_bf16 v[58:61], v[146:149], v[170:173], v[58:61]
	v_mfma_f32_16x16x32_bf16 v[42:45], v[146:149], v[178:181], v[42:45]
	v_mfma_f32_16x16x32_bf16 v[46:49], v[130:133], v[178:181], v[46:49]
	v_mfma_f32_16x16x32_bf16 v[30:33], v[130:133], v[186:189], v[30:33]
	v_mfma_f32_16x16x32_bf16 v[26:29], v[146:149], v[186:189], v[26:29]
	v_mfma_f32_16x16x32_bf16 v[10:13], v[146:149], v[200:203], v[10:13]
	v_mfma_f32_16x16x32_bf16 v[14:17], v[130:133], v[200:203], v[14:17]
	v_mfma_f32_16x16x32_bf16 v[6:9], v[154:157], v[200:203], v[6:9]
	v_mfma_f32_16x16x32_bf16 v[2:5], v[162:165], v[200:203], v[2:5]
	v_mfma_f32_16x16x32_bf16 v[18:21], v[162:165], v[186:189], v[18:21]
	v_mfma_f32_16x16x32_bf16 v[22:25], v[154:157], v[186:189], v[22:25]
	v_mfma_f32_16x16x32_bf16 v[38:41], v[154:157], v[178:181], v[38:41]
	v_mfma_f32_16x16x32_bf16 v[34:37], v[162:165], v[178:181], v[34:37]
	v_mfma_f32_16x16x32_bf16 v[50:53], v[162:165], v[170:173], v[50:53]
	v_mfma_f32_16x16x32_bf16 v[54:57], v[154:157], v[170:173], v[54:57]
	v_mfma_f32_16x16x32_bf16 v[62:65], v[142:145], v[174:177], v[62:65]
	v_mfma_f32_16x16x32_bf16 v[58:61], v[150:153], v[174:177], v[58:61]
	v_mfma_f32_16x16x32_bf16 v[42:45], v[150:153], v[182:185], v[42:45]
	v_mfma_f32_16x16x32_bf16 v[46:49], v[142:145], v[182:185], v[46:49]
	v_mfma_f32_16x16x32_bf16 v[30:33], v[142:145], v[190:193], v[30:33]
	v_mfma_f32_16x16x32_bf16 v[26:29], v[150:153], v[190:193], v[26:29]
	v_mfma_f32_16x16x32_bf16 v[10:13], v[150:153], v[206:209], v[10:13]
	v_mfma_f32_16x16x32_bf16 v[14:17], v[142:145], v[206:209], v[14:17]
	v_mfma_f32_16x16x32_bf16 v[6:9], v[158:161], v[206:209], v[6:9]
	v_mfma_f32_16x16x32_bf16 v[2:5], v[166:169], v[206:209], v[2:5]
	v_mfma_f32_16x16x32_bf16 v[18:21], v[166:169], v[190:193], v[18:21]
	v_mfma_f32_16x16x32_bf16 v[22:25], v[158:161], v[190:193], v[22:25]
	v_mfma_f32_16x16x32_bf16 v[38:41], v[158:161], v[182:185], v[38:41]
	v_mfma_f32_16x16x32_bf16 v[34:37], v[166:169], v[182:185], v[34:37]
	v_mfma_f32_16x16x32_bf16 v[50:53], v[166:169], v[174:177], v[50:53]
	v_mfma_f32_16x16x32_bf16 v[54:57], v[158:161], v[174:177], v[54:57]
	s_barrier
	s_setprio 0
	v_add_u32_e32 v141, 0x18000, v139
	ds_read_b128 v[130:133], v141
	ds_read_b128 v[142:145], v141 offset:1024
	ds_read_b128 v[146:149], v141 offset:2048
	ds_read_b128 v[150:153], v141 offset:3072
	v_add_u32_e32 v141, 0x1c000, v139
	ds_read_b128 v[154:157], v141
	ds_read_b128 v[158:161], v141 offset:1024
	ds_read_b128 v[162:165], v141 offset:2048
	ds_read_b128 v[166:169], v141 offset:3072
	s_add_i32 s74, s17, 0x80000
	s_mov_b32 m0, s48
	ds_read_b128 v[170:173], v140 offset:32768
	ds_read_b128 v[174:177], v140 offset:33792
	ds_read_b128 v[178:181], v140 offset:34816
	ds_read_b128 v[182:185], v140 offset:35840
	ds_read_b128 v[186:189], v140 offset:36864
	ds_read_b128 v[190:193], v140 offset:37888
	ds_read_b128 v[200:203], v140 offset:38912
	ds_read_b128 v[206:209], v140 offset:39936
	s_mov_b32 m0, s47
	s_nop 0
	buffer_load_dwordx4 v135, s[4:7], s17 offen lds
	s_mov_b32 m0, s48
	s_nop 0
	buffer_load_dwordx4 v0, s[4:7], s74 offen lds
	s_mov_b32 m0, s49
	s_nop 0
	buffer_load_dwordx4 v135, s[4:7], s74 offen lds
	s_waitcnt vmcnt(8)
	s_waitcnt lgkmcnt(0)
	s_setprio 1
	s_barrier
; #define PG8_STAGE(bufoff, gbase, voff) do { const int so_ = (int)(unsigned)((const char*)(gbase) - base_##voff); _Pragma("unroll") for (int _i = 0; _i < 2; ++_i) \
;         __builtin_amdgcn_raw_ptr_buffer_load_lds(rs_##voff, (PG8_LAS unsigned*)(lds + (bufoff) + ldsw + _i * 8192), 16, (int)(voff)[_i], so_, 0, 0); } while (0)
; #define PG8_LDA(dst, b, h) do { _Pragma("unroll") for (int m = 0; m < 4; ++m) _Pragma("unroll") for (int k = 0; k < 2; ++k) dst[m][k] = *(const PG8_LAS bf16x8*)(lds + PG8_SA(b, h) + aoff + m * 2048 + k * 1024); } while (0)
; #define PG8_LDB(dst, b, h) do { _Pragma("unroll") for (int n = 0; n < 2; ++n) _Pragma("unroll") for (int k = 0; k < 2; ++k) dst[n][k] = *(const PG8_LAS bf16x8*)(lds + PG8_SB(b, h) + boff + n * 2048 + k * 1024); } while (0)
; #define PG8_MMA(ai, bj, At, Bt) do { __builtin_amdgcn_s_setprio(1); _Pragma("unroll") for (int m = 0; m < 4; ++m) _Pragma("unroll") for (int n = 0; n < 2; ++n) _Pragma("unroll") for (int k = 0; k < 2; ++k) \
;         acc[ai][bj][m][n] = __builtin_amdgcn_mfma_f32_16x16x32_bf16(Bt[n][k], At[m][k], acc[ai][bj][m][n], 0, 0, 0); __builtin_amdgcn_s_setprio(0); } while (0)
; #define PG8_WAIT_V(n) asm volatile("s_waitcnt vmcnt(" #n ")" ::: "memory")
; #define PG8_WAIT_L(n) asm volatile("s_waitcnt lgkmcnt(" #n ")" ::: "memory")
; #define PG8_BAR __builtin_amdgcn_s_barrier()
; #define PG8_SCHED __builtin_amdgcn_sched_barrier(0)
; template <class Epi, class Sched, bool ALIGN_EPI = false, bool SP2 = false>
; __device__ __forceinline__ void gemm_phase(PG8_LAS unsigned char* lds, const Gemm g, const Sched& S, const Epi& E, int tid_in) {
;     ...
;             PG8_LDB(B0, 1, 0); PG8_LDB(B1, 1, 1); PG8_SCHED; PG8_LDA(At, 1, 0); PG8_STAGE(PG8_SA(0, 1), a2 + hstepA, voffA);
;             PG8_WAIT_V(8); PG8_WAIT_L(0); PG8_BAR; PG8_MMA(0, 0, At, B0); PG8_MMA(0, 1, At, B1); PG8_BAR; PG8_SCHED;
;             PG8_LDA(At, 1, 1); PG8_STAGE(PG8_SB(1, 0), b3, voffB); PG8_STAGE(PG8_SB(1, 1), b3 + hstepB, voffB); PG8_STAGE(PG8_SA(1, 0), a3, voffA);
;             PG8_WAIT_V(8); PG8_WAIT_L(0); PG8_BAR; PG8_MMA(1, 0, At, B0); PG8_MMA(1, 1, At, B1); PG8_BAR; PG8_SCHED;
	v_mfma_f32_16x16x32_bf16 v[126:129], v[130:133], v[170:173], v[126:129]
	v_mfma_f32_16x16x32_bf16 v[122:125], v[146:149], v[170:173], v[122:125]
	v_mfma_f32_16x16x32_bf16 v[106:109], v[146:149], v[178:181], v[106:109]
	v_mfma_f32_16x16x32_bf16 v[110:113], v[130:133], v[178:181], v[110:113]
	v_mfma_f32_16x16x32_bf16 v[94:97], v[130:133], v[186:189], v[94:97]
	v_mfma_f32_16x16x32_bf16 v[90:93], v[146:149], v[186:189], v[90:93]
	v_mfma_f32_16x16x32_bf16 v[74:77], v[146:149], v[200:203], v[74:77]
	v_mfma_f32_16x16x32_bf16 v[78:81], v[130:133], v[200:203], v[78:81]
	s_mov_b32 m0, s53
	v_mfma_f32_16x16x32_bf16 v[70:73], v[154:157], v[200:203], v[70:73]
	s_add_i32 s74, s16, 0x80
	v_mfma_f32_16x16x32_bf16 v[66:69], v[162:165], v[200:203], v[66:69]
	v_mfma_f32_16x16x32_bf16 v[82:85], v[162:165], v[186:189], v[82:85]
	v_mfma_f32_16x16x32_bf16 v[86:89], v[154:157], v[186:189], v[86:89]
	v_mfma_f32_16x16x32_bf16 v[102:105], v[154:157], v[178:181], v[102:105]
	v_mfma_f32_16x16x32_bf16 v[98:101], v[162:165], v[178:181], v[98:101]
	v_mfma_f32_16x16x32_bf16 v[114:117], v[162:165], v[170:173], v[114:117]
	v_mfma_f32_16x16x32_bf16 v[118:121], v[154:157], v[170:173], v[118:121]
	v_mfma_f32_16x16x32_bf16 v[126:129], v[142:145], v[174:177], v[126:129]
	v_mfma_f32_16x16x32_bf16 v[122:125], v[150:153], v[174:177], v[122:125]
	v_mfma_f32_16x16x32_bf16 v[106:109], v[150:153], v[182:185], v[106:109]
	v_mfma_f32_16x16x32_bf16 v[110:113], v[142:145], v[182:185], v[110:113]
	v_mfma_f32_16x16x32_bf16 v[94:97], v[142:145], v[190:193], v[94:97]
	v_mfma_f32_16x16x32_bf16 v[90:93], v[150:153], v[190:193], v[90:93]
	v_mfma_f32_16x16x32_bf16 v[74:77], v[150:153], v[206:209], v[74:77]
	v_mfma_f32_16x16x32_bf16 v[78:81], v[142:145], v[206:209], v[78:81]
	v_mfma_f32_16x16x32_bf16 v[70:73], v[158:161], v[206:209], v[70:73]
	v_mfma_f32_16x16x32_bf16 v[66:69], v[166:169], v[206:209], v[66:69]
	v_mfma_f32_16x16x32_bf16 v[82:85], v[166:169], v[190:193], v[82:85]
	v_mfma_f32_16x16x32_bf16 v[86:89], v[158:161], v[190:193], v[86:89]
	v_mfma_f32_16x16x32_bf16 v[102:105], v[158:161], v[182:185], v[102:105]
	v_mfma_f32_16x16x32_bf16 v[98:101], v[166:169], v[182:185], v[98:101]
	v_mfma_f32_16x16x32_bf16 v[114:117], v[166:169], v[174:177], v[114:117]
	v_mfma_f32_16x16x32_bf16 v[118:121], v[158:161], v[174:177], v[118:121]
	s_barrier
	s_setprio 0
	ds_read_b128 v[170:173], v140 offset:49152
	ds_read_b128 v[174:177], v140 offset:50176
	ds_read_b128 v[178:181], v140 offset:51200
	ds_read_b128 v[182:185], v140 offset:52224
	ds_read_b128 v[186:189], v140 offset:53248
	ds_read_b128 v[190:193], v140 offset:54272
	ds_read_b128 v[200:203], v140 offset:55296
	ds_read_b128 v[206:209], v140 offset:56320
	buffer_load_dwordx4 v134, s[40:43], s74 offen lds
	s_mov_b32 m0, s60
	s_add_i32 s16, s16, 0x80080
	buffer_load_dwordx4 v136, s[40:43], s74 offen lds
	s_mov_b32 m0, s63
	s_addk_i32 s17, 0x80
	buffer_load_dwordx4 v134, s[40:43], s16 offen lds
	s_mov_b32 m0, s66
	s_nop 0
	buffer_load_dwordx4 v136, s[40:43], s16 offen lds
	s_mov_b32 m0, s61
	s_nop 0
	buffer_load_dwordx4 v0, s[4:7], s17 offen lds
	s_waitcnt vmcnt(7)
	s_waitcnt lgkmcnt(0)
	s_setprio 1
	s_barrier
	v_mfma_f32_16x16x32_bf16 v[62:65], v[130:133], v[170:173], v[62:65]
	v_mfma_f32_16x16x32_bf16 v[58:61], v[146:149], v[170:173], v[58:61]
	v_mfma_f32_16x16x32_bf16 v[42:45], v[146:149], v[178:181], v[42:45]
	v_mfma_f32_16x16x32_bf16 v[46:49], v[130:133], v[178:181], v[46:49]
	v_mfma_f32_16x16x32_bf16 v[30:33], v[130:133], v[186:189], v[30:33]
	v_mfma_f32_16x16x32_bf16 v[26:29], v[146:149], v[186:189], v[26:29]
	v_mfma_f32_16x16x32_bf16 v[10:13], v[146:149], v[200:203], v[10:13]
	v_mfma_f32_16x16x32_bf16 v[14:17], v[130:133], v[200:203], v[14:17]
	s_add_i32 s73, s73, 2
	v_mfma_f32_16x16x32_bf16 v[6:9], v[154:157], v[200:203], v[6:9]
	s_add_u32 s19, s19, 0x100
	v_mfma_f32_16x16x32_bf16 v[2:5], v[162:165], v[200:203], v[2:5]
	s_addc_u32 s21, s21, 0
	v_mfma_f32_16x16x32_bf16 v[18:21], v[162:165], v[186:189], v[18:21]
	s_cmp_gt_u32 s73, 29
	v_mfma_f32_16x16x32_bf16 v[22:25], v[154:157], v[186:189], v[22:25]
	s_mov_b64 s[16:17], s[38:39]
	v_mfma_f32_16x16x32_bf16 v[38:41], v[154:157], v[178:181], v[38:41]
	v_mfma_f32_16x16x32_bf16 v[34:37], v[162:165], v[178:181], v[34:37]
	v_mfma_f32_16x16x32_bf16 v[50:53], v[162:165], v[170:173], v[50:53]
	v_mfma_f32_16x16x32_bf16 v[54:57], v[154:157], v[170:173], v[54:57]
	v_mfma_f32_16x16x32_bf16 v[62:65], v[142:145], v[174:177], v[62:65]
	v_mfma_f32_16x16x32_bf16 v[58:61], v[150:153], v[174:177], v[58:61]
	v_mfma_f32_16x16x32_bf16 v[42:45], v[150:153], v[182:185], v[42:45]
	v_mfma_f32_16x16x32_bf16 v[46:49], v[142:145], v[182:185], v[46:49]
	v_mfma_f32_16x16x32_bf16 v[30:33], v[142:145], v[190:193], v[30:33]
	v_mfma_f32_16x16x32_bf16 v[26:29], v[150:153], v[190:193], v[26:29]
	v_mfma_f32_16x16x32_bf16 v[10:13], v[150:153], v[206:209], v[10:13]
	v_mfma_f32_16x16x32_bf16 v[14:17], v[142:145], v[206:209], v[14:17]
	v_mfma_f32_16x16x32_bf16 v[6:9], v[158:161], v[206:209], v[6:9]
	v_mfma_f32_16x16x32_bf16 v[2:5], v[166:169], v[206:209], v[2:5]
	v_mfma_f32_16x16x32_bf16 v[18:21], v[166:169], v[190:193], v[18:21]
	v_mfma_f32_16x16x32_bf16 v[22:25], v[158:161], v[190:193], v[22:25]
	v_mfma_f32_16x16x32_bf16 v[38:41], v[158:161], v[182:185], v[38:41]
	v_mfma_f32_16x16x32_bf16 v[34:37], v[166:169], v[182:185], v[34:37]
	v_mfma_f32_16x16x32_bf16 v[50:53], v[166:169], v[174:177], v[50:53]
	v_mfma_f32_16x16x32_bf16 v[54:57], v[158:161], v[174:177], v[54:57]
	s_barrier
	s_setprio 0
	s_cbranch_scc0 .LBB0_1514
	s_and_b64 vcc, exec, s[12:13]
	s_cbranch_vccz .LBB0_1517
	s_barrier

; #define PG8_STAGE(bufoff, gbase, voff) do { const int so_ = (int)(unsigned)((const char*)(gbase) - base_##voff); _Pragma("unroll") for (int _i = 0; _i < 2; ++_i) \
;         __builtin_amdgcn_raw_ptr_buffer_load_lds(rs_##voff, (PG8_LAS unsigned*)(lds + (bufoff) + ldsw + _i * 8192), 16, (int)(voff)[_i], so_, 0, 0); } while (0)
; #define PG8_LDA(dst, b, h) do { _Pragma("unroll") for (int m = 0; m < 4; ++m) _Pragma("unroll") for (int k = 0; k < 2; ++k) dst[m][k] = *(const PG8_LAS bf16x8*)(lds + PG8_SA(b, h) + aoff + m * 2048 + k * 1024); } while (0)
; #define PG8_LDB(dst, b, h) do { _Pragma("unroll") for (int n = 0; n < 2; ++n) _Pragma("unroll") for (int k = 0; k < 2; ++k) dst[n][k] = *(const PG8_LAS bf16x8*)(lds + PG8_SB(b, h) + boff + n * 2048 + k * 1024); } while (0)
; #define PG8_MMA(ai, bj, At, Bt) do { __builtin_amdgcn_s_setprio(1); _Pragma("unroll") for (int m = 0; m < 4; ++m) _Pragma("unroll") for (int n = 0; n < 2; ++n) _Pragma("unroll") for (int k = 0; k < 2; ++k) \
;         acc[ai][bj][m][n] = __builtin_amdgcn_mfma_f32_16x16x32_bf16(Bt[n][k], At[m][k], acc[ai][bj][m][n], 0, 0, 0); __builtin_amdgcn_s_setprio(0); } while (0)
; #define PG8_WAIT_V(n) asm volatile("s_waitcnt vmcnt(" #n ")" ::: "memory")
; #define PG8_WAIT_L(n) asm volatile("s_waitcnt lgkmcnt(" #n ")" ::: "memory")
; #define PG8_BAR __builtin_amdgcn_s_barrier()
; #define PG8_SCHED __builtin_amdgcn_sched_barrier(0)
; template <class Epi, class Sched, bool ALIGN_EPI = false, bool SP2 = false>
; __device__ __forceinline__ void gemm_phase(PG8_LAS unsigned char* lds, const Gemm g, const Sched& S, const Epi& E, int tid_in) {
;     ...
;             PG8_LDB(B0, 0, 0); PG8_LDB(B1, 0, 1); PG8_SCHED; PG8_LDA(At, 0, 0); PG8_STAGE(PG8_SA(1, 1), a1 + hstepA, voffA);
;             PG8_WAIT_V(8); PG8_WAIT_L(0); PG8_BAR; PG8_MMA(0, 0, At, B0); PG8_MMA(0, 1, At, B1); PG8_BAR; PG8_SCHED;
;             PG8_LDA(At, 0, 1); PG8_STAGE(PG8_SB(0, 0), b2, voffB); PG8_STAGE(PG8_SB(0, 1), b2 + hstepB, voffB); PG8_STAGE(PG8_SA(0, 0), a2, voffA);
;             PG8_WAIT_V(8); PG8_WAIT_L(0); PG8_BAR; PG8_MMA(1, 0, At, B0); PG8_MMA(1, 1, At, B1); PG8_BAR; PG8_SCHED;
.LBB0_1584:
	v_add_u32_e32 v133, 0x10000, v131
	ds_read_b128 v[134:137], v133
	ds_read_b128 v[138:141], v133 offset:1024
	ds_read_b128 v[142:145], v133 offset:2048
	ds_read_b128 v[146:149], v133 offset:3072
	v_add_u32_e32 v133, 0x14000, v131
	ds_read_b128 v[150:153], v133
	ds_read_b128 v[154:157], v133 offset:1024
	ds_read_b128 v[158:161], v133 offset:2048
	ds_read_b128 v[166:169], v133 offset:3072
	s_add_i32 s43, s38, s22
	s_add_i32 s42, s14, s22
	s_add_i32 s76, s12, s22
	s_addk_i32 s43, 0xff80
	s_sub_i32 s78, s43, 0x160000
	s_cmpk_eq_i32 s39, 0x54
	s_cselect_b32 s77, s16, s42
	s_mov_b32 m0, s68
	ds_read_b128 v[170:173], v132
	ds_read_b128 v[174:177], v132 offset:1024
	ds_read_b128 v[178:181], v132 offset:2048
	ds_read_b128 v[182:185], v132 offset:3072
	ds_read_b128 v[186:189], v132 offset:4096
	ds_read_b128 v[190:193], v132 offset:5120
	ds_read_b128 v[200:203], v132 offset:6144
	ds_read_b128 v[206:209], v132 offset:7168
	s_mov_b32 m0, s63
	s_nop 0
	buffer_load_dwordx4 v130, s[4:7], s78 offen lds
	s_mov_b32 m0, s68
	s_nop 0
	buffer_load_dwordx4 v0, s[4:7], s43 offen lds
	s_mov_b32 m0, s69
	s_nop 0
	buffer_load_dwordx4 v130, s[4:7], s43 offen lds
	s_waitcnt vmcnt(8)
	s_waitcnt lgkmcnt(0)
	s_setprio 1
	s_barrier
	v_mfma_f32_16x16x32_bf16 v[22:25], v[134:137], v[170:173], v[22:25]
	v_mfma_f32_16x16x32_bf16 v[14:17], v[142:145], v[170:173], v[14:17]
	v_mfma_f32_16x16x32_bf16 v[54:57], v[142:145], v[178:181], v[54:57]
	v_mfma_f32_16x16x32_bf16 v[74:77], v[134:137], v[178:181], v[74:77]
	v_mfma_f32_16x16x32_bf16 v[106:109], v[134:137], v[186:189], v[106:109]
	v_mfma_f32_16x16x32_bf16 v[102:105], v[142:145], v[186:189], v[102:105]
	v_mfma_f32_16x16x32_bf16 v[118:121], v[142:145], v[200:203], v[118:121]
	v_mfma_f32_16x16x32_bf16 v[122:125], v[134:137], v[200:203], v[122:125]
	s_cselect_b32 s76, s20, s76
	v_mfma_f32_16x16x32_bf16 v[114:117], v[150:153], v[200:203], v[114:117]
	s_mov_b32 m0, s26
	v_mfma_f32_16x16x32_bf16 v[126:129], v[158:161], v[200:203], v[126:129]
	s_mov_b32 s42, s6
	v_mfma_f32_16x16x32_bf16 v[110:113], v[158:161], v[186:189], v[110:113]
	s_mov_b32 s43, s7
	v_mfma_f32_16x16x32_bf16 v[98:101], v[150:153], v[186:189], v[98:101]
	s_sub_i32 s76, s76, s40
	v_mfma_f32_16x16x32_bf16 v[50:53], v[150:153], v[178:181], v[50:53]
	v_mfma_f32_16x16x32_bf16 v[78:81], v[158:161], v[178:181], v[78:81]
	v_mfma_f32_16x16x32_bf16 v[18:21], v[158:161], v[170:173], v[18:21]
	v_mfma_f32_16x16x32_bf16 v[6:9], v[150:153], v[170:173], v[6:9]
	v_mfma_f32_16x16x32_bf16 v[22:25], v[138:141], v[174:177], v[22:25]
	v_mfma_f32_16x16x32_bf16 v[14:17], v[146:149], v[174:177], v[14:17]
	v_mfma_f32_16x16x32_bf16 v[54:57], v[146:149], v[182:185], v[54:57]
	v_mfma_f32_16x16x32_bf16 v[74:77], v[138:141], v[182:185], v[74:77]
	v_mfma_f32_16x16x32_bf16 v[106:109], v[138:141], v[190:193], v[106:109]
	v_mfma_f32_16x16x32_bf16 v[102:105], v[146:149], v[190:193], v[102:105]
	v_mfma_f32_16x16x32_bf16 v[118:121], v[146:149], v[206:209], v[118:121]
	v_mfma_f32_16x16x32_bf16 v[122:125], v[138:141], v[206:209], v[122:125]
	v_mfma_f32_16x16x32_bf16 v[114:117], v[154:157], v[206:209], v[114:117]
	v_mfma_f32_16x16x32_bf16 v[126:129], v[166:169], v[206:209], v[126:129]
	v_mfma_f32_16x16x32_bf16 v[110:113], v[166:169], v[190:193], v[110:113]
	v_mfma_f32_16x16x32_bf16 v[98:101], v[154:157], v[190:193], v[98:101]
	v_mfma_f32_16x16x32_bf16 v[50:53], v[154:157], v[182:185], v[50:53]
	v_mfma_f32_16x16x32_bf16 v[78:81], v[166:169], v[182:185], v[78:81]
	v_mfma_f32_16x16x32_bf16 v[18:21], v[166:169], v[174:177], v[18:21]
	v_mfma_f32_16x16x32_bf16 v[6:9], v[154:157], v[174:177], v[6:9]
	s_barrier
	s_setprio 0
	ds_read_b128 v[170:173], v132 offset:16384
	ds_read_b128 v[174:177], v132 offset:17408
	ds_read_b128 v[178:181], v132 offset:18432
	ds_read_b128 v[182:185], v132 offset:19456
	ds_read_b128 v[186:189], v132 offset:20480
	ds_read_b128 v[190:193], v132 offset:21504
	ds_read_b128 v[200:203], v132 offset:22528
	ds_read_b128 v[206:209], v132 offset:23552
	buffer_load_dwordx4 v0, s[40:43], s76 offen lds
	s_mov_b32 m0, s44
	s_add_i32 s78, s76, 0x160000
	buffer_load_dwordx4 v130, s[40:43], s76 offen lds
	s_mov_b32 m0, s45
	s_sub_i32 s77, s77, s4
	buffer_load_dwordx4 v0, s[40:43], s78 offen lds
	s_mov_b32 m0, s46
	s_nop 0
	buffer_load_dwordx4 v130, s[40:43], s78 offen lds
	s_mov_b32 m0, s19
	s_nop 0
	buffer_load_dwordx4 v0, s[4:7], s77 offen lds
	s_waitcnt vmcnt(7)
	s_waitcnt lgkmcnt(0)
	s_setprio 1
	s_barrier
	v_mfma_f32_16x16x32_bf16 v[62:65], v[134:137], v[170:173], v[62:65]
	v_mfma_f32_16x16x32_bf16 v[46:49], v[142:145], v[170:173], v[46:49]
	v_mfma_f32_16x16x32_bf16 v[70:73], v[142:145], v[178:181], v[70:73]
	v_mfma_f32_16x16x32_bf16 v[82:85], v[134:137], v[178:181], v[82:85]
	v_mfma_f32_16x16x32_bf16 v[94:97], v[134:137], v[186:189], v[94:97]
	v_mfma_f32_16x16x32_bf16 v[90:93], v[142:145], v[186:189], v[90:93]
	v_mfma_f32_16x16x32_bf16 v[26:29], v[142:145], v[200:203], v[26:29]
	v_mfma_f32_16x16x32_bf16 v[38:41], v[134:137], v[200:203], v[38:41]
	v_mfma_f32_16x16x32_bf16 v[10:13], v[150:153], v[200:203], v[10:13]
	v_mfma_f32_16x16x32_bf16 v[2:5], v[158:161], v[200:203], v[2:5]
	v_mfma_f32_16x16x32_bf16 v[34:37], v[158:161], v[186:189], v[34:37]
	v_mfma_f32_16x16x32_bf16 v[58:61], v[150:153], v[186:189], v[58:61]
	v_mfma_f32_16x16x32_bf16 v[66:69], v[150:153], v[178:181], v[66:69]
	v_mfma_f32_16x16x32_bf16 v[86:89], v[158:161], v[178:181], v[86:89]
	v_mfma_f32_16x16x32_bf16 v[30:33], v[158:161], v[170:173], v[30:33]
	v_mfma_f32_16x16x32_bf16 v[42:45], v[150:153], v[170:173], v[42:45]
	v_mfma_f32_16x16x32_bf16 v[62:65], v[138:141], v[174:177], v[62:65]
	v_mfma_f32_16x16x32_bf16 v[46:49], v[146:149], v[174:177], v[46:49]
	v_mfma_f32_16x16x32_bf16 v[70:73], v[146:149], v[182:185], v[70:73]
	v_mfma_f32_16x16x32_bf16 v[82:85], v[138:141], v[182:185], v[82:85]
	v_mfma_f32_16x16x32_bf16 v[94:97], v[138:141], v[190:193], v[94:97]
	v_mfma_f32_16x16x32_bf16 v[90:93], v[146:149], v[190:193], v[90:93]
	v_mfma_f32_16x16x32_bf16 v[26:29], v[146:149], v[206:209], v[26:29]
	v_mfma_f32_16x16x32_bf16 v[38:41], v[138:141], v[206:209], v[38:41]
	v_mfma_f32_16x16x32_bf16 v[10:13], v[154:157], v[206:209], v[10:13]
	v_mfma_f32_16x16x32_bf16 v[2:5], v[166:169], v[206:209], v[2:5]
	v_mfma_f32_16x16x32_bf16 v[34:37], v[166:169], v[190:193], v[34:37]
	v_mfma_f32_16x16x32_bf16 v[58:61], v[154:157], v[190:193], v[58:61]
	v_mfma_f32_16x16x32_bf16 v[66:69], v[154:157], v[182:185], v[66:69]
	v_mfma_f32_16x16x32_bf16 v[86:89], v[166:169], v[182:185], v[86:89]
	v_mfma_f32_16x16x32_bf16 v[30:33], v[166:169], v[174:177], v[30:33]
	v_mfma_f32_16x16x32_bf16 v[42:45], v[154:157], v[174:177], v[42:45]
	s_barrier
; #define PG8_STAGE(bufoff, gbase, voff) do { const int so_ = (int)(unsigned)((const char*)(gbase) - base_##voff); _Pragma("unroll") for (int _i = 0; _i < 2; ++_i) \
;         __builtin_amdgcn_raw_ptr_buffer_load_lds(rs_##voff, (PG8_LAS unsigned*)(lds + (bufoff) + ldsw + _i * 8192), 16, (int)(voff)[_i], so_, 0, 0); } while (0)
; #define PG8_LDA(dst, b, h) do { _Pragma("unroll") for (int m = 0; m < 4; ++m) _Pragma("unroll") for (int k = 0; k < 2; ++k) dst[m][k] = *(const PG8_LAS bf16x8*)(lds + PG8_SA(b, h) + aoff + m * 2048 + k * 1024); } while (0)
; #define PG8_LDB(dst, b, h) do { _Pragma("unroll") for (int n = 0; n < 2; ++n) _Pragma("unroll") for (int k = 0; k < 2; ++k) dst[n][k] = *(const PG8_LAS bf16x8*)(lds + PG8_SB(b, h) + boff + n * 2048 + k * 1024); } while (0)
; #define PG8_MMA(ai, bj, At, Bt) do { __builtin_amdgcn_s_setprio(1); _Pragma("unroll") for (int m = 0; m < 4; ++m) _Pragma("unroll") for (int n = 0; n < 2; ++n) _Pragma("unroll") for (int k = 0; k < 2; ++k) \
;         acc[ai][bj][m][n] = __builtin_amdgcn_mfma_f32_16x16x32_bf16(Bt[n][k], At[m][k], acc[ai][bj][m][n], 0, 0, 0); __builtin_amdgcn_s_setprio(0); } while (0)
; #define PG8_WAIT_V(n) asm volatile("s_waitcnt vmcnt(" #n ")" ::: "memory")
; #define PG8_WAIT_L(n) asm volatile("s_waitcnt lgkmcnt(" #n ")" ::: "memory")
; #define PG8_BAR __builtin_amdgcn_s_barrier()
; #define PG8_SCHED __builtin_amdgcn_sched_barrier(0)
; template <class Epi, class Sched, bool ALIGN_EPI = false, bool SP2 = false>
; __device__ __forceinline__ void gemm_phase(PG8_LAS unsigned char* lds, const Gemm g, const Sched& S, const Epi& E, int tid_in) {
;     ...
;             PG8_LDA(At, 0, 1); PG8_STAGE(PG8_SB(0, 0), b2, voffB); PG8_STAGE(PG8_SB(0, 1), b2 + hstepB, voffB); PG8_STAGE(PG8_SA(0, 0), a2, voffA);
;             PG8_WAIT_V(8); PG8_WAIT_L(0); PG8_BAR; PG8_MMA(1, 0, At, B0); PG8_MMA(1, 1, At, B1); PG8_BAR; PG8_SCHED;
;             PG8_LDB(B0, 1, 0); PG8_LDB(B1, 1, 1); PG8_SCHED; PG8_LDA(At, 1, 0); PG8_STAGE(PG8_SA(0, 1), a2 + hstepA, voffA);
;             PG8_WAIT_V(8); PG8_WAIT_L(0); PG8_BAR; PG8_MMA(0, 0, At, B0); PG8_MMA(0, 1, At, B1); PG8_BAR; PG8_SCHED;
	s_setprio 0
	v_add_u32_e32 v133, 0x18000, v131
	ds_read_b128 v[134:137], v133
	ds_read_b128 v[138:141], v133 offset:1024
	ds_read_b128 v[142:145], v133 offset:2048
	ds_read_b128 v[146:149], v133 offset:3072
	v_add_u32_e32 v133, 0x1c000, v131
	ds_read_b128 v[150:153], v133
	ds_read_b128 v[154:157], v133 offset:1024
	ds_read_b128 v[158:161], v133 offset:2048
	ds_read_b128 v[166:169], v133 offset:3072
	s_add_i32 s78, s77, 0x160000
	s_mov_b32 m0, s48
	ds_read_b128 v[170:173], v132 offset:32768
	ds_read_b128 v[174:177], v132 offset:33792
	ds_read_b128 v[178:181], v132 offset:34816
	ds_read_b128 v[182:185], v132 offset:35840
	ds_read_b128 v[186:189], v132 offset:36864
	ds_read_b128 v[190:193], v132 offset:37888
	ds_read_b128 v[200:203], v132 offset:38912
	ds_read_b128 v[206:209], v132 offset:39936
	s_mov_b32 m0, s47
	s_nop 0
	buffer_load_dwordx4 v130, s[4:7], s77 offen lds
	s_mov_b32 m0, s48
	s_nop 0
	buffer_load_dwordx4 v0, s[4:7], s78 offen lds
	s_mov_b32 m0, s49
	s_nop 0
	buffer_load_dwordx4 v130, s[4:7], s78 offen lds
	s_waitcnt vmcnt(8)
	s_waitcnt lgkmcnt(0)
	s_setprio 1
	s_barrier
	v_mfma_f32_16x16x32_bf16 v[22:25], v[134:137], v[170:173], v[22:25]
	v_mfma_f32_16x16x32_bf16 v[14:17], v[142:145], v[170:173], v[14:17]
	v_mfma_f32_16x16x32_bf16 v[54:57], v[142:145], v[178:181], v[54:57]
	v_mfma_f32_16x16x32_bf16 v[74:77], v[134:137], v[178:181], v[74:77]
	v_mfma_f32_16x16x32_bf16 v[106:109], v[134:137], v[186:189], v[106:109]
	v_mfma_f32_16x16x32_bf16 v[102:105], v[142:145], v[186:189], v[102:105]
	v_mfma_f32_16x16x32_bf16 v[118:121], v[142:145], v[200:203], v[118:121]
	v_mfma_f32_16x16x32_bf16 v[122:125], v[134:137], v[200:203], v[122:125]
	s_mov_b32 m0, s60
	v_mfma_f32_16x16x32_bf16 v[114:117], v[150:153], v[200:203], v[114:117]
	s_add_i32 s78, s76, 0x80
	v_mfma_f32_16x16x32_bf16 v[126:129], v[158:161], v[200:203], v[126:129]
	v_mfma_f32_16x16x32_bf16 v[110:113], v[158:161], v[186:189], v[110:113]
	v_mfma_f32_16x16x32_bf16 v[98:101], v[150:153], v[186:189], v[98:101]
	v_mfma_f32_16x16x32_bf16 v[50:53], v[150:153], v[178:181], v[50:53]
	v_mfma_f32_16x16x32_bf16 v[78:81], v[158:161], v[178:181], v[78:81]
	v_mfma_f32_16x16x32_bf16 v[18:21], v[158:161], v[170:173], v[18:21]
	v_mfma_f32_16x16x32_bf16 v[6:9], v[150:153], v[170:173], v[6:9]
	v_mfma_f32_16x16x32_bf16 v[22:25], v[138:141], v[174:177], v[22:25]
	v_mfma_f32_16x16x32_bf16 v[14:17], v[146:149], v[174:177], v[14:17]
	v_mfma_f32_16x16x32_bf16 v[54:57], v[146:149], v[182:185], v[54:57]
	v_mfma_f32_16x16x32_bf16 v[74:77], v[138:141], v[182:185], v[74:77]
	v_mfma_f32_16x16x32_bf16 v[106:109], v[138:141], v[190:193], v[106:109]
	v_mfma_f32_16x16x32_bf16 v[102:105], v[146:149], v[190:193], v[102:105]
	v_mfma_f32_16x16x32_bf16 v[118:121], v[146:149], v[206:209], v[118:121]
	v_mfma_f32_16x16x32_bf16 v[122:125], v[138:141], v[206:209], v[122:125]
	v_mfma_f32_16x16x32_bf16 v[114:117], v[154:157], v[206:209], v[114:117]
	v_mfma_f32_16x16x32_bf16 v[126:129], v[166:169], v[206:209], v[126:129]
	v_mfma_f32_16x16x32_bf16 v[110:113], v[166:169], v[190:193], v[110:113]
	v_mfma_f32_16x16x32_bf16 v[98:101], v[154:157], v[190:193], v[98:101]
	v_mfma_f32_16x16x32_bf16 v[50:53], v[154:157], v[182:185], v[50:53]
	v_mfma_f32_16x16x32_bf16 v[78:81], v[166:169], v[182:185], v[78:81]
	v_mfma_f32_16x16x32_bf16 v[18:21], v[166:169], v[174:177], v[18:21]
	v_mfma_f32_16x16x32_bf16 v[6:9], v[154:157], v[174:177], v[6:9]
	s_barrier
	s_setprio 0
	ds_read_b128 v[170:173], v132 offset:49152
	ds_read_b128 v[174:177], v132 offset:50176
	ds_read_b128 v[178:181], v132 offset:51200
	ds_read_b128 v[182:185], v132 offset:52224
	ds_read_b128 v[186:189], v132 offset:53248
	ds_read_b128 v[190:193], v132 offset:54272
	ds_read_b128 v[200:203], v132 offset:55296
	ds_read_b128 v[206:209], v132 offset:56320
	buffer_load_dwordx4 v0, s[40:43], s78 offen lds
	s_mov_b32 m0, s61
	s_add_i32 s76, s76, 0x160080
	buffer_load_dwordx4 v130, s[40:43], s78 offen lds
	s_mov_b32 m0, s66
	s_addk_i32 s77, 0x80
	buffer_load_dwordx4 v0, s[40:43], s76 offen lds
	s_mov_b32 m0, s67
	s_nop 0
	buffer_load_dwordx4 v130, s[40:43], s76 offen lds
	s_mov_b32 m0, s62
	s_nop 0
	buffer_load_dwordx4 v0, s[4:7], s77 offen lds
	s_waitcnt vmcnt(7)
	s_waitcnt lgkmcnt(0)
	s_setprio 1
	s_barrier
;     static __device__ __forceinline__ bool last_of_chain(const Unit& u) { return (u.pn >> 3) == 2; }
; #define PG8_STAGE(bufoff, gbase, voff) do { const int so_ = (int)(unsigned)((const char*)(gbase) - base_##voff); _Pragma("unroll") for (int _i = 0; _i < 2; ++_i) \
;         __builtin_amdgcn_raw_ptr_buffer_load_lds(rs_##voff, (PG8_LAS unsigned*)(lds + (bufoff) + ldsw + _i * 8192), 16, (int)(voff)[_i], so_, 0, 0); } while (0)
; #define PG8_LDA(dst, b, h) do { _Pragma("unroll") for (int m = 0; m < 4; ++m) _Pragma("unroll") for (int k = 0; k < 2; ++k) dst[m][k] = *(const PG8_LAS bf16x8*)(lds + PG8_SA(b, h) + aoff + m * 2048 + k * 1024); } while (0)
; #define PG8_MMA(ai, bj, At, Bt) do { __builtin_amdgcn_s_setprio(1); _Pragma("unroll") for (int m = 0; m < 4; ++m) _Pragma("unroll") for (int n = 0; n < 2; ++n) _Pragma("unroll") for (int k = 0; k < 2; ++k) \
;         acc[ai][bj][m][n] = __builtin_amdgcn_mfma_f32_16x16x32_bf16(Bt[n][k], At[m][k], acc[ai][bj][m][n], 0, 0, 0); __builtin_amdgcn_s_setprio(0); } while (0)
; #define PG8_WAIT_V(n) asm volatile("s_waitcnt vmcnt(" #n ")" ::: "memory")
; #define PG8_WAIT_L(n) asm volatile("s_waitcnt lgkmcnt(" #n ")" ::: "memory")
; #define PG8_BAR __builtin_amdgcn_s_barrier()
; #define PG8_SCHED __builtin_amdgcn_sched_barrier(0)
; template <class Epi, class Sched, bool ALIGN_EPI = false, bool SP2 = false>
; __device__ __forceinline__ void gemm_phase(PG8_LAS unsigned char* lds, const Gemm g, const Sched& S, const Epi& E, int tid_in) {
;     ...
;             PG8_WAIT_V(8); PG8_WAIT_L(0); PG8_BAR; PG8_MMA(0, 0, At, B0); PG8_MMA(0, 1, At, B1); PG8_BAR; PG8_SCHED;
;             PG8_LDA(At, 1, 1); PG8_STAGE(PG8_SB(1, 0), b3, voffB); PG8_STAGE(PG8_SB(1, 1), b3 + hstepB, voffB); PG8_STAGE(PG8_SA(1, 0), a3, voffA);
;             PG8_WAIT_V(8); PG8_WAIT_L(0); PG8_BAR; PG8_MMA(1, 0, At, B0); PG8_MMA(1, 1, At, B1); PG8_BAR; PG8_SCHED;
;     ...
;         bool zero_acc = true; if constexpr (Epi::CHAIN) zero_acc = Epi::last_of_chain(cur);
;         if (zero_acc) {
; #pragma unroll
;         for (int a = 0; a < 2; ++a)
; #pragma unroll
;             for (int b = 0; b < 2; ++b)
; #pragma unroll
;                 for (int m = 0; m < 4; ++m)
; #pragma unroll
;                     for (int n = 0; n < 2; ++n) acc[a][b][m][n] = (f32x4){0.f, 0.f, 0.f, 0.f};
;         }
	v_mfma_f32_16x16x32_bf16 v[62:65], v[134:137], v[170:173], v[62:65]
	v_mfma_f32_16x16x32_bf16 v[46:49], v[142:145], v[170:173], v[46:49]
	v_mfma_f32_16x16x32_bf16 v[70:73], v[142:145], v[178:181], v[70:73]
	v_mfma_f32_16x16x32_bf16 v[82:85], v[134:137], v[178:181], v[82:85]
	v_mfma_f32_16x16x32_bf16 v[94:97], v[134:137], v[186:189], v[94:97]
	v_mfma_f32_16x16x32_bf16 v[90:93], v[142:145], v[186:189], v[90:93]
	v_mfma_f32_16x16x32_bf16 v[26:29], v[142:145], v[200:203], v[26:29]
	v_mfma_f32_16x16x32_bf16 v[38:41], v[134:137], v[200:203], v[38:41]
	s_add_i32 s39, s39, 2
	v_mfma_f32_16x16x32_bf16 v[10:13], v[150:153], v[200:203], v[10:13]
	s_add_u32 s22, s22, 0x100
	v_mfma_f32_16x16x32_bf16 v[2:5], v[158:161], v[200:203], v[2:5]
	s_addc_u32 s23, s23, 0
	v_mfma_f32_16x16x32_bf16 v[34:37], v[158:161], v[186:189], v[34:37]
	v_mfma_f32_16x16x32_bf16 v[58:61], v[150:153], v[186:189], v[58:61]
	v_mfma_f32_16x16x32_bf16 v[66:69], v[150:153], v[178:181], v[66:69]
	v_mfma_f32_16x16x32_bf16 v[86:89], v[158:161], v[178:181], v[86:89]
	v_mfma_f32_16x16x32_bf16 v[30:33], v[158:161], v[170:173], v[30:33]
	v_mfma_f32_16x16x32_bf16 v[42:45], v[150:153], v[170:173], v[42:45]
	v_mfma_f32_16x16x32_bf16 v[62:65], v[138:141], v[174:177], v[62:65]
	v_mfma_f32_16x16x32_bf16 v[46:49], v[146:149], v[174:177], v[46:49]
	v_mfma_f32_16x16x32_bf16 v[70:73], v[146:149], v[182:185], v[70:73]
	v_mfma_f32_16x16x32_bf16 v[82:85], v[138:141], v[182:185], v[82:85]
	v_mfma_f32_16x16x32_bf16 v[94:97], v[138:141], v[190:193], v[94:97]
	v_mfma_f32_16x16x32_bf16 v[90:93], v[146:149], v[190:193], v[90:93]
	v_mfma_f32_16x16x32_bf16 v[26:29], v[146:149], v[206:209], v[26:29]
	v_mfma_f32_16x16x32_bf16 v[38:41], v[138:141], v[206:209], v[38:41]
	v_mfma_f32_16x16x32_bf16 v[10:13], v[154:157], v[206:209], v[10:13]
	v_mfma_f32_16x16x32_bf16 v[2:5], v[166:169], v[206:209], v[2:5]
	v_mfma_f32_16x16x32_bf16 v[34:37], v[166:169], v[190:193], v[34:37]
	v_mfma_f32_16x16x32_bf16 v[58:61], v[154:157], v[190:193], v[58:61]
	v_mfma_f32_16x16x32_bf16 v[66:69], v[154:157], v[182:185], v[66:69]
	v_mfma_f32_16x16x32_bf16 v[86:89], v[166:169], v[182:185], v[86:89]
	v_mfma_f32_16x16x32_bf16 v[30:33], v[166:169], v[174:177], v[30:33]
	v_mfma_f32_16x16x32_bf16 v[42:45], v[154:157], v[174:177], v[42:45]
	s_barrier
	s_setprio 0
	s_cmpk_gt_u32 s39, 0x55
	s_cbranch_scc0 .LBB0_1584
	s_and_b64 vcc, exec, s[36:37]
	s_cbranch_vccnz .LBB0_1572
	v_mov_b32_e32 v2, 0
	s_mov_b32 s10, s73
	s_mov_b32 s25, s74
	s_mov_b64 s[12:13], s[20:21]
	s_mov_b64 s[14:15], s[16:17]
	s_mov_b32 s72, s75
	v_mov_b32_e32 v3, v2
	v_mov_b32_e32 v4, v2
	v_mov_b32_e32 v5, v2
	v_mov_b32_e32 v10, v2
	v_mov_b32_e32 v11, v2
	v_mov_b32_e32 v12, v2
	v_mov_b32_e32 v13, v2
	v_mov_b32_e32 v34, v2
	v_mov_b32_e32 v35, v2
	v_mov_b32_e32 v36, v2
	v_mov_b32_e32 v37, v2
	v_mov_b32_e32 v58, v2
	v_mov_b32_e32 v59, v2
	v_mov_b32_e32 v60, v2
	v_mov_b32_e32 v61, v2
	v_mov_b32_e32 v86, v2
	v_mov_b32_e32 v87, v2
	v_mov_b32_e32 v88, v2
	v_mov_b32_e32 v89, v2
	v_mov_b32_e32 v66, v2
	v_mov_b32_e32 v67, v2
	v_mov_b32_e32 v68, v2
	v_mov_b32_e32 v69, v2
	v_mov_b32_e32 v30, v2
	v_mov_b32_e32 v31, v2
	v_mov_b32_e32 v32, v2
	v_mov_b32_e32 v33, v2
	v_mov_b32_e32 v42, v2
	v_mov_b32_e32 v43, v2
	v_mov_b32_e32 v44, v2
	v_mov_b32_e32 v45, v2
	v_mov_b32_e32 v26, v2
	v_mov_b32_e32 v27, v2
	v_mov_b32_e32 v28, v2
	v_mov_b32_e32 v29, v2
	v_mov_b32_e32 v38, v2
	v_mov_b32_e32 v39, v2
	v_mov_b32_e32 v40, v2
	v_mov_b32_e32 v41, v2
	v_mov_b32_e32 v90, v2
	v_mov_b32_e32 v91, v2
	v_mov_b32_e32 v92, v2
	v_mov_b32_e32 v93, v2
	v_mov_b32_e32 v94, v2
	v_mov_b32_e32 v95, v2
	v_mov_b32_e32 v96, v2
	v_mov_b32_e32 v97, v2
	v_mov_b32_e32 v70, v2
	v_mov_b32_e32 v71, v2
	v_mov_b32_e32 v72, v2
	v_mov_b32_e32 v73, v2
	v_mov_b32_e32 v82, v2
	v_mov_b32_e32 v83, v2
	v_mov_b32_e32 v84, v2
	v_mov_b32_e32 v85, v2
	v_mov_b32_e32 v46, v2
	v_mov_b32_e32 v47, v2
	v_mov_b32_e32 v48, v2
	v_mov_b32_e32 v49, v2
	v_mov_b32_e32 v62, v2
	v_mov_b32_e32 v63, v2
	v_mov_b32_e32 v64, v2
	v_mov_b32_e32 v65, v2
	v_mov_b32_e32 v126, v2
	v_mov_b32_e32 v127, v2
	v_mov_b32_e32 v128, v2
	v_mov_b32_e32 v129, v2
	v_mov_b32_e32 v114, v2
	v_mov_b32_e32 v115, v2
	v_mov_b32_e32 v116, v2
	v_mov_b32_e32 v117, v2
	v_mov_b32_e32 v110, v2
	v_mov_b32_e32 v111, v2
	v_mov_b32_e32 v112, v2
	v_mov_b32_e32 v113, v2
	v_mov_b32_e32 v98, v2
	v_mov_b32_e32 v99, v2
	v_mov_b32_e32 v100, v2
	v_mov_b32_e32 v101, v2
	v_mov_b32_e32 v78, v2
	v_mov_b32_e32 v79, v2
	v_mov_b32_e32 v80, v2
	v_mov_b32_e32 v81, v2
	v_mov_b32_e32 v50, v2
	v_mov_b32_e32 v51, v2
	v_mov_b32_e32 v52, v2
	v_mov_b32_e32 v53, v2
	v_mov_b32_e32 v18, v2
	v_mov_b32_e32 v19, v2
	v_mov_b32_e32 v20, v2
	v_mov_b32_e32 v21, v2
	v_mov_b32_e32 v6, v2
	v_mov_b32_e32 v7, v2
	v_mov_b32_e32 v8, v2
	v_mov_b32_e32 v9, v2
	v_mov_b32_e32 v118, v2
	v_mov_b32_e32 v119, v2
	v_mov_b32_e32 v120, v2
	v_mov_b32_e32 v121, v2
	v_mov_b32_e32 v122, v2
	v_mov_b32_e32 v123, v2
	v_mov_b32_e32 v124, v2
	v_mov_b32_e32 v125, v2
	v_mov_b32_e32 v102, v2
	v_mov_b32_e32 v103, v2
	v_mov_b32_e32 v104, v2
	v_mov_b32_e32 v105, v2
	v_mov_b32_e32 v106, v2
	v_mov_b32_e32 v107, v2
	v_mov_b32_e32 v108, v2
	v_mov_b32_e32 v109, v2
	v_mov_b32_e32 v54, v2
	v_mov_b32_e32 v55, v2
	v_mov_b32_e32 v56, v2
	v_mov_b32_e32 v57, v2
	v_mov_b32_e32 v74, v2
	v_mov_b32_e32 v75, v2
	v_mov_b32_e32 v76, v2
	v_mov_b32_e32 v77, v2
	v_mov_b32_e32 v14, v2
	v_mov_b32_e32 v15, v2
	v_mov_b32_e32 v16, v2
	v_mov_b32_e32 v17, v2
	v_mov_b32_e32 v22, v2
	v_mov_b32_e32 v23, v2
	v_mov_b32_e32 v24, v2
	v_mov_b32_e32 v25, v2
	s_branch .LBB0_1572
